# all K-loops: every fragment read issued right behind the barrier, DMA for the later stage issued after the reads (before the MFMAs)
# baseline (speedup 1.0000x reference)
; #define BLOAD(A_, B_, kt) do { _Pragma("unroll") for (int i = 0; i < 4; ++i) { \
;     A_[i] = *(const u32x4*)((const char*)Ap + (aoff + (unsigned)(32 * i * lda + (kt) * 64) * 2u)); B_[i] = *(const u32x4*)((const char*)Wt + (woff + (unsigned)(32 * i * K + (kt) * 64) * 2u)); } } while (0)
; #define BLOAD(A_, B_, kt) do { _Pragma("unroll") for (int i = 0; i < 4; ++i) { \
;     A_[i] = *(const u32x4*)((const char*)Ap + (aoff + (unsigned)(32 * i * lda + (kt) * 64) * 2u)); B_[i] = *(const u32x4*)((const char*)Wt + (woff + (unsigned)(32 * i * K + (kt) * 64) * 2u)); } } while (0)
; #define BSTORE(A_, B_, buf) do { _Pragma("unroll") for (int i = 0; i < 4; ++i) { \
;     *(u32x4*)&As[(buf) * GBUF + (srow + 32 * i) * LDT + sc8] = A_[i]; \
;     *(u32x4*)&Bs[(buf) * GBUF + (srow + 32 * i) * LDT + sc8] = B_[i]; } } while (0)
; template <int NK>
; DI void gemm_run(PF& pf, const u16* __restrict__ Ap, int lda, const u16* __restrict__ Wt, f32x16 (&acc)[2][2], char* smem) {
;     ...
;   __builtin_amdgcn_s_setprio(0);
;   __syncthreads();
;   BSTORE(pf.a0, pf.b0, 0);
;   BLOAD(pf.a0, pf.b0, 2);
;   __syncthreads();
; #pragma unroll
;   for (int kt = 0; kt < nk; kt += 2) {
;     BCOMP(0);
;     BSTORE(pf.a1, pf.b1, 1);
;     if (kt + 3 < nk) BLOAD(pf.a1, pf.b1, kt + 3);
;     __syncthreads();
;     BCOMP(1);
;     if (kt + 2 < nk) { BSTORE(pf.a0, pf.b0, 0); if (kt + 4 < nk) BLOAD(pf.a0, pf.b0, kt + 4); }
;     __syncthreads();
;   }
.Lffn2_kloop:
	s_waitcnt vmcnt(6)
	s_barrier
	ds_read_b128 v[224:227], v126 offset:0
	ds_read_b128 v[240:243], v128 offset:0
	ds_read_b128 v[244:247], v128 offset:1024
	ds_read_b128 v[248:251], v128 offset:2048
	ds_read_b128 v[156:159], v128 offset:3072
	ds_read_b128 v[228:231], v126 offset:1024
	ds_read_b128 v[232:235], v126 offset:2048
	ds_read_b128 v[236:239], v126 offset:3072
	ds_read_b128 v[160:163], v128 offset:8192
	ds_read_b128 v[164:167], v128 offset:9216
	ds_read_b128 v[168:171], v128 offset:10240
	ds_read_b128 v[122:125], v128 offset:11264
	s_add_u32 m0, s16, 0xc000
	s_add_u32 s42, s42, 0x100000
	s_addc_u32 s43, s43, 0
	global_load_lds_dwordx4 v137, s[42:43]
	global_load_lds_dwordx4 v150, s[42:43] offset:1024
	s_add_u32 m0, s0, 0xc000
	s_add_u32 s30, s30, 0x10000
	s_addc_u32 s31, s31, 0
	global_load_lds_dwordx4 v151, s[30:31]
	global_load_lds_dwordx4 v152, s[30:31] offset:1024
	global_load_lds_dwordx4 v153, s[30:31] offset:2048
	global_load_lds_dwordx4 v154, s[30:31] offset:3072
	s_waitcnt lgkmcnt(10)
	v_mfma_f32_16x16x32_bf16 v[2:5], v[240:243], v[224:227], v[2:5]
	s_waitcnt lgkmcnt(9)
	v_mfma_f32_16x16x32_bf16 v[6:9], v[244:247], v[224:227], v[6:9]
	s_waitcnt lgkmcnt(8)
	v_mfma_f32_16x16x32_bf16 v[10:13], v[248:251], v[224:227], v[10:13]
	s_waitcnt lgkmcnt(7)
	v_mfma_f32_16x16x32_bf16 v[14:17], v[156:159], v[224:227], v[14:17]
	s_waitcnt lgkmcnt(6)
	v_mfma_f32_16x16x32_bf16 v[18:21], v[240:243], v[228:231], v[18:21]
	v_mfma_f32_16x16x32_bf16 v[22:25], v[244:247], v[228:231], v[22:25]
	v_mfma_f32_16x16x32_bf16 v[26:29], v[248:251], v[228:231], v[26:29]
	v_mfma_f32_16x16x32_bf16 v[30:33], v[156:159], v[228:231], v[30:33]
	s_waitcnt lgkmcnt(5)
	v_mfma_f32_16x16x32_bf16 v[34:37], v[240:243], v[232:235], v[34:37]
	v_mfma_f32_16x16x32_bf16 v[38:41], v[244:247], v[232:235], v[38:41]
	v_mfma_f32_16x16x32_bf16 v[42:45], v[248:251], v[232:235], v[42:45]
	v_mfma_f32_16x16x32_bf16 v[46:49], v[156:159], v[232:235], v[46:49]
	s_waitcnt lgkmcnt(4)
	v_mfma_f32_16x16x32_bf16 v[50:53], v[240:243], v[236:239], v[50:53]
	v_mfma_f32_16x16x32_bf16 v[54:57], v[244:247], v[236:239], v[54:57]
	v_mfma_f32_16x16x32_bf16 v[58:61], v[248:251], v[236:239], v[58:61]
	v_mfma_f32_16x16x32_bf16 v[62:65], v[156:159], v[236:239], v[62:65]
	s_waitcnt lgkmcnt(3)
	v_mfma_f32_16x16x32_bf16 v[74:77], v[160:163], v[224:227], v[74:77]
	s_waitcnt lgkmcnt(2)
	v_mfma_f32_16x16x32_bf16 v[78:81], v[164:167], v[224:227], v[78:81]
	s_waitcnt lgkmcnt(1)
	v_mfma_f32_16x16x32_bf16 v[82:85], v[168:171], v[224:227], v[82:85]
	s_waitcnt lgkmcnt(0)
	v_mfma_f32_16x16x32_bf16 v[86:89], v[122:125], v[224:227], v[86:89]
	v_mfma_f32_16x16x32_bf16 v[90:93], v[160:163], v[228:231], v[90:93]
	v_mfma_f32_16x16x32_bf16 v[94:97], v[164:167], v[228:231], v[94:97]
	v_mfma_f32_16x16x32_bf16 v[98:101], v[168:171], v[228:231], v[98:101]
	v_mfma_f32_16x16x32_bf16 v[102:105], v[122:125], v[228:231], v[102:105]
	v_mfma_f32_16x16x32_bf16 v[106:109], v[160:163], v[232:235], v[106:109]
	v_mfma_f32_16x16x32_bf16 v[110:113], v[164:167], v[232:235], v[110:113]
	v_mfma_f32_16x16x32_bf16 v[114:117], v[168:171], v[232:235], v[114:117]
	v_mfma_f32_16x16x32_bf16 v[118:121], v[122:125], v[232:235], v[118:121]
	v_mfma_f32_16x16x32_bf16 v[208:211], v[160:163], v[236:239], v[208:211]
	v_mfma_f32_16x16x32_bf16 v[212:215], v[164:167], v[236:239], v[212:215]
	v_mfma_f32_16x16x32_bf16 v[216:219], v[168:171], v[236:239], v[216:219]
	v_mfma_f32_16x16x32_bf16 v[220:223], v[122:125], v[236:239], v[220:223]
	s_waitcnt vmcnt(6)
	s_barrier
	ds_read_b128 v[224:227], v126 offset:24576
	ds_read_b128 v[240:243], v128 offset:24576
	ds_read_b128 v[244:247], v128 offset:25600
	ds_read_b128 v[248:251], v128 offset:26624
	ds_read_b128 v[156:159], v128 offset:27648
	ds_read_b128 v[228:231], v126 offset:25600
	ds_read_b128 v[232:235], v126 offset:26624
	ds_read_b128 v[236:239], v126 offset:27648
	ds_read_b128 v[160:163], v128 offset:32768
	ds_read_b128 v[164:167], v128 offset:33792
	ds_read_b128 v[168:171], v128 offset:34816
	ds_read_b128 v[122:125], v128 offset:35840
	s_add_u32 m0, s16, 0x0
	s_add_u32 s42, s42, 0x100000
	s_addc_u32 s43, s43, 0
	global_load_lds_dwordx4 v137, s[42:43]
	global_load_lds_dwordx4 v150, s[42:43] offset:1024
	s_add_u32 m0, s0, 0x0
	s_add_u32 s30, s30, 0x10000
	s_addc_u32 s31, s31, 0
	global_load_lds_dwordx4 v151, s[30:31]
	global_load_lds_dwordx4 v152, s[30:31] offset:1024
	global_load_lds_dwordx4 v153, s[30:31] offset:2048
	global_load_lds_dwordx4 v154, s[30:31] offset:3072
	s_waitcnt lgkmcnt(10)
	v_mfma_f32_16x16x32_bf16 v[2:5], v[240:243], v[224:227], v[2:5]
	s_waitcnt lgkmcnt(9)
	v_mfma_f32_16x16x32_bf16 v[6:9], v[244:247], v[224:227], v[6:9]
	s_waitcnt lgkmcnt(8)
	v_mfma_f32_16x16x32_bf16 v[10:13], v[248:251], v[224:227], v[10:13]
	s_waitcnt lgkmcnt(7)
	v_mfma_f32_16x16x32_bf16 v[14:17], v[156:159], v[224:227], v[14:17]
	s_waitcnt lgkmcnt(6)
	v_mfma_f32_16x16x32_bf16 v[18:21], v[240:243], v[228:231], v[18:21]
	v_mfma_f32_16x16x32_bf16 v[22:25], v[244:247], v[228:231], v[22:25]
	v_mfma_f32_16x16x32_bf16 v[26:29], v[248:251], v[228:231], v[26:29]
	v_mfma_f32_16x16x32_bf16 v[30:33], v[156:159], v[228:231], v[30:33]
	s_waitcnt lgkmcnt(5)
	v_mfma_f32_16x16x32_bf16 v[34:37], v[240:243], v[232:235], v[34:37]
	v_mfma_f32_16x16x32_bf16 v[38:41], v[244:247], v[232:235], v[38:41]
	v_mfma_f32_16x16x32_bf16 v[42:45], v[248:251], v[232:235], v[42:45]
	v_mfma_f32_16x16x32_bf16 v[46:49], v[156:159], v[232:235], v[46:49]
	s_waitcnt lgkmcnt(4)
	v_mfma_f32_16x16x32_bf16 v[50:53], v[240:243], v[236:239], v[50:53]
	v_mfma_f32_16x16x32_bf16 v[54:57], v[244:247], v[236:239], v[54:57]
	v_mfma_f32_16x16x32_bf16 v[58:61], v[248:251], v[236:239], v[58:61]
	v_mfma_f32_16x16x32_bf16 v[62:65], v[156:159], v[236:239], v[62:65]
	s_waitcnt lgkmcnt(3)
	v_mfma_f32_16x16x32_bf16 v[74:77], v[160:163], v[224:227], v[74:77]
	s_waitcnt lgkmcnt(2)
	v_mfma_f32_16x16x32_bf16 v[78:81], v[164:167], v[224:227], v[78:81]
	s_waitcnt lgkmcnt(1)
	v_mfma_f32_16x16x32_bf16 v[82:85], v[168:171], v[224:227], v[82:85]
	s_waitcnt lgkmcnt(0)
	v_mfma_f32_16x16x32_bf16 v[86:89], v[122:125], v[224:227], v[86:89]
	v_mfma_f32_16x16x32_bf16 v[90:93], v[160:163], v[228:231], v[90:93]
	v_mfma_f32_16x16x32_bf16 v[94:97], v[164:167], v[228:231], v[94:97]
	v_mfma_f32_16x16x32_bf16 v[98:101], v[168:171], v[228:231], v[98:101]
	v_mfma_f32_16x16x32_bf16 v[102:105], v[122:125], v[228:231], v[102:105]
	v_mfma_f32_16x16x32_bf16 v[106:109], v[160:163], v[232:235], v[106:109]
	v_mfma_f32_16x16x32_bf16 v[110:113], v[164:167], v[232:235], v[110:113]
	v_mfma_f32_16x16x32_bf16 v[114:117], v[168:171], v[232:235], v[114:117]
	v_mfma_f32_16x16x32_bf16 v[118:121], v[122:125], v[232:235], v[118:121]
	v_mfma_f32_16x16x32_bf16 v[208:211], v[160:163], v[236:239], v[208:211]
	v_mfma_f32_16x16x32_bf16 v[212:215], v[164:167], v[236:239], v[212:215]
	v_mfma_f32_16x16x32_bf16 v[216:219], v[168:171], v[236:239], v[216:219]
	v_mfma_f32_16x16x32_bf16 v[220:223], v[122:125], v[236:239], v[220:223]
	s_waitcnt vmcnt(6)
	s_barrier
; #define BLOAD(A_, B_, kt) do { _Pragma("unroll") for (int i = 0; i < 4; ++i) { \
;     A_[i] = *(const u32x4*)((const char*)Ap + (aoff + (unsigned)(32 * i * lda + (kt) * 64) * 2u)); B_[i] = *(const u32x4*)((const char*)Wt + (woff + (unsigned)(32 * i * K + (kt) * 64) * 2u)); } } while (0)
; #define BLOAD(A_, B_, kt) do { _Pragma("unroll") for (int i = 0; i < 4; ++i) { \
;     A_[i] = *(const u32x4*)((const char*)Ap + (aoff + (unsigned)(32 * i * lda + (kt) * 64) * 2u)); B_[i] = *(const u32x4*)((const char*)Wt + (woff + (unsigned)(32 * i * K + (kt) * 64) * 2u)); } } while (0)
; #define BSTORE(A_, B_, buf) do { _Pragma("unroll") for (int i = 0; i < 4; ++i) { \
;     *(u32x4*)&As[(buf) * GBUF + (srow + 32 * i) * LDT + sc8] = A_[i]; \
;     *(u32x4*)&Bs[(buf) * GBUF + (srow + 32 * i) * LDT + sc8] = B_[i]; } } while (0)
; template <int NK>
; DI void gemm_run(PF& pf, const u16* __restrict__ Ap, int lda, const u16* __restrict__ Wt, f32x16 (&acc)[2][2], char* smem) {
;     ...
;   __builtin_amdgcn_s_setprio(0);
;   __syncthreads();
;   BSTORE(pf.a0, pf.b0, 0);
;   BLOAD(pf.a0, pf.b0, 2);
;   __syncthreads();
; #pragma unroll
;   for (int kt = 0; kt < nk; kt += 2) {
;     BCOMP(0);
;     BSTORE(pf.a1, pf.b1, 1);
;     if (kt + 3 < nk) BLOAD(pf.a1, pf.b1, kt + 3);
;     __syncthreads();
;     BCOMP(1);
;     if (kt + 2 < nk) { BSTORE(pf.a0, pf.b0, 0); if (kt + 4 < nk) BLOAD(pf.a0, pf.b0, kt + 4); }
;     __syncthreads();
;   }
	ds_read_b128 v[224:227], v126 offset:49152
	ds_read_b128 v[240:243], v128 offset:49152
	ds_read_b128 v[244:247], v128 offset:50176
	ds_read_b128 v[248:251], v128 offset:51200
	ds_read_b128 v[156:159], v128 offset:52224
	ds_read_b128 v[228:231], v126 offset:50176
	ds_read_b128 v[232:235], v126 offset:51200
	ds_read_b128 v[236:239], v126 offset:52224
	ds_read_b128 v[160:163], v128 offset:57344
	ds_read_b128 v[164:167], v128 offset:58368
	ds_read_b128 v[168:171], v128 offset:59392
	ds_read_b128 v[122:125], v128 offset:60416
	s_add_u32 m0, s16, 0x6000
	s_add_u32 s42, s42, 0x100000
	s_addc_u32 s43, s43, 0
	global_load_lds_dwordx4 v137, s[42:43]
	global_load_lds_dwordx4 v150, s[42:43] offset:1024
	s_add_u32 m0, s0, 0x6000
	s_add_u32 s30, s30, 0x10000
	s_addc_u32 s31, s31, 0
	global_load_lds_dwordx4 v151, s[30:31]
	global_load_lds_dwordx4 v152, s[30:31] offset:1024
	global_load_lds_dwordx4 v153, s[30:31] offset:2048
	global_load_lds_dwordx4 v154, s[30:31] offset:3072
	s_waitcnt lgkmcnt(10)
	v_mfma_f32_16x16x32_bf16 v[2:5], v[240:243], v[224:227], v[2:5]
	s_waitcnt lgkmcnt(9)
	v_mfma_f32_16x16x32_bf16 v[6:9], v[244:247], v[224:227], v[6:9]
	s_waitcnt lgkmcnt(8)
	v_mfma_f32_16x16x32_bf16 v[10:13], v[248:251], v[224:227], v[10:13]
	s_waitcnt lgkmcnt(7)
	v_mfma_f32_16x16x32_bf16 v[14:17], v[156:159], v[224:227], v[14:17]
	s_waitcnt lgkmcnt(6)
	v_mfma_f32_16x16x32_bf16 v[18:21], v[240:243], v[228:231], v[18:21]
	v_mfma_f32_16x16x32_bf16 v[22:25], v[244:247], v[228:231], v[22:25]
	v_mfma_f32_16x16x32_bf16 v[26:29], v[248:251], v[228:231], v[26:29]
	v_mfma_f32_16x16x32_bf16 v[30:33], v[156:159], v[228:231], v[30:33]
	s_waitcnt lgkmcnt(5)
	v_mfma_f32_16x16x32_bf16 v[34:37], v[240:243], v[232:235], v[34:37]
	v_mfma_f32_16x16x32_bf16 v[38:41], v[244:247], v[232:235], v[38:41]
	v_mfma_f32_16x16x32_bf16 v[42:45], v[248:251], v[232:235], v[42:45]
	v_mfma_f32_16x16x32_bf16 v[46:49], v[156:159], v[232:235], v[46:49]
	s_waitcnt lgkmcnt(4)
	v_mfma_f32_16x16x32_bf16 v[50:53], v[240:243], v[236:239], v[50:53]
	v_mfma_f32_16x16x32_bf16 v[54:57], v[244:247], v[236:239], v[54:57]
	v_mfma_f32_16x16x32_bf16 v[58:61], v[248:251], v[236:239], v[58:61]
	v_mfma_f32_16x16x32_bf16 v[62:65], v[156:159], v[236:239], v[62:65]
	s_waitcnt lgkmcnt(3)
	v_mfma_f32_16x16x32_bf16 v[74:77], v[160:163], v[224:227], v[74:77]
	s_waitcnt lgkmcnt(2)
	v_mfma_f32_16x16x32_bf16 v[78:81], v[164:167], v[224:227], v[78:81]
	s_waitcnt lgkmcnt(1)
	v_mfma_f32_16x16x32_bf16 v[82:85], v[168:171], v[224:227], v[82:85]
	s_waitcnt lgkmcnt(0)
	v_mfma_f32_16x16x32_bf16 v[86:89], v[122:125], v[224:227], v[86:89]
	v_mfma_f32_16x16x32_bf16 v[90:93], v[160:163], v[228:231], v[90:93]
	v_mfma_f32_16x16x32_bf16 v[94:97], v[164:167], v[228:231], v[94:97]
	v_mfma_f32_16x16x32_bf16 v[98:101], v[168:171], v[228:231], v[98:101]
	v_mfma_f32_16x16x32_bf16 v[102:105], v[122:125], v[228:231], v[102:105]
	v_mfma_f32_16x16x32_bf16 v[106:109], v[160:163], v[232:235], v[106:109]
	v_mfma_f32_16x16x32_bf16 v[110:113], v[164:167], v[232:235], v[110:113]
	v_mfma_f32_16x16x32_bf16 v[114:117], v[168:171], v[232:235], v[114:117]
	v_mfma_f32_16x16x32_bf16 v[118:121], v[122:125], v[232:235], v[118:121]
	v_mfma_f32_16x16x32_bf16 v[208:211], v[160:163], v[236:239], v[208:211]
	v_mfma_f32_16x16x32_bf16 v[212:215], v[164:167], v[236:239], v[212:215]
	v_mfma_f32_16x16x32_bf16 v[216:219], v[168:171], v[236:239], v[216:219]
	v_mfma_f32_16x16x32_bf16 v[220:223], v[122:125], v[236:239], v[220:223]
	s_sub_u32 s46, s46, 1
	s_cmp_lg_u32 s46, 0
	s_cbranch_scc1 .Lffn2_kloop
	s_waitcnt vmcnt(6)
	s_barrier
; #define BLOAD(A_, B_, kt) do { _Pragma("unroll") for (int i = 0; i < 4; ++i) { \
;     A_[i] = *(const u32x4*)((const char*)Ap + (aoff + (unsigned)(32 * i * lda + (kt) * 64) * 2u)); B_[i] = *(const u32x4*)((const char*)Wt + (woff + (unsigned)(32 * i * K + (kt) * 64) * 2u)); } } while (0)
; #define BLOAD(A_, B_, kt) do { _Pragma("unroll") for (int i = 0; i < 4; ++i) { \
;     A_[i] = *(const u32x4*)((const char*)Ap + (aoff + (unsigned)(32 * i * lda + (kt) * 64) * 2u)); B_[i] = *(const u32x4*)((const char*)Wt + (woff + (unsigned)(32 * i * K + (kt) * 64) * 2u)); } } while (0)
; #define BSTORE(A_, B_, buf) do { _Pragma("unroll") for (int i = 0; i < 4; ++i) { \
;     *(u32x4*)&As[(buf) * GBUF + (srow + 32 * i) * LDT + sc8] = A_[i]; \
;     *(u32x4*)&Bs[(buf) * GBUF + (srow + 32 * i) * LDT + sc8] = B_[i]; } } while (0)
; template <int NK>
; DI void gemm_run(PF& pf, const u16* __restrict__ Ap, int lda, const u16* __restrict__ Wt, f32x16 (&acc)[2][2], char* smem) {
;     ...
;   __builtin_amdgcn_s_setprio(0);
;   __syncthreads();
;   BSTORE(pf.a0, pf.b0, 0);
;   BLOAD(pf.a0, pf.b0, 2);
;   __syncthreads();
; #pragma unroll
;   for (int kt = 0; kt < nk; kt += 2) {
;     BCOMP(0);
;     BSTORE(pf.a1, pf.b1, 1);
;     if (kt + 3 < nk) BLOAD(pf.a1, pf.b1, kt + 3);
;     __syncthreads();
;     BCOMP(1);
;     if (kt + 2 < nk) { BSTORE(pf.a0, pf.b0, 0); if (kt + 4 < nk) BLOAD(pf.a0, pf.b0, kt + 4); }
;     __syncthreads();
;   }
	ds_read_b128 v[224:227], v126 offset:0
	ds_read_b128 v[240:243], v128 offset:0
	ds_read_b128 v[244:247], v128 offset:1024
	ds_read_b128 v[248:251], v128 offset:2048
	ds_read_b128 v[156:159], v128 offset:3072
	ds_read_b128 v[228:231], v126 offset:1024
	ds_read_b128 v[232:235], v126 offset:2048
	ds_read_b128 v[236:239], v126 offset:3072
	ds_read_b128 v[160:163], v128 offset:8192
	ds_read_b128 v[164:167], v128 offset:9216
	ds_read_b128 v[168:171], v128 offset:10240
	ds_read_b128 v[122:125], v128 offset:11264
	s_waitcnt lgkmcnt(10)
	v_mfma_f32_16x16x32_bf16 v[2:5], v[240:243], v[224:227], v[2:5]
	s_waitcnt lgkmcnt(9)
	v_mfma_f32_16x16x32_bf16 v[6:9], v[244:247], v[224:227], v[6:9]
	s_waitcnt lgkmcnt(8)
	v_mfma_f32_16x16x32_bf16 v[10:13], v[248:251], v[224:227], v[10:13]
	s_waitcnt lgkmcnt(7)
	v_mfma_f32_16x16x32_bf16 v[14:17], v[156:159], v[224:227], v[14:17]
	s_waitcnt lgkmcnt(6)
	v_mfma_f32_16x16x32_bf16 v[18:21], v[240:243], v[228:231], v[18:21]
	v_mfma_f32_16x16x32_bf16 v[22:25], v[244:247], v[228:231], v[22:25]
	v_mfma_f32_16x16x32_bf16 v[26:29], v[248:251], v[228:231], v[26:29]
	v_mfma_f32_16x16x32_bf16 v[30:33], v[156:159], v[228:231], v[30:33]
	s_waitcnt lgkmcnt(5)
	v_mfma_f32_16x16x32_bf16 v[34:37], v[240:243], v[232:235], v[34:37]
	v_mfma_f32_16x16x32_bf16 v[38:41], v[244:247], v[232:235], v[38:41]
	v_mfma_f32_16x16x32_bf16 v[42:45], v[248:251], v[232:235], v[42:45]
	v_mfma_f32_16x16x32_bf16 v[46:49], v[156:159], v[232:235], v[46:49]
	s_waitcnt lgkmcnt(4)
	v_mfma_f32_16x16x32_bf16 v[50:53], v[240:243], v[236:239], v[50:53]
	v_mfma_f32_16x16x32_bf16 v[54:57], v[244:247], v[236:239], v[54:57]
	v_mfma_f32_16x16x32_bf16 v[58:61], v[248:251], v[236:239], v[58:61]
	v_mfma_f32_16x16x32_bf16 v[62:65], v[156:159], v[236:239], v[62:65]
	s_waitcnt lgkmcnt(3)
	v_mfma_f32_16x16x32_bf16 v[74:77], v[160:163], v[224:227], v[74:77]
	s_waitcnt lgkmcnt(2)
	v_mfma_f32_16x16x32_bf16 v[78:81], v[164:167], v[224:227], v[78:81]
	s_waitcnt lgkmcnt(1)
	v_mfma_f32_16x16x32_bf16 v[82:85], v[168:171], v[224:227], v[82:85]
	s_waitcnt lgkmcnt(0)
	v_mfma_f32_16x16x32_bf16 v[86:89], v[122:125], v[224:227], v[86:89]
	v_mfma_f32_16x16x32_bf16 v[90:93], v[160:163], v[228:231], v[90:93]
	v_mfma_f32_16x16x32_bf16 v[94:97], v[164:167], v[228:231], v[94:97]
	v_mfma_f32_16x16x32_bf16 v[98:101], v[168:171], v[228:231], v[98:101]
	v_mfma_f32_16x16x32_bf16 v[102:105], v[122:125], v[228:231], v[102:105]
	v_mfma_f32_16x16x32_bf16 v[106:109], v[160:163], v[232:235], v[106:109]
	v_mfma_f32_16x16x32_bf16 v[110:113], v[164:167], v[232:235], v[110:113]
	v_mfma_f32_16x16x32_bf16 v[114:117], v[168:171], v[232:235], v[114:117]
	v_mfma_f32_16x16x32_bf16 v[118:121], v[122:125], v[232:235], v[118:121]
	v_mfma_f32_16x16x32_bf16 v[208:211], v[160:163], v[236:239], v[208:211]
	v_mfma_f32_16x16x32_bf16 v[212:215], v[164:167], v[236:239], v[212:215]
	v_mfma_f32_16x16x32_bf16 v[216:219], v[168:171], v[236:239], v[216:219]
	v_mfma_f32_16x16x32_bf16 v[220:223], v[122:125], v[236:239], v[220:223]
	s_waitcnt vmcnt(0)
	s_barrier
	ds_read_b128 v[224:227], v126 offset:24576
	ds_read_b128 v[240:243], v128 offset:24576
	ds_read_b128 v[244:247], v128 offset:25600
	ds_read_b128 v[248:251], v128 offset:26624
	ds_read_b128 v[156:159], v128 offset:27648
	ds_read_b128 v[228:231], v126 offset:25600
	ds_read_b128 v[232:235], v126 offset:26624
	ds_read_b128 v[236:239], v126 offset:27648
	ds_read_b128 v[160:163], v128 offset:32768
	ds_read_b128 v[164:167], v128 offset:33792
	ds_read_b128 v[168:171], v128 offset:34816
	ds_read_b128 v[122:125], v128 offset:35840
	s_waitcnt lgkmcnt(10)
	v_mfma_f32_16x16x32_bf16 v[2:5], v[240:243], v[224:227], v[2:5]
	s_waitcnt lgkmcnt(9)
	v_mfma_f32_16x16x32_bf16 v[6:9], v[244:247], v[224:227], v[6:9]
	s_waitcnt lgkmcnt(8)
	v_mfma_f32_16x16x32_bf16 v[10:13], v[248:251], v[224:227], v[10:13]
	s_waitcnt lgkmcnt(7)
	v_mfma_f32_16x16x32_bf16 v[14:17], v[156:159], v[224:227], v[14:17]
	s_waitcnt lgkmcnt(6)
	v_mfma_f32_16x16x32_bf16 v[18:21], v[240:243], v[228:231], v[18:21]
	v_mfma_f32_16x16x32_bf16 v[22:25], v[244:247], v[228:231], v[22:25]
	v_mfma_f32_16x16x32_bf16 v[26:29], v[248:251], v[228:231], v[26:29]
	v_mfma_f32_16x16x32_bf16 v[30:33], v[156:159], v[228:231], v[30:33]
	s_waitcnt lgkmcnt(5)
	v_mfma_f32_16x16x32_bf16 v[34:37], v[240:243], v[232:235], v[34:37]
	v_mfma_f32_16x16x32_bf16 v[38:41], v[244:247], v[232:235], v[38:41]
	v_mfma_f32_16x16x32_bf16 v[42:45], v[248:251], v[232:235], v[42:45]
	v_mfma_f32_16x16x32_bf16 v[46:49], v[156:159], v[232:235], v[46:49]
	s_waitcnt lgkmcnt(4)
	v_mfma_f32_16x16x32_bf16 v[50:53], v[240:243], v[236:239], v[50:53]
	v_mfma_f32_16x16x32_bf16 v[54:57], v[244:247], v[236:239], v[54:57]
	v_mfma_f32_16x16x32_bf16 v[58:61], v[248:251], v[236:239], v[58:61]
	v_mfma_f32_16x16x32_bf16 v[62:65], v[156:159], v[236:239], v[62:65]
	s_waitcnt lgkmcnt(3)
	v_mfma_f32_16x16x32_bf16 v[74:77], v[160:163], v[224:227], v[74:77]
	s_waitcnt lgkmcnt(2)
	v_mfma_f32_16x16x32_bf16 v[78:81], v[164:167], v[224:227], v[78:81]
	s_waitcnt lgkmcnt(1)
	v_mfma_f32_16x16x32_bf16 v[82:85], v[168:171], v[224:227], v[82:85]
	s_waitcnt lgkmcnt(0)
	v_mfma_f32_16x16x32_bf16 v[86:89], v[122:125], v[224:227], v[86:89]
	v_mfma_f32_16x16x32_bf16 v[90:93], v[160:163], v[228:231], v[90:93]
	v_mfma_f32_16x16x32_bf16 v[94:97], v[164:167], v[228:231], v[94:97]
	v_mfma_f32_16x16x32_bf16 v[98:101], v[168:171], v[228:231], v[98:101]
	v_mfma_f32_16x16x32_bf16 v[102:105], v[122:125], v[228:231], v[102:105]
	v_mfma_f32_16x16x32_bf16 v[106:109], v[160:163], v[232:235], v[106:109]
	v_mfma_f32_16x16x32_bf16 v[110:113], v[164:167], v[232:235], v[110:113]
	v_mfma_f32_16x16x32_bf16 v[114:117], v[168:171], v[232:235], v[114:117]
	v_mfma_f32_16x16x32_bf16 v[118:121], v[122:125], v[232:235], v[118:121]
	v_mfma_f32_16x16x32_bf16 v[208:211], v[160:163], v[236:239], v[208:211]
	v_mfma_f32_16x16x32_bf16 v[212:215], v[164:167], v[236:239], v[212:215]
	v_mfma_f32_16x16x32_bf16 v[216:219], v[168:171], v[236:239], v[216:219]
	v_mfma_f32_16x16x32_bf16 v[220:223], v[122:125], v[236:239], v[220:223]
	s_barrier
	s_mov_b32 s16, 0

; #define BLOAD(A_, B_, kt) do { _Pragma("unroll") for (int i = 0; i < 4; ++i) { \
;     A_[i] = *(const u32x4*)((const char*)Ap + (aoff + (unsigned)(32 * i * lda + (kt) * 64) * 2u)); B_[i] = *(const u32x4*)((const char*)Wt + (woff + (unsigned)(32 * i * K + (kt) * 64) * 2u)); } } while (0)
; #define BLOAD(A_, B_, kt) do { _Pragma("unroll") for (int i = 0; i < 4; ++i) { \
;     A_[i] = *(const u32x4*)((const char*)Ap + (aoff + (unsigned)(32 * i * lda + (kt) * 64) * 2u)); B_[i] = *(const u32x4*)((const char*)Wt + (woff + (unsigned)(32 * i * K + (kt) * 64) * 2u)); } } while (0)
; #define BSTORE(A_, B_, buf) do { _Pragma("unroll") for (int i = 0; i < 4; ++i) { \
;     *(u32x4*)&As[(buf) * GBUF + (srow + 32 * i) * LDT + sc8] = A_[i]; \
;     *(u32x4*)&Bs[(buf) * GBUF + (srow + 32 * i) * LDT + sc8] = B_[i]; } } while (0)
; template <int NK>
; DI void gemm_run(PF& pf, const u16* __restrict__ Ap, int lda, const u16* __restrict__ Wt, f32x16 (&acc)[2][2], char* smem) {
;     ...
;   __builtin_amdgcn_s_setprio(0);
;   __syncthreads();
;   BSTORE(pf.a0, pf.b0, 0);
;   BLOAD(pf.a0, pf.b0, 2);
;   __syncthreads();
; #pragma unroll
;   for (int kt = 0; kt < nk; kt += 2) {
;     BCOMP(0);
;     BSTORE(pf.a1, pf.b1, 1);
;     if (kt + 3 < nk) BLOAD(pf.a1, pf.b1, kt + 3);
;     __syncthreads();
;     BCOMP(1);
;     if (kt + 2 < nk) { BSTORE(pf.a0, pf.b0, 0); if (kt + 4 < nk) BLOAD(pf.a0, pf.b0, kt + 4); }
;     __syncthreads();
.Lffn1_kloop:
	s_waitcnt vmcnt(6)
	s_barrier
	ds_read_b128 v[208:211], v138 offset:0
	ds_read_b128 v[224:227], v140 offset:0
	ds_read_b128 v[228:231], v140 offset:1024
	ds_read_b128 v[232:235], v140 offset:2048
	ds_read_b128 v[236:239], v140 offset:3072
	ds_read_b128 v[212:215], v138 offset:1024
	ds_read_b128 v[216:219], v138 offset:2048
	ds_read_b128 v[220:223], v138 offset:3072
	ds_read_b128 v[240:243], v140 offset:8192
	ds_read_b128 v[244:247], v140 offset:9216
	ds_read_b128 v[248:251], v140 offset:10240
	ds_read_b128 v[156:159], v140 offset:11264
	s_add_u32 m0, s42, 0xc000
	s_add_u32 s28, s28, 0x100000
	s_addc_u32 s29, s29, 0
	global_load_lds_dwordx4 v142, s[28:29]
	global_load_lds_dwordx4 v143, s[28:29] offset:1024
	s_add_u32 m0, s43, 0xc000
	s_add_u32 s30, s30, 0x40000
	s_addc_u32 s31, s31, 0
	global_load_lds_dwordx4 v144, s[30:31]
	global_load_lds_dwordx4 v145, s[30:31] offset:1024
	global_load_lds_dwordx4 v146, s[30:31] offset:2048
	global_load_lds_dwordx4 v147, s[30:31] offset:3072
	s_waitcnt lgkmcnt(10)
	v_mfma_f32_16x16x32_bf16 v[2:5], v[224:227], v[208:211], v[2:5]
	s_waitcnt lgkmcnt(9)
	v_mfma_f32_16x16x32_bf16 v[6:9], v[228:231], v[208:211], v[6:9]
	s_waitcnt lgkmcnt(8)
	v_mfma_f32_16x16x32_bf16 v[10:13], v[232:235], v[208:211], v[10:13]
	s_waitcnt lgkmcnt(7)
	v_mfma_f32_16x16x32_bf16 v[14:17], v[236:239], v[208:211], v[14:17]
	s_waitcnt lgkmcnt(6)
	v_mfma_f32_16x16x32_bf16 v[18:21], v[224:227], v[212:215], v[18:21]
	v_mfma_f32_16x16x32_bf16 v[22:25], v[228:231], v[212:215], v[22:25]
	v_mfma_f32_16x16x32_bf16 v[26:29], v[232:235], v[212:215], v[26:29]
	v_mfma_f32_16x16x32_bf16 v[30:33], v[236:239], v[212:215], v[30:33]
	s_waitcnt lgkmcnt(5)
	v_mfma_f32_16x16x32_bf16 v[34:37], v[224:227], v[216:219], v[34:37]
	v_mfma_f32_16x16x32_bf16 v[38:41], v[228:231], v[216:219], v[38:41]
	v_mfma_f32_16x16x32_bf16 v[42:45], v[232:235], v[216:219], v[42:45]
	v_mfma_f32_16x16x32_bf16 v[46:49], v[236:239], v[216:219], v[46:49]
	s_waitcnt lgkmcnt(4)
	v_mfma_f32_16x16x32_bf16 v[50:53], v[224:227], v[220:223], v[50:53]
	v_mfma_f32_16x16x32_bf16 v[54:57], v[228:231], v[220:223], v[54:57]
	v_mfma_f32_16x16x32_bf16 v[58:61], v[232:235], v[220:223], v[58:61]
	v_mfma_f32_16x16x32_bf16 v[62:65], v[236:239], v[220:223], v[62:65]
	s_waitcnt lgkmcnt(3)
	v_mfma_f32_16x16x32_bf16 v[74:77], v[240:243], v[208:211], v[74:77]
	s_waitcnt lgkmcnt(2)
	v_mfma_f32_16x16x32_bf16 v[78:81], v[244:247], v[208:211], v[78:81]
	s_waitcnt lgkmcnt(1)
	v_mfma_f32_16x16x32_bf16 v[82:85], v[248:251], v[208:211], v[82:85]
	s_waitcnt lgkmcnt(0)
	v_mfma_f32_16x16x32_bf16 v[86:89], v[156:159], v[208:211], v[86:89]
	v_mfma_f32_16x16x32_bf16 v[90:93], v[240:243], v[212:215], v[90:93]
	v_mfma_f32_16x16x32_bf16 v[94:97], v[244:247], v[212:215], v[94:97]
	v_mfma_f32_16x16x32_bf16 v[98:101], v[248:251], v[212:215], v[98:101]
	v_mfma_f32_16x16x32_bf16 v[102:105], v[156:159], v[212:215], v[102:105]
	v_mfma_f32_16x16x32_bf16 v[106:109], v[240:243], v[216:219], v[106:109]
	v_mfma_f32_16x16x32_bf16 v[110:113], v[244:247], v[216:219], v[110:113]
	v_mfma_f32_16x16x32_bf16 v[114:117], v[248:251], v[216:219], v[114:117]
	v_mfma_f32_16x16x32_bf16 v[118:121], v[156:159], v[216:219], v[118:121]
	v_mfma_f32_16x16x32_bf16 v[122:125], v[240:243], v[220:223], v[122:125]
	v_mfma_f32_16x16x32_bf16 v[126:129], v[244:247], v[220:223], v[126:129]
	v_mfma_f32_16x16x32_bf16 v[130:133], v[248:251], v[220:223], v[130:133]
	v_mfma_f32_16x16x32_bf16 v[134:137], v[156:159], v[220:223], v[134:137]
	s_waitcnt vmcnt(6)
	s_barrier
	ds_read_b128 v[208:211], v138 offset:24576
	ds_read_b128 v[224:227], v140 offset:24576
	ds_read_b128 v[228:231], v140 offset:25600
	ds_read_b128 v[232:235], v140 offset:26624
	ds_read_b128 v[236:239], v140 offset:27648
	ds_read_b128 v[212:215], v138 offset:25600
	ds_read_b128 v[216:219], v138 offset:26624
	ds_read_b128 v[220:223], v138 offset:27648
	ds_read_b128 v[240:243], v140 offset:32768
	ds_read_b128 v[244:247], v140 offset:33792
	ds_read_b128 v[248:251], v140 offset:34816
	ds_read_b128 v[156:159], v140 offset:35840
	s_add_u32 m0, s42, 0x0
	s_add_u32 s28, s28, 0x100000
	s_addc_u32 s29, s29, 0
	global_load_lds_dwordx4 v142, s[28:29]
	global_load_lds_dwordx4 v143, s[28:29] offset:1024
	s_add_u32 m0, s43, 0x0
	s_add_u32 s30, s30, 0x40000
	s_addc_u32 s31, s31, 0
	global_load_lds_dwordx4 v144, s[30:31]
	global_load_lds_dwordx4 v145, s[30:31] offset:1024
	global_load_lds_dwordx4 v146, s[30:31] offset:2048
	global_load_lds_dwordx4 v147, s[30:31] offset:3072
	s_waitcnt lgkmcnt(10)
	v_mfma_f32_16x16x32_bf16 v[2:5], v[224:227], v[208:211], v[2:5]
	s_waitcnt lgkmcnt(9)
	v_mfma_f32_16x16x32_bf16 v[6:9], v[228:231], v[208:211], v[6:9]
	s_waitcnt lgkmcnt(8)
	v_mfma_f32_16x16x32_bf16 v[10:13], v[232:235], v[208:211], v[10:13]
	s_waitcnt lgkmcnt(7)
	v_mfma_f32_16x16x32_bf16 v[14:17], v[236:239], v[208:211], v[14:17]
	s_waitcnt lgkmcnt(6)
	v_mfma_f32_16x16x32_bf16 v[18:21], v[224:227], v[212:215], v[18:21]
	v_mfma_f32_16x16x32_bf16 v[22:25], v[228:231], v[212:215], v[22:25]
	v_mfma_f32_16x16x32_bf16 v[26:29], v[232:235], v[212:215], v[26:29]
	v_mfma_f32_16x16x32_bf16 v[30:33], v[236:239], v[212:215], v[30:33]
	s_waitcnt lgkmcnt(5)
	v_mfma_f32_16x16x32_bf16 v[34:37], v[224:227], v[216:219], v[34:37]
	v_mfma_f32_16x16x32_bf16 v[38:41], v[228:231], v[216:219], v[38:41]
	v_mfma_f32_16x16x32_bf16 v[42:45], v[232:235], v[216:219], v[42:45]
	v_mfma_f32_16x16x32_bf16 v[46:49], v[236:239], v[216:219], v[46:49]
	s_waitcnt lgkmcnt(4)
	v_mfma_f32_16x16x32_bf16 v[50:53], v[224:227], v[220:223], v[50:53]
	v_mfma_f32_16x16x32_bf16 v[54:57], v[228:231], v[220:223], v[54:57]
	v_mfma_f32_16x16x32_bf16 v[58:61], v[232:235], v[220:223], v[58:61]
	v_mfma_f32_16x16x32_bf16 v[62:65], v[236:239], v[220:223], v[62:65]
	s_waitcnt lgkmcnt(3)
	v_mfma_f32_16x16x32_bf16 v[74:77], v[240:243], v[208:211], v[74:77]
	s_waitcnt lgkmcnt(2)
	v_mfma_f32_16x16x32_bf16 v[78:81], v[244:247], v[208:211], v[78:81]
	s_waitcnt lgkmcnt(1)
	v_mfma_f32_16x16x32_bf16 v[82:85], v[248:251], v[208:211], v[82:85]
	s_waitcnt lgkmcnt(0)
	v_mfma_f32_16x16x32_bf16 v[86:89], v[156:159], v[208:211], v[86:89]
	v_mfma_f32_16x16x32_bf16 v[90:93], v[240:243], v[212:215], v[90:93]
	v_mfma_f32_16x16x32_bf16 v[94:97], v[244:247], v[212:215], v[94:97]
	v_mfma_f32_16x16x32_bf16 v[98:101], v[248:251], v[212:215], v[98:101]
	v_mfma_f32_16x16x32_bf16 v[102:105], v[156:159], v[212:215], v[102:105]
	v_mfma_f32_16x16x32_bf16 v[106:109], v[240:243], v[216:219], v[106:109]
	v_mfma_f32_16x16x32_bf16 v[110:113], v[244:247], v[216:219], v[110:113]
	v_mfma_f32_16x16x32_bf16 v[114:117], v[248:251], v[216:219], v[114:117]
	v_mfma_f32_16x16x32_bf16 v[118:121], v[156:159], v[216:219], v[118:121]
	v_mfma_f32_16x16x32_bf16 v[122:125], v[240:243], v[220:223], v[122:125]
	v_mfma_f32_16x16x32_bf16 v[126:129], v[244:247], v[220:223], v[126:129]
	v_mfma_f32_16x16x32_bf16 v[130:133], v[248:251], v[220:223], v[130:133]
	v_mfma_f32_16x16x32_bf16 v[134:137], v[156:159], v[220:223], v[134:137]
	s_waitcnt vmcnt(6)
	s_barrier
; #define BLOAD(A_, B_, kt) do { _Pragma("unroll") for (int i = 0; i < 4; ++i) { \
;     A_[i] = *(const u32x4*)((const char*)Ap + (aoff + (unsigned)(32 * i * lda + (kt) * 64) * 2u)); B_[i] = *(const u32x4*)((const char*)Wt + (woff + (unsigned)(32 * i * K + (kt) * 64) * 2u)); } } while (0)
; #define BLOAD(A_, B_, kt) do { _Pragma("unroll") for (int i = 0; i < 4; ++i) { \
;     A_[i] = *(const u32x4*)((const char*)Ap + (aoff + (unsigned)(32 * i * lda + (kt) * 64) * 2u)); B_[i] = *(const u32x4*)((const char*)Wt + (woff + (unsigned)(32 * i * K + (kt) * 64) * 2u)); } } while (0)
; #define BSTORE(A_, B_, buf) do { _Pragma("unroll") for (int i = 0; i < 4; ++i) { \
;     *(u32x4*)&As[(buf) * GBUF + (srow + 32 * i) * LDT + sc8] = A_[i]; \
;     *(u32x4*)&Bs[(buf) * GBUF + (srow + 32 * i) * LDT + sc8] = B_[i]; } } while (0)
; template <int NK>
; DI void gemm_run(PF& pf, const u16* __restrict__ Ap, int lda, const u16* __restrict__ Wt, f32x16 (&acc)[2][2], char* smem) {
;     ...
;   __builtin_amdgcn_s_setprio(0);
;   __syncthreads();
;   BSTORE(pf.a0, pf.b0, 0);
;   BLOAD(pf.a0, pf.b0, 2);
;   __syncthreads();
; #pragma unroll
;   for (int kt = 0; kt < nk; kt += 2) {
;     BCOMP(0);
;     BSTORE(pf.a1, pf.b1, 1);
;     if (kt + 3 < nk) BLOAD(pf.a1, pf.b1, kt + 3);
;     __syncthreads();
;     BCOMP(1);
;     if (kt + 2 < nk) { BSTORE(pf.a0, pf.b0, 0); if (kt + 4 < nk) BLOAD(pf.a0, pf.b0, kt + 4); }
;     __syncthreads();
	ds_read_b128 v[208:211], v138 offset:49152
	ds_read_b128 v[224:227], v140 offset:49152
	ds_read_b128 v[228:231], v140 offset:50176
	ds_read_b128 v[232:235], v140 offset:51200
	ds_read_b128 v[236:239], v140 offset:52224
	ds_read_b128 v[212:215], v138 offset:50176
	ds_read_b128 v[216:219], v138 offset:51200
	ds_read_b128 v[220:223], v138 offset:52224
	ds_read_b128 v[240:243], v140 offset:57344
	ds_read_b128 v[244:247], v140 offset:58368
	ds_read_b128 v[248:251], v140 offset:59392
	ds_read_b128 v[156:159], v140 offset:60416
	s_add_u32 m0, s42, 0x6000
	s_add_u32 s28, s28, 0x100000
	s_addc_u32 s29, s29, 0
	global_load_lds_dwordx4 v142, s[28:29]
	global_load_lds_dwordx4 v143, s[28:29] offset:1024
	s_add_u32 m0, s43, 0x6000
	s_add_u32 s30, s30, 0x40000
	s_addc_u32 s31, s31, 0
	global_load_lds_dwordx4 v144, s[30:31]
	global_load_lds_dwordx4 v145, s[30:31] offset:1024
	global_load_lds_dwordx4 v146, s[30:31] offset:2048
	global_load_lds_dwordx4 v147, s[30:31] offset:3072
	s_waitcnt lgkmcnt(10)
	v_mfma_f32_16x16x32_bf16 v[2:5], v[224:227], v[208:211], v[2:5]
	s_waitcnt lgkmcnt(9)
	v_mfma_f32_16x16x32_bf16 v[6:9], v[228:231], v[208:211], v[6:9]
	s_waitcnt lgkmcnt(8)
	v_mfma_f32_16x16x32_bf16 v[10:13], v[232:235], v[208:211], v[10:13]
	s_waitcnt lgkmcnt(7)
	v_mfma_f32_16x16x32_bf16 v[14:17], v[236:239], v[208:211], v[14:17]
	s_waitcnt lgkmcnt(6)
	v_mfma_f32_16x16x32_bf16 v[18:21], v[224:227], v[212:215], v[18:21]
	v_mfma_f32_16x16x32_bf16 v[22:25], v[228:231], v[212:215], v[22:25]
	v_mfma_f32_16x16x32_bf16 v[26:29], v[232:235], v[212:215], v[26:29]
	v_mfma_f32_16x16x32_bf16 v[30:33], v[236:239], v[212:215], v[30:33]
	s_waitcnt lgkmcnt(5)
	v_mfma_f32_16x16x32_bf16 v[34:37], v[224:227], v[216:219], v[34:37]
	v_mfma_f32_16x16x32_bf16 v[38:41], v[228:231], v[216:219], v[38:41]
	v_mfma_f32_16x16x32_bf16 v[42:45], v[232:235], v[216:219], v[42:45]
	v_mfma_f32_16x16x32_bf16 v[46:49], v[236:239], v[216:219], v[46:49]
	s_waitcnt lgkmcnt(4)
	v_mfma_f32_16x16x32_bf16 v[50:53], v[224:227], v[220:223], v[50:53]
	v_mfma_f32_16x16x32_bf16 v[54:57], v[228:231], v[220:223], v[54:57]
	v_mfma_f32_16x16x32_bf16 v[58:61], v[232:235], v[220:223], v[58:61]
	v_mfma_f32_16x16x32_bf16 v[62:65], v[236:239], v[220:223], v[62:65]
	s_waitcnt lgkmcnt(3)
	v_mfma_f32_16x16x32_bf16 v[74:77], v[240:243], v[208:211], v[74:77]
	s_waitcnt lgkmcnt(2)
	v_mfma_f32_16x16x32_bf16 v[78:81], v[244:247], v[208:211], v[78:81]
	s_waitcnt lgkmcnt(1)
	v_mfma_f32_16x16x32_bf16 v[82:85], v[248:251], v[208:211], v[82:85]
	s_waitcnt lgkmcnt(0)
	v_mfma_f32_16x16x32_bf16 v[86:89], v[156:159], v[208:211], v[86:89]
	v_mfma_f32_16x16x32_bf16 v[90:93], v[240:243], v[212:215], v[90:93]
	v_mfma_f32_16x16x32_bf16 v[94:97], v[244:247], v[212:215], v[94:97]
	v_mfma_f32_16x16x32_bf16 v[98:101], v[248:251], v[212:215], v[98:101]
	v_mfma_f32_16x16x32_bf16 v[102:105], v[156:159], v[212:215], v[102:105]
	v_mfma_f32_16x16x32_bf16 v[106:109], v[240:243], v[216:219], v[106:109]
	v_mfma_f32_16x16x32_bf16 v[110:113], v[244:247], v[216:219], v[110:113]
	v_mfma_f32_16x16x32_bf16 v[114:117], v[248:251], v[216:219], v[114:117]
	v_mfma_f32_16x16x32_bf16 v[118:121], v[156:159], v[216:219], v[118:121]
	v_mfma_f32_16x16x32_bf16 v[122:125], v[240:243], v[220:223], v[122:125]
	v_mfma_f32_16x16x32_bf16 v[126:129], v[244:247], v[220:223], v[126:129]
	v_mfma_f32_16x16x32_bf16 v[130:133], v[248:251], v[220:223], v[130:133]
	v_mfma_f32_16x16x32_bf16 v[134:137], v[156:159], v[220:223], v[134:137]
	s_sub_u32 s46, s46, 1
	s_cmp_lg_u32 s46, 0
	s_cbranch_scc1 .Lffn1_kloop
	s_waitcnt vmcnt(6)
	s_barrier
; #define BLOAD(A_, B_, kt) do { _Pragma("unroll") for (int i = 0; i < 4; ++i) { \
;     A_[i] = *(const u32x4*)((const char*)Ap + (aoff + (unsigned)(32 * i * lda + (kt) * 64) * 2u)); B_[i] = *(const u32x4*)((const char*)Wt + (woff + (unsigned)(32 * i * K + (kt) * 64) * 2u)); } } while (0)
; #define BLOAD(A_, B_, kt) do { _Pragma("unroll") for (int i = 0; i < 4; ++i) { \
;     A_[i] = *(const u32x4*)((const char*)Ap + (aoff + (unsigned)(32 * i * lda + (kt) * 64) * 2u)); B_[i] = *(const u32x4*)((const char*)Wt + (woff + (unsigned)(32 * i * K + (kt) * 64) * 2u)); } } while (0)
; #define BSTORE(A_, B_, buf) do { _Pragma("unroll") for (int i = 0; i < 4; ++i) { \
;     *(u32x4*)&As[(buf) * GBUF + (srow + 32 * i) * LDT + sc8] = A_[i]; \
;     *(u32x4*)&Bs[(buf) * GBUF + (srow + 32 * i) * LDT + sc8] = B_[i]; } } while (0)
; template <int NK>
; DI void gemm_run(PF& pf, const u16* __restrict__ Ap, int lda, const u16* __restrict__ Wt, f32x16 (&acc)[2][2], char* smem) {
;     ...
; #pragma unroll
;   for (int kt = 0; kt < nk; kt += 2) {
;     BCOMP(0);
;     BSTORE(pf.a1, pf.b1, 1);
;     if (kt + 3 < nk) BLOAD(pf.a1, pf.b1, kt + 3);
;     __syncthreads();
;     BCOMP(1);
;     if (kt + 2 < nk) { BSTORE(pf.a0, pf.b0, 0); if (kt + 4 < nk) BLOAD(pf.a0, pf.b0, kt + 4); }
;     __syncthreads();
;   }
	ds_read_b128 v[208:211], v138 offset:0
	ds_read_b128 v[224:227], v140 offset:0
	ds_read_b128 v[228:231], v140 offset:1024
	ds_read_b128 v[232:235], v140 offset:2048
	ds_read_b128 v[236:239], v140 offset:3072
	ds_read_b128 v[212:215], v138 offset:1024
	ds_read_b128 v[216:219], v138 offset:2048
	ds_read_b128 v[220:223], v138 offset:3072
	ds_read_b128 v[240:243], v140 offset:8192
	ds_read_b128 v[244:247], v140 offset:9216
	ds_read_b128 v[248:251], v140 offset:10240
	ds_read_b128 v[156:159], v140 offset:11264
	s_waitcnt lgkmcnt(10)
	v_mfma_f32_16x16x32_bf16 v[2:5], v[224:227], v[208:211], v[2:5]
	s_waitcnt lgkmcnt(9)
	v_mfma_f32_16x16x32_bf16 v[6:9], v[228:231], v[208:211], v[6:9]
	s_waitcnt lgkmcnt(8)
	v_mfma_f32_16x16x32_bf16 v[10:13], v[232:235], v[208:211], v[10:13]
	s_waitcnt lgkmcnt(7)
	v_mfma_f32_16x16x32_bf16 v[14:17], v[236:239], v[208:211], v[14:17]
	s_waitcnt lgkmcnt(6)
	v_mfma_f32_16x16x32_bf16 v[18:21], v[224:227], v[212:215], v[18:21]
	v_mfma_f32_16x16x32_bf16 v[22:25], v[228:231], v[212:215], v[22:25]
	v_mfma_f32_16x16x32_bf16 v[26:29], v[232:235], v[212:215], v[26:29]
	v_mfma_f32_16x16x32_bf16 v[30:33], v[236:239], v[212:215], v[30:33]
	s_waitcnt lgkmcnt(5)
	v_mfma_f32_16x16x32_bf16 v[34:37], v[224:227], v[216:219], v[34:37]
	v_mfma_f32_16x16x32_bf16 v[38:41], v[228:231], v[216:219], v[38:41]
	v_mfma_f32_16x16x32_bf16 v[42:45], v[232:235], v[216:219], v[42:45]
	v_mfma_f32_16x16x32_bf16 v[46:49], v[236:239], v[216:219], v[46:49]
	s_waitcnt lgkmcnt(4)
	v_mfma_f32_16x16x32_bf16 v[50:53], v[224:227], v[220:223], v[50:53]
	v_mfma_f32_16x16x32_bf16 v[54:57], v[228:231], v[220:223], v[54:57]
	v_mfma_f32_16x16x32_bf16 v[58:61], v[232:235], v[220:223], v[58:61]
	v_mfma_f32_16x16x32_bf16 v[62:65], v[236:239], v[220:223], v[62:65]
	s_waitcnt lgkmcnt(3)
	v_mfma_f32_16x16x32_bf16 v[74:77], v[240:243], v[208:211], v[74:77]
	s_waitcnt lgkmcnt(2)
	v_mfma_f32_16x16x32_bf16 v[78:81], v[244:247], v[208:211], v[78:81]
	s_waitcnt lgkmcnt(1)
	v_mfma_f32_16x16x32_bf16 v[82:85], v[248:251], v[208:211], v[82:85]
	s_waitcnt lgkmcnt(0)
	v_mfma_f32_16x16x32_bf16 v[86:89], v[156:159], v[208:211], v[86:89]
	v_mfma_f32_16x16x32_bf16 v[90:93], v[240:243], v[212:215], v[90:93]
	v_mfma_f32_16x16x32_bf16 v[94:97], v[244:247], v[212:215], v[94:97]
	v_mfma_f32_16x16x32_bf16 v[98:101], v[248:251], v[212:215], v[98:101]
	v_mfma_f32_16x16x32_bf16 v[102:105], v[156:159], v[212:215], v[102:105]
	v_mfma_f32_16x16x32_bf16 v[106:109], v[240:243], v[216:219], v[106:109]
	v_mfma_f32_16x16x32_bf16 v[110:113], v[244:247], v[216:219], v[110:113]
	v_mfma_f32_16x16x32_bf16 v[114:117], v[248:251], v[216:219], v[114:117]
	v_mfma_f32_16x16x32_bf16 v[118:121], v[156:159], v[216:219], v[118:121]
	v_mfma_f32_16x16x32_bf16 v[122:125], v[240:243], v[220:223], v[122:125]
	v_mfma_f32_16x16x32_bf16 v[126:129], v[244:247], v[220:223], v[126:129]
	v_mfma_f32_16x16x32_bf16 v[130:133], v[248:251], v[220:223], v[130:133]
	v_mfma_f32_16x16x32_bf16 v[134:137], v[156:159], v[220:223], v[134:137]
	s_waitcnt vmcnt(0)
	s_barrier
	ds_read_b128 v[208:211], v138 offset:24576
	ds_read_b128 v[224:227], v140 offset:24576
	ds_read_b128 v[228:231], v140 offset:25600
	ds_read_b128 v[232:235], v140 offset:26624
	ds_read_b128 v[236:239], v140 offset:27648
	ds_read_b128 v[212:215], v138 offset:25600
	ds_read_b128 v[216:219], v138 offset:26624
	ds_read_b128 v[220:223], v138 offset:27648
	ds_read_b128 v[240:243], v140 offset:32768
	ds_read_b128 v[244:247], v140 offset:33792
	ds_read_b128 v[248:251], v140 offset:34816
	ds_read_b128 v[156:159], v140 offset:35840
	s_waitcnt lgkmcnt(10)
	v_mfma_f32_16x16x32_bf16 v[2:5], v[224:227], v[208:211], v[2:5]
	s_waitcnt lgkmcnt(9)
	v_mfma_f32_16x16x32_bf16 v[6:9], v[228:231], v[208:211], v[6:9]
	s_waitcnt lgkmcnt(8)
	v_mfma_f32_16x16x32_bf16 v[10:13], v[232:235], v[208:211], v[10:13]
	s_waitcnt lgkmcnt(7)
	v_mfma_f32_16x16x32_bf16 v[14:17], v[236:239], v[208:211], v[14:17]
	s_waitcnt lgkmcnt(6)
	v_mfma_f32_16x16x32_bf16 v[18:21], v[224:227], v[212:215], v[18:21]
	v_mfma_f32_16x16x32_bf16 v[22:25], v[228:231], v[212:215], v[22:25]
	v_mfma_f32_16x16x32_bf16 v[26:29], v[232:235], v[212:215], v[26:29]
	v_mfma_f32_16x16x32_bf16 v[30:33], v[236:239], v[212:215], v[30:33]
	s_waitcnt lgkmcnt(5)
	v_mfma_f32_16x16x32_bf16 v[34:37], v[224:227], v[216:219], v[34:37]
	v_mfma_f32_16x16x32_bf16 v[38:41], v[228:231], v[216:219], v[38:41]
	v_mfma_f32_16x16x32_bf16 v[42:45], v[232:235], v[216:219], v[42:45]
	v_mfma_f32_16x16x32_bf16 v[46:49], v[236:239], v[216:219], v[46:49]
	s_waitcnt lgkmcnt(4)
	v_mfma_f32_16x16x32_bf16 v[50:53], v[224:227], v[220:223], v[50:53]
	v_mfma_f32_16x16x32_bf16 v[54:57], v[228:231], v[220:223], v[54:57]
	v_mfma_f32_16x16x32_bf16 v[58:61], v[232:235], v[220:223], v[58:61]
	v_mfma_f32_16x16x32_bf16 v[62:65], v[236:239], v[220:223], v[62:65]
	s_waitcnt lgkmcnt(3)
	v_mfma_f32_16x16x32_bf16 v[74:77], v[240:243], v[208:211], v[74:77]
	s_waitcnt lgkmcnt(2)
	v_mfma_f32_16x16x32_bf16 v[78:81], v[244:247], v[208:211], v[78:81]
	s_waitcnt lgkmcnt(1)
	v_mfma_f32_16x16x32_bf16 v[82:85], v[248:251], v[208:211], v[82:85]
	s_waitcnt lgkmcnt(0)
	v_mfma_f32_16x16x32_bf16 v[86:89], v[156:159], v[208:211], v[86:89]
	v_mfma_f32_16x16x32_bf16 v[90:93], v[240:243], v[212:215], v[90:93]
	v_mfma_f32_16x16x32_bf16 v[94:97], v[244:247], v[212:215], v[94:97]
	v_mfma_f32_16x16x32_bf16 v[98:101], v[248:251], v[212:215], v[98:101]
	v_mfma_f32_16x16x32_bf16 v[102:105], v[156:159], v[212:215], v[102:105]
	v_mfma_f32_16x16x32_bf16 v[106:109], v[240:243], v[216:219], v[106:109]
	v_mfma_f32_16x16x32_bf16 v[110:113], v[244:247], v[216:219], v[110:113]
	v_mfma_f32_16x16x32_bf16 v[114:117], v[248:251], v[216:219], v[114:117]
	v_mfma_f32_16x16x32_bf16 v[118:121], v[156:159], v[216:219], v[118:121]
	v_mfma_f32_16x16x32_bf16 v[122:125], v[240:243], v[220:223], v[122:125]
	v_mfma_f32_16x16x32_bf16 v[126:129], v[244:247], v[220:223], v[126:129]
	v_mfma_f32_16x16x32_bf16 v[130:133], v[248:251], v[220:223], v[130:133]
	v_mfma_f32_16x16x32_bf16 v[134:137], v[156:159], v[220:223], v[134:137]
	s_barrier

; #define BLOAD(A_, B_, kt) do { _Pragma("unroll") for (int i = 0; i < 4; ++i) { \
;     A_[i] = *(const u32x4*)((const char*)Ap + (aoff + (unsigned)(32 * i * lda + (kt) * 64) * 2u)); B_[i] = *(const u32x4*)((const char*)Wt + (woff + (unsigned)(32 * i * K + (kt) * 64) * 2u)); } } while (0)
; #define BLOAD(A_, B_, kt) do { _Pragma("unroll") for (int i = 0; i < 4; ++i) { \
;     A_[i] = *(const u32x4*)((const char*)Ap + (aoff + (unsigned)(32 * i * lda + (kt) * 64) * 2u)); B_[i] = *(const u32x4*)((const char*)Wt + (woff + (unsigned)(32 * i * K + (kt) * 64) * 2u)); } } while (0)
; #define BSTORE(A_, B_, buf) do { _Pragma("unroll") for (int i = 0; i < 4; ++i) { \
;     *(u32x4*)&As[(buf) * GBUF + (srow + 32 * i) * LDT + sc8] = A_[i]; \
;     *(u32x4*)&Bs[(buf) * GBUF + (srow + 32 * i) * LDT + sc8] = B_[i]; } } while (0)
; template <int NK>
; DI void gemm_run(PF& pf, const u16* __restrict__ Ap, int lda, const u16* __restrict__ Wt, f32x16 (&acc)[2][2], char* smem) {
;     ...
;   __builtin_amdgcn_s_setprio(0);
;   __syncthreads();
;   BSTORE(pf.a0, pf.b0, 0);
;   BLOAD(pf.a0, pf.b0, 2);
;   __syncthreads();
; #pragma unroll
;   for (int kt = 0; kt < nk; kt += 2) {
;     BCOMP(0);
;     BSTORE(pf.a1, pf.b1, 1);
;     if (kt + 3 < nk) BLOAD(pf.a1, pf.b1, kt + 3);
;     __syncthreads();
;     BCOMP(1);
;     if (kt + 2 < nk) { BSTORE(pf.a0, pf.b0, 0); if (kt + 4 < nk) BLOAD(pf.a0, pf.b0, kt + 4); }
;     __syncthreads();
.Lout_kloop:
	s_waitcnt vmcnt(6)
	s_barrier
	ds_read_b128 v[224:227], v126 offset:0
	ds_read_b128 v[240:243], v128 offset:0
	ds_read_b128 v[244:247], v128 offset:1024
	ds_read_b128 v[248:251], v128 offset:2048
	ds_read_b128 v[156:159], v128 offset:3072
	ds_read_b128 v[228:231], v126 offset:1024
	ds_read_b128 v[232:235], v126 offset:2048
	ds_read_b128 v[236:239], v126 offset:3072
	ds_read_b128 v[160:163], v128 offset:8192
	ds_read_b128 v[164:167], v128 offset:9216
	ds_read_b128 v[168:171], v128 offset:10240
	ds_read_b128 v[122:125], v128 offset:11264
	s_add_u32 m0, s42, 0xc000
	s_add_u32 s28, s28, 0x100000
	s_addc_u32 s29, s29, 0
	global_load_lds_dwordx4 v143, s[28:29]
	global_load_lds_dwordx4 v144, s[28:29] offset:1024
	s_add_u32 m0, s43, 0xc000
	s_add_u32 s30, s30, 0x10000
	s_addc_u32 s31, s31, 0
	global_load_lds_dwordx4 v145, s[30:31]
	global_load_lds_dwordx4 v146, s[30:31] offset:1024
	global_load_lds_dwordx4 v147, s[30:31] offset:2048
	global_load_lds_dwordx4 v148, s[30:31] offset:3072
	s_waitcnt lgkmcnt(10)
	v_mfma_f32_16x16x32_bf16 v[2:5], v[240:243], v[224:227], v[2:5]
	s_waitcnt lgkmcnt(9)
	v_mfma_f32_16x16x32_bf16 v[6:9], v[244:247], v[224:227], v[6:9]
	s_waitcnt lgkmcnt(8)
	v_mfma_f32_16x16x32_bf16 v[10:13], v[248:251], v[224:227], v[10:13]
	s_waitcnt lgkmcnt(7)
	v_mfma_f32_16x16x32_bf16 v[14:17], v[156:159], v[224:227], v[14:17]
	s_waitcnt lgkmcnt(6)
	v_mfma_f32_16x16x32_bf16 v[18:21], v[240:243], v[228:231], v[18:21]
	v_mfma_f32_16x16x32_bf16 v[22:25], v[244:247], v[228:231], v[22:25]
	v_mfma_f32_16x16x32_bf16 v[26:29], v[248:251], v[228:231], v[26:29]
	v_mfma_f32_16x16x32_bf16 v[30:33], v[156:159], v[228:231], v[30:33]
	s_waitcnt lgkmcnt(5)
	v_mfma_f32_16x16x32_bf16 v[34:37], v[240:243], v[232:235], v[34:37]
	v_mfma_f32_16x16x32_bf16 v[38:41], v[244:247], v[232:235], v[38:41]
	v_mfma_f32_16x16x32_bf16 v[42:45], v[248:251], v[232:235], v[42:45]
	v_mfma_f32_16x16x32_bf16 v[46:49], v[156:159], v[232:235], v[46:49]
	s_waitcnt lgkmcnt(4)
	v_mfma_f32_16x16x32_bf16 v[50:53], v[240:243], v[236:239], v[50:53]
	v_mfma_f32_16x16x32_bf16 v[54:57], v[244:247], v[236:239], v[54:57]
	v_mfma_f32_16x16x32_bf16 v[58:61], v[248:251], v[236:239], v[58:61]
	v_mfma_f32_16x16x32_bf16 v[62:65], v[156:159], v[236:239], v[62:65]
	s_waitcnt lgkmcnt(3)
	v_mfma_f32_16x16x32_bf16 v[74:77], v[160:163], v[224:227], v[74:77]
	s_waitcnt lgkmcnt(2)
	v_mfma_f32_16x16x32_bf16 v[78:81], v[164:167], v[224:227], v[78:81]
	s_waitcnt lgkmcnt(1)
	v_mfma_f32_16x16x32_bf16 v[82:85], v[168:171], v[224:227], v[82:85]
	s_waitcnt lgkmcnt(0)
	v_mfma_f32_16x16x32_bf16 v[86:89], v[122:125], v[224:227], v[86:89]
	v_mfma_f32_16x16x32_bf16 v[90:93], v[160:163], v[228:231], v[90:93]
	v_mfma_f32_16x16x32_bf16 v[94:97], v[164:167], v[228:231], v[94:97]
	v_mfma_f32_16x16x32_bf16 v[98:101], v[168:171], v[228:231], v[98:101]
	v_mfma_f32_16x16x32_bf16 v[102:105], v[122:125], v[228:231], v[102:105]
	v_mfma_f32_16x16x32_bf16 v[106:109], v[160:163], v[232:235], v[106:109]
	v_mfma_f32_16x16x32_bf16 v[110:113], v[164:167], v[232:235], v[110:113]
	v_mfma_f32_16x16x32_bf16 v[114:117], v[168:171], v[232:235], v[114:117]
	v_mfma_f32_16x16x32_bf16 v[118:121], v[122:125], v[232:235], v[118:121]
	v_mfma_f32_16x16x32_bf16 v[208:211], v[160:163], v[236:239], v[208:211]
	v_mfma_f32_16x16x32_bf16 v[212:215], v[164:167], v[236:239], v[212:215]
	v_mfma_f32_16x16x32_bf16 v[216:219], v[168:171], v[236:239], v[216:219]
	v_mfma_f32_16x16x32_bf16 v[220:223], v[122:125], v[236:239], v[220:223]
	s_waitcnt vmcnt(6)
	s_barrier
	ds_read_b128 v[224:227], v126 offset:24576
	ds_read_b128 v[240:243], v128 offset:24576
	ds_read_b128 v[244:247], v128 offset:25600
	ds_read_b128 v[248:251], v128 offset:26624
	ds_read_b128 v[156:159], v128 offset:27648
	ds_read_b128 v[228:231], v126 offset:25600
	ds_read_b128 v[232:235], v126 offset:26624
	ds_read_b128 v[236:239], v126 offset:27648
	ds_read_b128 v[160:163], v128 offset:32768
	ds_read_b128 v[164:167], v128 offset:33792
	ds_read_b128 v[168:171], v128 offset:34816
	ds_read_b128 v[122:125], v128 offset:35840
	s_add_u32 m0, s42, 0x0
	s_add_u32 s28, s28, 0x100000
	s_addc_u32 s29, s29, 0
	global_load_lds_dwordx4 v143, s[28:29]
	global_load_lds_dwordx4 v144, s[28:29] offset:1024
	s_add_u32 m0, s43, 0x0
	s_add_u32 s30, s30, 0x10000
	s_addc_u32 s31, s31, 0
	global_load_lds_dwordx4 v145, s[30:31]
	global_load_lds_dwordx4 v146, s[30:31] offset:1024
	global_load_lds_dwordx4 v147, s[30:31] offset:2048
	global_load_lds_dwordx4 v148, s[30:31] offset:3072
	s_waitcnt lgkmcnt(10)
	v_mfma_f32_16x16x32_bf16 v[2:5], v[240:243], v[224:227], v[2:5]
	s_waitcnt lgkmcnt(9)
	v_mfma_f32_16x16x32_bf16 v[6:9], v[244:247], v[224:227], v[6:9]
	s_waitcnt lgkmcnt(8)
	v_mfma_f32_16x16x32_bf16 v[10:13], v[248:251], v[224:227], v[10:13]
	s_waitcnt lgkmcnt(7)
	v_mfma_f32_16x16x32_bf16 v[14:17], v[156:159], v[224:227], v[14:17]
	s_waitcnt lgkmcnt(6)
	v_mfma_f32_16x16x32_bf16 v[18:21], v[240:243], v[228:231], v[18:21]
	v_mfma_f32_16x16x32_bf16 v[22:25], v[244:247], v[228:231], v[22:25]
	v_mfma_f32_16x16x32_bf16 v[26:29], v[248:251], v[228:231], v[26:29]
	v_mfma_f32_16x16x32_bf16 v[30:33], v[156:159], v[228:231], v[30:33]
	s_waitcnt lgkmcnt(5)
	v_mfma_f32_16x16x32_bf16 v[34:37], v[240:243], v[232:235], v[34:37]
	v_mfma_f32_16x16x32_bf16 v[38:41], v[244:247], v[232:235], v[38:41]
	v_mfma_f32_16x16x32_bf16 v[42:45], v[248:251], v[232:235], v[42:45]
	v_mfma_f32_16x16x32_bf16 v[46:49], v[156:159], v[232:235], v[46:49]
	s_waitcnt lgkmcnt(4)
	v_mfma_f32_16x16x32_bf16 v[50:53], v[240:243], v[236:239], v[50:53]
	v_mfma_f32_16x16x32_bf16 v[54:57], v[244:247], v[236:239], v[54:57]
	v_mfma_f32_16x16x32_bf16 v[58:61], v[248:251], v[236:239], v[58:61]
	v_mfma_f32_16x16x32_bf16 v[62:65], v[156:159], v[236:239], v[62:65]
	s_waitcnt lgkmcnt(3)
	v_mfma_f32_16x16x32_bf16 v[74:77], v[160:163], v[224:227], v[74:77]
	s_waitcnt lgkmcnt(2)
	v_mfma_f32_16x16x32_bf16 v[78:81], v[164:167], v[224:227], v[78:81]
	s_waitcnt lgkmcnt(1)
	v_mfma_f32_16x16x32_bf16 v[82:85], v[168:171], v[224:227], v[82:85]
	s_waitcnt lgkmcnt(0)
	v_mfma_f32_16x16x32_bf16 v[86:89], v[122:125], v[224:227], v[86:89]
	v_mfma_f32_16x16x32_bf16 v[90:93], v[160:163], v[228:231], v[90:93]
	v_mfma_f32_16x16x32_bf16 v[94:97], v[164:167], v[228:231], v[94:97]
	v_mfma_f32_16x16x32_bf16 v[98:101], v[168:171], v[228:231], v[98:101]
	v_mfma_f32_16x16x32_bf16 v[102:105], v[122:125], v[228:231], v[102:105]
	v_mfma_f32_16x16x32_bf16 v[106:109], v[160:163], v[232:235], v[106:109]
	v_mfma_f32_16x16x32_bf16 v[110:113], v[164:167], v[232:235], v[110:113]
	v_mfma_f32_16x16x32_bf16 v[114:117], v[168:171], v[232:235], v[114:117]
	v_mfma_f32_16x16x32_bf16 v[118:121], v[122:125], v[232:235], v[118:121]
	v_mfma_f32_16x16x32_bf16 v[208:211], v[160:163], v[236:239], v[208:211]
	v_mfma_f32_16x16x32_bf16 v[212:215], v[164:167], v[236:239], v[212:215]
	v_mfma_f32_16x16x32_bf16 v[216:219], v[168:171], v[236:239], v[216:219]
	v_mfma_f32_16x16x32_bf16 v[220:223], v[122:125], v[236:239], v[220:223]
	s_waitcnt vmcnt(6)
	s_barrier
; #define BLOAD(A_, B_, kt) do { _Pragma("unroll") for (int i = 0; i < 4; ++i) { \
;     A_[i] = *(const u32x4*)((const char*)Ap + (aoff + (unsigned)(32 * i * lda + (kt) * 64) * 2u)); B_[i] = *(const u32x4*)((const char*)Wt + (woff + (unsigned)(32 * i * K + (kt) * 64) * 2u)); } } while (0)
; #define BLOAD(A_, B_, kt) do { _Pragma("unroll") for (int i = 0; i < 4; ++i) { \
;     A_[i] = *(const u32x4*)((const char*)Ap + (aoff + (unsigned)(32 * i * lda + (kt) * 64) * 2u)); B_[i] = *(const u32x4*)((const char*)Wt + (woff + (unsigned)(32 * i * K + (kt) * 64) * 2u)); } } while (0)
; #define BSTORE(A_, B_, buf) do { _Pragma("unroll") for (int i = 0; i < 4; ++i) { \
;     *(u32x4*)&As[(buf) * GBUF + (srow + 32 * i) * LDT + sc8] = A_[i]; \
;     *(u32x4*)&Bs[(buf) * GBUF + (srow + 32 * i) * LDT + sc8] = B_[i]; } } while (0)
; template <int NK>
; DI void gemm_run(PF& pf, const u16* __restrict__ Ap, int lda, const u16* __restrict__ Wt, f32x16 (&acc)[2][2], char* smem) {
;     ...
;   __builtin_amdgcn_s_setprio(0);
;   __syncthreads();
;   BSTORE(pf.a0, pf.b0, 0);
;   BLOAD(pf.a0, pf.b0, 2);
;   __syncthreads();
; #pragma unroll
;   for (int kt = 0; kt < nk; kt += 2) {
;     BCOMP(0);
;     BSTORE(pf.a1, pf.b1, 1);
;     if (kt + 3 < nk) BLOAD(pf.a1, pf.b1, kt + 3);
;     __syncthreads();
;     BCOMP(1);
;     if (kt + 2 < nk) { BSTORE(pf.a0, pf.b0, 0); if (kt + 4 < nk) BLOAD(pf.a0, pf.b0, kt + 4); }
;     __syncthreads();
;   }
	ds_read_b128 v[224:227], v126 offset:49152
	ds_read_b128 v[240:243], v128 offset:49152
	ds_read_b128 v[244:247], v128 offset:50176
	ds_read_b128 v[248:251], v128 offset:51200
	ds_read_b128 v[156:159], v128 offset:52224
	ds_read_b128 v[228:231], v126 offset:50176
	ds_read_b128 v[232:235], v126 offset:51200
	ds_read_b128 v[236:239], v126 offset:52224
	ds_read_b128 v[160:163], v128 offset:57344
	ds_read_b128 v[164:167], v128 offset:58368
	ds_read_b128 v[168:171], v128 offset:59392
	ds_read_b128 v[122:125], v128 offset:60416
	s_add_u32 m0, s42, 0x6000
	s_add_u32 s28, s28, 0x100000
	s_addc_u32 s29, s29, 0
	global_load_lds_dwordx4 v143, s[28:29]
	global_load_lds_dwordx4 v144, s[28:29] offset:1024
	s_add_u32 m0, s43, 0x6000
	s_add_u32 s30, s30, 0x10000
	s_addc_u32 s31, s31, 0
	global_load_lds_dwordx4 v145, s[30:31]
	global_load_lds_dwordx4 v146, s[30:31] offset:1024
	global_load_lds_dwordx4 v147, s[30:31] offset:2048
	global_load_lds_dwordx4 v148, s[30:31] offset:3072
	s_waitcnt lgkmcnt(10)
	v_mfma_f32_16x16x32_bf16 v[2:5], v[240:243], v[224:227], v[2:5]
	s_waitcnt lgkmcnt(9)
	v_mfma_f32_16x16x32_bf16 v[6:9], v[244:247], v[224:227], v[6:9]
	s_waitcnt lgkmcnt(8)
	v_mfma_f32_16x16x32_bf16 v[10:13], v[248:251], v[224:227], v[10:13]
	s_waitcnt lgkmcnt(7)
	v_mfma_f32_16x16x32_bf16 v[14:17], v[156:159], v[224:227], v[14:17]
	s_waitcnt lgkmcnt(6)
	v_mfma_f32_16x16x32_bf16 v[18:21], v[240:243], v[228:231], v[18:21]
	v_mfma_f32_16x16x32_bf16 v[22:25], v[244:247], v[228:231], v[22:25]
	v_mfma_f32_16x16x32_bf16 v[26:29], v[248:251], v[228:231], v[26:29]
	v_mfma_f32_16x16x32_bf16 v[30:33], v[156:159], v[228:231], v[30:33]
	s_waitcnt lgkmcnt(5)
	v_mfma_f32_16x16x32_bf16 v[34:37], v[240:243], v[232:235], v[34:37]
	v_mfma_f32_16x16x32_bf16 v[38:41], v[244:247], v[232:235], v[38:41]
	v_mfma_f32_16x16x32_bf16 v[42:45], v[248:251], v[232:235], v[42:45]
	v_mfma_f32_16x16x32_bf16 v[46:49], v[156:159], v[232:235], v[46:49]
	s_waitcnt lgkmcnt(4)
	v_mfma_f32_16x16x32_bf16 v[50:53], v[240:243], v[236:239], v[50:53]
	v_mfma_f32_16x16x32_bf16 v[54:57], v[244:247], v[236:239], v[54:57]
	v_mfma_f32_16x16x32_bf16 v[58:61], v[248:251], v[236:239], v[58:61]
	v_mfma_f32_16x16x32_bf16 v[62:65], v[156:159], v[236:239], v[62:65]
	s_waitcnt lgkmcnt(3)
	v_mfma_f32_16x16x32_bf16 v[74:77], v[160:163], v[224:227], v[74:77]
	s_waitcnt lgkmcnt(2)
	v_mfma_f32_16x16x32_bf16 v[78:81], v[164:167], v[224:227], v[78:81]
	s_waitcnt lgkmcnt(1)
	v_mfma_f32_16x16x32_bf16 v[82:85], v[168:171], v[224:227], v[82:85]
	s_waitcnt lgkmcnt(0)
	v_mfma_f32_16x16x32_bf16 v[86:89], v[122:125], v[224:227], v[86:89]
	v_mfma_f32_16x16x32_bf16 v[90:93], v[160:163], v[228:231], v[90:93]
	v_mfma_f32_16x16x32_bf16 v[94:97], v[164:167], v[228:231], v[94:97]
	v_mfma_f32_16x16x32_bf16 v[98:101], v[168:171], v[228:231], v[98:101]
	v_mfma_f32_16x16x32_bf16 v[102:105], v[122:125], v[228:231], v[102:105]
	v_mfma_f32_16x16x32_bf16 v[106:109], v[160:163], v[232:235], v[106:109]
	v_mfma_f32_16x16x32_bf16 v[110:113], v[164:167], v[232:235], v[110:113]
	v_mfma_f32_16x16x32_bf16 v[114:117], v[168:171], v[232:235], v[114:117]
	v_mfma_f32_16x16x32_bf16 v[118:121], v[122:125], v[232:235], v[118:121]
	v_mfma_f32_16x16x32_bf16 v[208:211], v[160:163], v[236:239], v[208:211]
	v_mfma_f32_16x16x32_bf16 v[212:215], v[164:167], v[236:239], v[212:215]
	v_mfma_f32_16x16x32_bf16 v[216:219], v[168:171], v[236:239], v[216:219]
	v_mfma_f32_16x16x32_bf16 v[220:223], v[122:125], v[236:239], v[220:223]
	s_sub_u32 s46, s46, 1
	s_cmp_lg_u32 s46, 0
	s_cbranch_scc1 .Lout_kloop
	s_waitcnt vmcnt(6)
	s_barrier
	ds_read_b128 v[224:227], v126 offset:0
	ds_read_b128 v[240:243], v128 offset:0
	ds_read_b128 v[244:247], v128 offset:1024
	ds_read_b128 v[248:251], v128 offset:2048
	ds_read_b128 v[156:159], v128 offset:3072
	ds_read_b128 v[228:231], v126 offset:1024
	ds_read_b128 v[232:235], v126 offset:2048
	ds_read_b128 v[236:239], v126 offset:3072
	ds_read_b128 v[160:163], v128 offset:8192
	ds_read_b128 v[164:167], v128 offset:9216
	ds_read_b128 v[168:171], v128 offset:10240
	ds_read_b128 v[122:125], v128 offset:11264
	s_waitcnt lgkmcnt(10)
	v_mfma_f32_16x16x32_bf16 v[2:5], v[240:243], v[224:227], v[2:5]
	s_waitcnt lgkmcnt(9)
	v_mfma_f32_16x16x32_bf16 v[6:9], v[244:247], v[224:227], v[6:9]
	s_waitcnt lgkmcnt(8)
	v_mfma_f32_16x16x32_bf16 v[10:13], v[248:251], v[224:227], v[10:13]
	s_waitcnt lgkmcnt(7)
	v_mfma_f32_16x16x32_bf16 v[14:17], v[156:159], v[224:227], v[14:17]
	s_waitcnt lgkmcnt(6)
	v_mfma_f32_16x16x32_bf16 v[18:21], v[240:243], v[228:231], v[18:21]
	v_mfma_f32_16x16x32_bf16 v[22:25], v[244:247], v[228:231], v[22:25]
	v_mfma_f32_16x16x32_bf16 v[26:29], v[248:251], v[228:231], v[26:29]
	v_mfma_f32_16x16x32_bf16 v[30:33], v[156:159], v[228:231], v[30:33]
	s_waitcnt lgkmcnt(5)
	v_mfma_f32_16x16x32_bf16 v[34:37], v[240:243], v[232:235], v[34:37]
	v_mfma_f32_16x16x32_bf16 v[38:41], v[244:247], v[232:235], v[38:41]
	v_mfma_f32_16x16x32_bf16 v[42:45], v[248:251], v[232:235], v[42:45]
	v_mfma_f32_16x16x32_bf16 v[46:49], v[156:159], v[232:235], v[46:49]
	s_waitcnt lgkmcnt(4)
	v_mfma_f32_16x16x32_bf16 v[50:53], v[240:243], v[236:239], v[50:53]
	v_mfma_f32_16x16x32_bf16 v[54:57], v[244:247], v[236:239], v[54:57]
	v_mfma_f32_16x16x32_bf16 v[58:61], v[248:251], v[236:239], v[58:61]
	v_mfma_f32_16x16x32_bf16 v[62:65], v[156:159], v[236:239], v[62:65]
	s_waitcnt lgkmcnt(3)
	v_mfma_f32_16x16x32_bf16 v[74:77], v[160:163], v[224:227], v[74:77]
	s_waitcnt lgkmcnt(2)
	v_mfma_f32_16x16x32_bf16 v[78:81], v[164:167], v[224:227], v[78:81]
	s_waitcnt lgkmcnt(1)
	v_mfma_f32_16x16x32_bf16 v[82:85], v[168:171], v[224:227], v[82:85]
	s_waitcnt lgkmcnt(0)
	v_mfma_f32_16x16x32_bf16 v[86:89], v[122:125], v[224:227], v[86:89]
	v_mfma_f32_16x16x32_bf16 v[90:93], v[160:163], v[228:231], v[90:93]
	v_mfma_f32_16x16x32_bf16 v[94:97], v[164:167], v[228:231], v[94:97]
	v_mfma_f32_16x16x32_bf16 v[98:101], v[168:171], v[228:231], v[98:101]
	v_mfma_f32_16x16x32_bf16 v[102:105], v[122:125], v[228:231], v[102:105]
	v_mfma_f32_16x16x32_bf16 v[106:109], v[160:163], v[232:235], v[106:109]
	v_mfma_f32_16x16x32_bf16 v[110:113], v[164:167], v[232:235], v[110:113]
	v_mfma_f32_16x16x32_bf16 v[114:117], v[168:171], v[232:235], v[114:117]
	v_mfma_f32_16x16x32_bf16 v[118:121], v[122:125], v[232:235], v[118:121]
	v_mfma_f32_16x16x32_bf16 v[208:211], v[160:163], v[236:239], v[208:211]
	v_mfma_f32_16x16x32_bf16 v[212:215], v[164:167], v[236:239], v[212:215]
	v_mfma_f32_16x16x32_bf16 v[216:219], v[168:171], v[236:239], v[216:219]
	v_mfma_f32_16x16x32_bf16 v[220:223], v[122:125], v[236:239], v[220:223]
	s_waitcnt vmcnt(0)
	s_barrier
; #define BLOAD(A_, B_, kt) do { _Pragma("unroll") for (int i = 0; i < 4; ++i) { \
;     A_[i] = *(const u32x4*)((const char*)Ap + (aoff + (unsigned)(32 * i * lda + (kt) * 64) * 2u)); B_[i] = *(const u32x4*)((const char*)Wt + (woff + (unsigned)(32 * i * K + (kt) * 64) * 2u)); } } while (0)
; #define BLOAD(A_, B_, kt) do { _Pragma("unroll") for (int i = 0; i < 4; ++i) { \
;     A_[i] = *(const u32x4*)((const char*)Ap + (aoff + (unsigned)(32 * i * lda + (kt) * 64) * 2u)); B_[i] = *(const u32x4*)((const char*)Wt + (woff + (unsigned)(32 * i * K + (kt) * 64) * 2u)); } } while (0)
; #define BSTORE(A_, B_, buf) do { _Pragma("unroll") for (int i = 0; i < 4; ++i) { \
;     *(u32x4*)&As[(buf) * GBUF + (srow + 32 * i) * LDT + sc8] = A_[i]; \
;     *(u32x4*)&Bs[(buf) * GBUF + (srow + 32 * i) * LDT + sc8] = B_[i]; } } while (0)
; template <int NK>
; DI void gemm_run(PF& pf, const u16* __restrict__ Ap, int lda, const u16* __restrict__ Wt, f32x16 (&acc)[2][2], char* smem) {
;     ...
; #pragma unroll
;   for (int kt = 0; kt < nk; kt += 2) {
;     BCOMP(0);
;     BSTORE(pf.a1, pf.b1, 1);
;     if (kt + 3 < nk) BLOAD(pf.a1, pf.b1, kt + 3);
;     __syncthreads();
;     BCOMP(1);
;     if (kt + 2 < nk) { BSTORE(pf.a0, pf.b0, 0); if (kt + 4 < nk) BLOAD(pf.a0, pf.b0, kt + 4); }
;     __syncthreads();
;   }
; DI void tile_outproj(const Params& p, int l, const Chunk& ck, int tile, int next, PF& pf, char* smem) {
;     ...
;   const int row = tid >> 1, half = tid & 1; float ssq = 0.f;
;   u16* xb = (u16*)(p.ws + OFF_XB) + (size_t)(m0 + row) * 1024 + n0 + half * 64;
; #pragma unroll
;   for (int c8 = 0; c8 < 8; ++c8) {
;     float v[8], x[8]; cs_ld8(Cs, row, half * 64 + c8 * 8, v); unpack8(*(const u32x4*)(xb + c8 * 8), x);
	ds_read_b128 v[224:227], v126 offset:24576
	ds_read_b128 v[240:243], v128 offset:24576
	ds_read_b128 v[244:247], v128 offset:25600
	ds_read_b128 v[248:251], v128 offset:26624
	ds_read_b128 v[156:159], v128 offset:27648
	ds_read_b128 v[228:231], v126 offset:25600
	ds_read_b128 v[232:235], v126 offset:26624
	ds_read_b128 v[236:239], v126 offset:27648
	ds_read_b128 v[160:163], v128 offset:32768
	ds_read_b128 v[164:167], v128 offset:33792
	ds_read_b128 v[168:171], v128 offset:34816
	ds_read_b128 v[122:125], v128 offset:35840
	s_waitcnt lgkmcnt(10)
	v_mfma_f32_16x16x32_bf16 v[2:5], v[240:243], v[224:227], v[2:5]
	s_waitcnt lgkmcnt(9)
	v_mfma_f32_16x16x32_bf16 v[6:9], v[244:247], v[224:227], v[6:9]
	s_waitcnt lgkmcnt(8)
	v_mfma_f32_16x16x32_bf16 v[10:13], v[248:251], v[224:227], v[10:13]
	s_waitcnt lgkmcnt(7)
	v_mfma_f32_16x16x32_bf16 v[14:17], v[156:159], v[224:227], v[14:17]
	s_waitcnt lgkmcnt(6)
	v_mfma_f32_16x16x32_bf16 v[18:21], v[240:243], v[228:231], v[18:21]
	v_mfma_f32_16x16x32_bf16 v[22:25], v[244:247], v[228:231], v[22:25]
	v_mfma_f32_16x16x32_bf16 v[26:29], v[248:251], v[228:231], v[26:29]
	v_mfma_f32_16x16x32_bf16 v[30:33], v[156:159], v[228:231], v[30:33]
	s_waitcnt lgkmcnt(5)
	v_mfma_f32_16x16x32_bf16 v[34:37], v[240:243], v[232:235], v[34:37]
	v_mfma_f32_16x16x32_bf16 v[38:41], v[244:247], v[232:235], v[38:41]
	v_mfma_f32_16x16x32_bf16 v[42:45], v[248:251], v[232:235], v[42:45]
	v_mfma_f32_16x16x32_bf16 v[46:49], v[156:159], v[232:235], v[46:49]
	s_waitcnt lgkmcnt(4)
	v_mfma_f32_16x16x32_bf16 v[50:53], v[240:243], v[236:239], v[50:53]
	v_mfma_f32_16x16x32_bf16 v[54:57], v[244:247], v[236:239], v[54:57]
	v_mfma_f32_16x16x32_bf16 v[58:61], v[248:251], v[236:239], v[58:61]
	v_mfma_f32_16x16x32_bf16 v[62:65], v[156:159], v[236:239], v[62:65]
	s_waitcnt lgkmcnt(3)
	v_mfma_f32_16x16x32_bf16 v[74:77], v[160:163], v[224:227], v[74:77]
	s_waitcnt lgkmcnt(2)
	v_mfma_f32_16x16x32_bf16 v[78:81], v[164:167], v[224:227], v[78:81]
	s_waitcnt lgkmcnt(1)
	v_mfma_f32_16x16x32_bf16 v[82:85], v[168:171], v[224:227], v[82:85]
	s_waitcnt lgkmcnt(0)
	v_mfma_f32_16x16x32_bf16 v[86:89], v[122:125], v[224:227], v[86:89]
	v_mfma_f32_16x16x32_bf16 v[90:93], v[160:163], v[228:231], v[90:93]
	v_mfma_f32_16x16x32_bf16 v[94:97], v[164:167], v[228:231], v[94:97]
	v_mfma_f32_16x16x32_bf16 v[98:101], v[168:171], v[228:231], v[98:101]
	v_mfma_f32_16x16x32_bf16 v[102:105], v[122:125], v[228:231], v[102:105]
	v_mfma_f32_16x16x32_bf16 v[106:109], v[160:163], v[232:235], v[106:109]
	v_mfma_f32_16x16x32_bf16 v[110:113], v[164:167], v[232:235], v[110:113]
	v_mfma_f32_16x16x32_bf16 v[114:117], v[168:171], v[232:235], v[114:117]
	v_mfma_f32_16x16x32_bf16 v[118:121], v[122:125], v[232:235], v[118:121]
	v_mfma_f32_16x16x32_bf16 v[208:211], v[160:163], v[236:239], v[208:211]
	v_mfma_f32_16x16x32_bf16 v[212:215], v[164:167], v[236:239], v[212:215]
	v_mfma_f32_16x16x32_bf16 v[216:219], v[168:171], v[236:239], v[216:219]
	v_mfma_f32_16x16x32_bf16 v[220:223], v[122:125], v[236:239], v[220:223]
	s_barrier
	s_and_b32 s0, s40, 0x3f80
	v_and_b32_e32 v160, 63, v172
	v_lshrrev_b32_e32 v161, 6, v172
	v_and_b32_e32 v162, 15, v160
	v_lshrrev_b32_e32 v163, 4, v160
	v_lshrrev_b32_e32 v167, 1, v161
	v_lshl_add_u32 v167, v167, 6, v162
	v_and_b32_e32 v168, 1, v161
	v_lshlrev_b32_e32 v169, 6, v168
	v_lshl_add_u32 v169, v163, 2, v169
	v_add_u32_e32 v169, s26, v169
	v_add_u32_e32 v170, s0, v167
	v_lshlrev_b32_e32 v164, 6, v170
	v_lshl_add_u32 v164, v163, 3, v164
	v_lshrrev_b32_e32 v122, 5, v169
	v_lshl_add_u32 v164, v122, 20, v164
	v_add_u32_e32 v122, 0x100000, v164
	v_lshlrev_b32_e32 v165, 12, v167
	v_lshl_add_u32 v165, v169, 2, v165
	v_lshlrev_b32_e32 v166, 6, v170
	v_lshl_add_u32 v166, v168, 2, v166
	s_lshr_b32 s0, s26, 4
	s_add_u32 s14, s22, s0
	s_addc_u32 s15, s23, 0
	global_load_dwordx2 v[224:225], v164, s[20:21] offset:0
	global_load_dwordx2 v[226:227], v164, s[20:21] offset:32
	global_load_dwordx2 v[228:229], v122, s[20:21] offset:0
	global_load_dwordx2 v[230:231], v122, s[20:21] offset:32
	global_load_dwordx2 v[232:233], v164, s[20:21] offset:1024
	global_load_dwordx2 v[234:235], v164, s[20:21] offset:1056
	global_load_dwordx2 v[236:237], v122, s[20:21] offset:1024
	global_load_dwordx2 v[238:239], v122, s[20:21] offset:1056
	global_load_dwordx2 v[240:241], v164, s[20:21] offset:2048
	global_load_dwordx2 v[242:243], v164, s[20:21] offset:2080
	global_load_dwordx2 v[244:245], v122, s[20:21] offset:2048
	global_load_dwordx2 v[246:247], v122, s[20:21] offset:2080
	global_load_dwordx2 v[248:249], v164, s[20:21] offset:3072
	global_load_dwordx2 v[250:251], v164, s[20:21] offset:3104
	global_load_dwordx2 v[156:157], v122, s[20:21] offset:3072
	global_load_dwordx2 v[158:159], v122, s[20:21] offset:3104
	s_waitcnt vmcnt(0)
; DI u32x4 pack8(const float (&v)[8]) { u32x4 r = {pk2(v[0], v[1]), pk2(v[2], v[3]), pk2(v[4], v[5]), pk2(v[6], v[7])}; return r; }
; DI void tile_outproj(const Params& p, int l, const Chunk& ck, int tile, int next, PF& pf, char* smem) {
;     ...
;   const int row = tid >> 1, half = tid & 1; float ssq = 0.f;
;   u16* xb = (u16*)(p.ws + OFF_XB) + (size_t)(m0 + row) * 1024 + n0 + half * 64;
; #pragma unroll
;   for (int c8 = 0; c8 < 8; ++c8) {
;     float v[8], x[8]; cs_ld8(Cs, row, half * 64 + c8 * 8, v); unpack8(*(const u32x4*)(xb + c8 * 8), x);
; #pragma unroll
;     for (int j = 0; j < 8; ++j) { v[j] += x[j]; ssq += v[j] * v[j]; }
;     *(u32x4*)(xb + c8 * 8) = pack8(v);
;   }
;   ((float*)(p.ws + OFF_PSMID))[(size_t)(m0 + row) * 16 + ni * 2 + half] = ssq;
	v_mov_b32_e32 v171, 0
	v_lshlrev_b32_e32 v167, 16, v224
	v_and_b32_e32 v168, 0xffff0000, v224
	v_lshlrev_b32_e32 v169, 16, v225
	v_and_b32_e32 v170, 0xffff0000, v225
	v_add_f32_e32 v2, v2, v167
	v_add_f32_e32 v3, v3, v168
	v_add_f32_e32 v4, v4, v169
	v_add_f32_e32 v5, v5, v170
	v_fma_f32 v171, v2, v2, v171
	v_fma_f32 v171, v3, v3, v171
	v_fma_f32 v171, v4, v4, v171
	v_fma_f32 v171, v5, v5, v171
	v_cvt_pk_bf16_f32 v2, v2, v3
	v_cvt_pk_bf16_f32 v3, v4, v5
	global_store_dwordx2 v164, v[2:3], s[20:21]
	v_lshlrev_b32_e32 v167, 16, v226
	v_and_b32_e32 v168, 0xffff0000, v226
	v_lshlrev_b32_e32 v169, 16, v227
	v_and_b32_e32 v170, 0xffff0000, v227
	v_add_f32_e32 v6, v6, v167
	v_add_f32_e32 v7, v7, v168
	v_add_f32_e32 v8, v8, v169
	v_add_f32_e32 v9, v9, v170
	v_fma_f32 v171, v6, v6, v171
	v_fma_f32 v171, v7, v7, v171
	v_fma_f32 v171, v8, v8, v171
	v_fma_f32 v171, v9, v9, v171
	v_cvt_pk_bf16_f32 v6, v6, v7
	v_cvt_pk_bf16_f32 v7, v8, v9
	global_store_dwordx2 v164, v[6:7], s[20:21] offset:32
	v_lshlrev_b32_e32 v167, 16, v228
	v_and_b32_e32 v168, 0xffff0000, v228
	v_lshlrev_b32_e32 v169, 16, v229
	v_and_b32_e32 v170, 0xffff0000, v229
	v_add_f32_e32 v10, v10, v167
	v_add_f32_e32 v11, v11, v168
	v_add_f32_e32 v12, v12, v169
	v_add_f32_e32 v13, v13, v170
	v_fma_f32 v171, v10, v10, v171
	v_fma_f32 v171, v11, v11, v171
	v_fma_f32 v171, v12, v12, v171
	v_fma_f32 v171, v13, v13, v171
	v_cvt_pk_bf16_f32 v10, v10, v11
	v_cvt_pk_bf16_f32 v11, v12, v13
	global_store_dwordx2 v122, v[10:11], s[20:21]
	v_lshlrev_b32_e32 v167, 16, v230
	v_and_b32_e32 v168, 0xffff0000, v230
	v_lshlrev_b32_e32 v169, 16, v231
	v_and_b32_e32 v170, 0xffff0000, v231
	v_add_f32_e32 v14, v14, v167
	v_add_f32_e32 v15, v15, v168
	v_add_f32_e32 v16, v16, v169
	v_add_f32_e32 v17, v17, v170
	v_fma_f32 v171, v14, v14, v171
	v_fma_f32 v171, v15, v15, v171
	v_fma_f32 v171, v16, v16, v171
	v_fma_f32 v171, v17, v17, v171
	v_cvt_pk_bf16_f32 v14, v14, v15
	v_cvt_pk_bf16_f32 v15, v16, v17
	global_store_dwordx2 v122, v[14:15], s[20:21] offset:32
	v_mov_b32_e32 v167, v171
	s_nop 1
	v_permlane32_swap_b32_e32 v171, v167
	v_add_f32_e32 v171, v171, v167
	ds_swizzle_b32 v167, v171 offset:0x401f
	s_waitcnt lgkmcnt(0)
	v_add_f32_e32 v171, v171, v167
	v_cmp_gt_u32_e32 vcc, 16, v160
	s_and_saveexec_b64 s[98:99], vcc
	global_store_dword v166, v171, s[14:15] offset:0
	s_or_b64 exec, exec, s[98:99]
	v_mov_b32_e32 v171, 0
	v_lshlrev_b32_e32 v167, 16, v232
	v_and_b32_e32 v168, 0xffff0000, v232
	v_lshlrev_b32_e32 v169, 16, v233
	v_and_b32_e32 v170, 0xffff0000, v233
	v_add_f32_e32 v18, v18, v167
	v_add_f32_e32 v19, v19, v168
	v_add_f32_e32 v20, v20, v169
	v_add_f32_e32 v21, v21, v170
	v_fma_f32 v171, v18, v18, v171
	v_fma_f32 v171, v19, v19, v171
	v_fma_f32 v171, v20, v20, v171
	v_fma_f32 v171, v21, v21, v171
	v_cvt_pk_bf16_f32 v18, v18, v19
	v_cvt_pk_bf16_f32 v19, v20, v21
	global_store_dwordx2 v164, v[18:19], s[20:21] offset:1024
	v_lshlrev_b32_e32 v167, 16, v234
	v_and_b32_e32 v168, 0xffff0000, v234
	v_lshlrev_b32_e32 v169, 16, v235
	v_and_b32_e32 v170, 0xffff0000, v235
	v_add_f32_e32 v22, v22, v167
	v_add_f32_e32 v23, v23, v168
	v_add_f32_e32 v24, v24, v169
	v_add_f32_e32 v25, v25, v170
	v_fma_f32 v171, v22, v22, v171
	v_fma_f32 v171, v23, v23, v171
	v_fma_f32 v171, v24, v24, v171
	v_fma_f32 v171, v25, v25, v171
	v_cvt_pk_bf16_f32 v22, v22, v23
	v_cvt_pk_bf16_f32 v23, v24, v25
	global_store_dwordx2 v164, v[22:23], s[20:21] offset:1056
	v_lshlrev_b32_e32 v167, 16, v236
	v_and_b32_e32 v168, 0xffff0000, v236
	v_lshlrev_b32_e32 v169, 16, v237
	v_and_b32_e32 v170, 0xffff0000, v237
	v_add_f32_e32 v26, v26, v167
	v_add_f32_e32 v27, v27, v168
	v_add_f32_e32 v28, v28, v169
	v_add_f32_e32 v29, v29, v170
	v_fma_f32 v171, v26, v26, v171
	v_fma_f32 v171, v27, v27, v171
	v_fma_f32 v171, v28, v28, v171
	v_fma_f32 v171, v29, v29, v171
	v_cvt_pk_bf16_f32 v26, v26, v27
	v_cvt_pk_bf16_f32 v27, v28, v29
	global_store_dwordx2 v122, v[26:27], s[20:21] offset:1024
	v_lshlrev_b32_e32 v167, 16, v238
	v_and_b32_e32 v168, 0xffff0000, v238
	v_lshlrev_b32_e32 v169, 16, v239
	v_and_b32_e32 v170, 0xffff0000, v239
	v_add_f32_e32 v30, v30, v167
	v_add_f32_e32 v31, v31, v168
	v_add_f32_e32 v32, v32, v169
	v_add_f32_e32 v33, v33, v170
	v_fma_f32 v171, v30, v30, v171
	v_fma_f32 v171, v31, v31, v171
	v_fma_f32 v171, v32, v32, v171
	v_fma_f32 v171, v33, v33, v171
	v_cvt_pk_bf16_f32 v30, v30, v31
	v_cvt_pk_bf16_f32 v31, v32, v33
	global_store_dwordx2 v122, v[30:31], s[20:21] offset:1056
	v_mov_b32_e32 v167, v171
	s_nop 1
	v_permlane32_swap_b32_e32 v171, v167
	v_add_f32_e32 v171, v171, v167
	ds_swizzle_b32 v167, v171 offset:0x401f
	s_waitcnt lgkmcnt(0)
; DI u32x4 pack8(const float (&v)[8]) { u32x4 r = {pk2(v[0], v[1]), pk2(v[2], v[3]), pk2(v[4], v[5]), pk2(v[6], v[7])}; return r; }
; DI void tile_outproj(const Params& p, int l, const Chunk& ck, int tile, int next, PF& pf, char* smem) {
;     ...
;   const int row = tid >> 1, half = tid & 1; float ssq = 0.f;
;   u16* xb = (u16*)(p.ws + OFF_XB) + (size_t)(m0 + row) * 1024 + n0 + half * 64;
; #pragma unroll
;   for (int c8 = 0; c8 < 8; ++c8) {
;     float v[8], x[8]; cs_ld8(Cs, row, half * 64 + c8 * 8, v); unpack8(*(const u32x4*)(xb + c8 * 8), x);
; #pragma unroll
;     for (int j = 0; j < 8; ++j) { v[j] += x[j]; ssq += v[j] * v[j]; }
;     *(u32x4*)(xb + c8 * 8) = pack8(v);
;   }
;   ((float*)(p.ws + OFF_PSMID))[(size_t)(m0 + row) * 16 + ni * 2 + half] = ssq;
	v_add_f32_e32 v171, v171, v167
	v_cmp_gt_u32_e32 vcc, 16, v160
	s_and_saveexec_b64 s[98:99], vcc
	global_store_dword v166, v171, s[14:15] offset:1024
	s_or_b64 exec, exec, s[98:99]
	v_mov_b32_e32 v171, 0
	v_lshlrev_b32_e32 v167, 16, v240
	v_and_b32_e32 v168, 0xffff0000, v240
	v_lshlrev_b32_e32 v169, 16, v241
	v_and_b32_e32 v170, 0xffff0000, v241
	v_add_f32_e32 v34, v34, v167
	v_add_f32_e32 v35, v35, v168
	v_add_f32_e32 v36, v36, v169
	v_add_f32_e32 v37, v37, v170
	v_fma_f32 v171, v34, v34, v171
	v_fma_f32 v171, v35, v35, v171
	v_fma_f32 v171, v36, v36, v171
	v_fma_f32 v171, v37, v37, v171
	v_cvt_pk_bf16_f32 v34, v34, v35
	v_cvt_pk_bf16_f32 v35, v36, v37
	global_store_dwordx2 v164, v[34:35], s[20:21] offset:2048
	v_lshlrev_b32_e32 v167, 16, v242
	v_and_b32_e32 v168, 0xffff0000, v242
	v_lshlrev_b32_e32 v169, 16, v243
	v_and_b32_e32 v170, 0xffff0000, v243
	v_add_f32_e32 v38, v38, v167
	v_add_f32_e32 v39, v39, v168
	v_add_f32_e32 v40, v40, v169
	v_add_f32_e32 v41, v41, v170
	v_fma_f32 v171, v38, v38, v171
	v_fma_f32 v171, v39, v39, v171
	v_fma_f32 v171, v40, v40, v171
	v_fma_f32 v171, v41, v41, v171
	v_cvt_pk_bf16_f32 v38, v38, v39
	v_cvt_pk_bf16_f32 v39, v40, v41
	global_store_dwordx2 v164, v[38:39], s[20:21] offset:2080
	v_lshlrev_b32_e32 v167, 16, v244
	v_and_b32_e32 v168, 0xffff0000, v244
	v_lshlrev_b32_e32 v169, 16, v245
	v_and_b32_e32 v170, 0xffff0000, v245
	v_add_f32_e32 v42, v42, v167
	v_add_f32_e32 v43, v43, v168
	v_add_f32_e32 v44, v44, v169
	v_add_f32_e32 v45, v45, v170
	v_fma_f32 v171, v42, v42, v171
	v_fma_f32 v171, v43, v43, v171
	v_fma_f32 v171, v44, v44, v171
	v_fma_f32 v171, v45, v45, v171
	v_cvt_pk_bf16_f32 v42, v42, v43
	v_cvt_pk_bf16_f32 v43, v44, v45
	global_store_dwordx2 v122, v[42:43], s[20:21] offset:2048
	v_lshlrev_b32_e32 v167, 16, v246
	v_and_b32_e32 v168, 0xffff0000, v246
	v_lshlrev_b32_e32 v169, 16, v247
	v_and_b32_e32 v170, 0xffff0000, v247
	v_add_f32_e32 v46, v46, v167
	v_add_f32_e32 v47, v47, v168
	v_add_f32_e32 v48, v48, v169
	v_add_f32_e32 v49, v49, v170
	v_fma_f32 v171, v46, v46, v171
	v_fma_f32 v171, v47, v47, v171
	v_fma_f32 v171, v48, v48, v171
	v_fma_f32 v171, v49, v49, v171
	v_cvt_pk_bf16_f32 v46, v46, v47
	v_cvt_pk_bf16_f32 v47, v48, v49
	global_store_dwordx2 v122, v[46:47], s[20:21] offset:2080
	v_mov_b32_e32 v167, v171
	s_nop 1
	v_permlane32_swap_b32_e32 v171, v167
	v_add_f32_e32 v171, v171, v167
	ds_swizzle_b32 v167, v171 offset:0x401f
	s_waitcnt lgkmcnt(0)
	v_add_f32_e32 v171, v171, v167
	v_cmp_gt_u32_e32 vcc, 16, v160
	s_and_saveexec_b64 s[98:99], vcc
	global_store_dword v166, v171, s[14:15] offset:2048
	s_or_b64 exec, exec, s[98:99]
	v_mov_b32_e32 v171, 0
	v_lshlrev_b32_e32 v167, 16, v248
	v_and_b32_e32 v168, 0xffff0000, v248
	v_lshlrev_b32_e32 v169, 16, v249
	v_and_b32_e32 v170, 0xffff0000, v249
	v_add_f32_e32 v50, v50, v167
	v_add_f32_e32 v51, v51, v168
	v_add_f32_e32 v52, v52, v169
	v_add_f32_e32 v53, v53, v170
	v_fma_f32 v171, v50, v50, v171
	v_fma_f32 v171, v51, v51, v171
	v_fma_f32 v171, v52, v52, v171
	v_fma_f32 v171, v53, v53, v171
	v_cvt_pk_bf16_f32 v50, v50, v51
	v_cvt_pk_bf16_f32 v51, v52, v53
	global_store_dwordx2 v164, v[50:51], s[20:21] offset:3072
	v_lshlrev_b32_e32 v167, 16, v250
	v_and_b32_e32 v168, 0xffff0000, v250
	v_lshlrev_b32_e32 v169, 16, v251
	v_and_b32_e32 v170, 0xffff0000, v251
	v_add_f32_e32 v54, v54, v167
	v_add_f32_e32 v55, v55, v168
	v_add_f32_e32 v56, v56, v169
	v_add_f32_e32 v57, v57, v170
	v_fma_f32 v171, v54, v54, v171
	v_fma_f32 v171, v55, v55, v171
	v_fma_f32 v171, v56, v56, v171
	v_fma_f32 v171, v57, v57, v171
	v_cvt_pk_bf16_f32 v54, v54, v55
	v_cvt_pk_bf16_f32 v55, v56, v57
	global_store_dwordx2 v164, v[54:55], s[20:21] offset:3104
	v_lshlrev_b32_e32 v167, 16, v156
	v_and_b32_e32 v168, 0xffff0000, v156
	v_lshlrev_b32_e32 v169, 16, v157
	v_and_b32_e32 v170, 0xffff0000, v157
	v_add_f32_e32 v58, v58, v167
	v_add_f32_e32 v59, v59, v168
	v_add_f32_e32 v60, v60, v169
	v_add_f32_e32 v61, v61, v170
	v_fma_f32 v171, v58, v58, v171
	v_fma_f32 v171, v59, v59, v171
	v_fma_f32 v171, v60, v60, v171
	v_fma_f32 v171, v61, v61, v171
	v_cvt_pk_bf16_f32 v58, v58, v59
	v_cvt_pk_bf16_f32 v59, v60, v61
	global_store_dwordx2 v122, v[58:59], s[20:21] offset:3072
	v_lshlrev_b32_e32 v167, 16, v158
	v_and_b32_e32 v168, 0xffff0000, v158
	v_lshlrev_b32_e32 v169, 16, v159
	v_and_b32_e32 v170, 0xffff0000, v159
	v_add_f32_e32 v62, v62, v167
	v_add_f32_e32 v63, v63, v168
	v_add_f32_e32 v64, v64, v169
	v_add_f32_e32 v65, v65, v170
	v_fma_f32 v171, v62, v62, v171
	v_fma_f32 v171, v63, v63, v171
	v_fma_f32 v171, v64, v64, v171
	v_fma_f32 v171, v65, v65, v171
	v_cvt_pk_bf16_f32 v62, v62, v63
	v_cvt_pk_bf16_f32 v63, v64, v65
	global_store_dwordx2 v122, v[62:63], s[20:21] offset:3104
	v_mov_b32_e32 v167, v171
	s_nop 1
	v_permlane32_swap_b32_e32 v171, v167
	v_add_f32_e32 v171, v171, v167
	ds_swizzle_b32 v167, v171 offset:0x401f
	s_waitcnt lgkmcnt(0)
	v_add_f32_e32 v171, v171, v167
	v_cmp_gt_u32_e32 vcc, 16, v160
	s_and_saveexec_b64 s[98:99], vcc
	global_store_dword v166, v171, s[14:15] offset:3072
	s_or_b64 exec, exec, s[98:99]
	v_add_u32_e32 v164, 0x400000, v164
	v_add_u32_e32 v122, 0x400000, v122
	global_load_dwordx2 v[224:225], v164, s[20:21] offset:0
	global_load_dwordx2 v[226:227], v164, s[20:21] offset:32
	global_load_dwordx2 v[228:229], v122, s[20:21] offset:0
	global_load_dwordx2 v[230:231], v122, s[20:21] offset:32
	global_load_dwordx2 v[232:233], v164, s[20:21] offset:1024
	global_load_dwordx2 v[234:235], v164, s[20:21] offset:1056
	global_load_dwordx2 v[236:237], v122, s[20:21] offset:1024
	global_load_dwordx2 v[238:239], v122, s[20:21] offset:1056
	global_load_dwordx2 v[240:241], v164, s[20:21] offset:2048
	global_load_dwordx2 v[242:243], v164, s[20:21] offset:2080
	global_load_dwordx2 v[244:245], v122, s[20:21] offset:2048
	global_load_dwordx2 v[246:247], v122, s[20:21] offset:2080
	global_load_dwordx2 v[248:249], v164, s[20:21] offset:3072
	global_load_dwordx2 v[250:251], v164, s[20:21] offset:3104
	global_load_dwordx2 v[156:157], v122, s[20:21] offset:3072
	global_load_dwordx2 v[158:159], v122, s[20:21] offset:3104
	s_waitcnt vmcnt(0)
; DI u32x4 pack8(const float (&v)[8]) { u32x4 r = {pk2(v[0], v[1]), pk2(v[2], v[3]), pk2(v[4], v[5]), pk2(v[6], v[7])}; return r; }
; DI void tile_outproj(const Params& p, int l, const Chunk& ck, int tile, int next, PF& pf, char* smem) {
;     ...
;   const int row = tid >> 1, half = tid & 1; float ssq = 0.f;
;   u16* xb = (u16*)(p.ws + OFF_XB) + (size_t)(m0 + row) * 1024 + n0 + half * 64;
; #pragma unroll
;   for (int c8 = 0; c8 < 8; ++c8) {
;     float v[8], x[8]; cs_ld8(Cs, row, half * 64 + c8 * 8, v); unpack8(*(const u32x4*)(xb + c8 * 8), x);
; #pragma unroll
;     for (int j = 0; j < 8; ++j) { v[j] += x[j]; ssq += v[j] * v[j]; }
;     *(u32x4*)(xb + c8 * 8) = pack8(v);
;   }
;   ((float*)(p.ws + OFF_PSMID))[(size_t)(m0 + row) * 16 + ni * 2 + half] = ssq;
	v_mov_b32_e32 v171, 0
	v_lshlrev_b32_e32 v167, 16, v224
	v_and_b32_e32 v168, 0xffff0000, v224
	v_lshlrev_b32_e32 v169, 16, v225
	v_and_b32_e32 v170, 0xffff0000, v225
	v_add_f32_e32 v74, v74, v167
	v_add_f32_e32 v75, v75, v168
	v_add_f32_e32 v76, v76, v169
	v_add_f32_e32 v77, v77, v170
	v_fma_f32 v171, v74, v74, v171
	v_fma_f32 v171, v75, v75, v171
	v_fma_f32 v171, v76, v76, v171
	v_fma_f32 v171, v77, v77, v171
	v_cvt_pk_bf16_f32 v74, v74, v75
	v_cvt_pk_bf16_f32 v75, v76, v77
	global_store_dwordx2 v164, v[74:75], s[20:21]
	v_lshlrev_b32_e32 v167, 16, v226
	v_and_b32_e32 v168, 0xffff0000, v226
	v_lshlrev_b32_e32 v169, 16, v227
	v_and_b32_e32 v170, 0xffff0000, v227
	v_add_f32_e32 v78, v78, v167
	v_add_f32_e32 v79, v79, v168
	v_add_f32_e32 v80, v80, v169
	v_add_f32_e32 v81, v81, v170
	v_fma_f32 v171, v78, v78, v171
	v_fma_f32 v171, v79, v79, v171
	v_fma_f32 v171, v80, v80, v171
	v_fma_f32 v171, v81, v81, v171
	v_cvt_pk_bf16_f32 v78, v78, v79
	v_cvt_pk_bf16_f32 v79, v80, v81
	global_store_dwordx2 v164, v[78:79], s[20:21] offset:32
	v_lshlrev_b32_e32 v167, 16, v228
	v_and_b32_e32 v168, 0xffff0000, v228
	v_lshlrev_b32_e32 v169, 16, v229
	v_and_b32_e32 v170, 0xffff0000, v229
	v_add_f32_e32 v82, v82, v167
	v_add_f32_e32 v83, v83, v168
	v_add_f32_e32 v84, v84, v169
	v_add_f32_e32 v85, v85, v170
	v_fma_f32 v171, v82, v82, v171
	v_fma_f32 v171, v83, v83, v171
	v_fma_f32 v171, v84, v84, v171
	v_fma_f32 v171, v85, v85, v171
	v_cvt_pk_bf16_f32 v82, v82, v83
	v_cvt_pk_bf16_f32 v83, v84, v85
	global_store_dwordx2 v122, v[82:83], s[20:21]
	v_lshlrev_b32_e32 v167, 16, v230
	v_and_b32_e32 v168, 0xffff0000, v230
	v_lshlrev_b32_e32 v169, 16, v231
	v_and_b32_e32 v170, 0xffff0000, v231
	v_add_f32_e32 v86, v86, v167
	v_add_f32_e32 v87, v87, v168
	v_add_f32_e32 v88, v88, v169
	v_add_f32_e32 v89, v89, v170
	v_fma_f32 v171, v86, v86, v171
	v_fma_f32 v171, v87, v87, v171
	v_fma_f32 v171, v88, v88, v171
	v_fma_f32 v171, v89, v89, v171
	v_cvt_pk_bf16_f32 v86, v86, v87
	v_cvt_pk_bf16_f32 v87, v88, v89
	global_store_dwordx2 v122, v[86:87], s[20:21] offset:32
	v_mov_b32_e32 v167, v171
	s_nop 1
	v_permlane32_swap_b32_e32 v171, v167
	v_add_f32_e32 v171, v171, v167
	ds_swizzle_b32 v167, v171 offset:0x401f
	s_waitcnt lgkmcnt(0)
	v_add_f32_e32 v171, v171, v167
	v_cmp_gt_u32_e32 vcc, 16, v160
	s_and_saveexec_b64 s[98:99], vcc
	global_store_dword v166, v171, s[14:15] offset:8
	s_or_b64 exec, exec, s[98:99]
	v_mov_b32_e32 v171, 0
	v_lshlrev_b32_e32 v167, 16, v232
	v_and_b32_e32 v168, 0xffff0000, v232
	v_lshlrev_b32_e32 v169, 16, v233
	v_and_b32_e32 v170, 0xffff0000, v233
	v_add_f32_e32 v90, v90, v167
	v_add_f32_e32 v91, v91, v168
	v_add_f32_e32 v92, v92, v169
	v_add_f32_e32 v93, v93, v170
	v_fma_f32 v171, v90, v90, v171
	v_fma_f32 v171, v91, v91, v171
	v_fma_f32 v171, v92, v92, v171
	v_fma_f32 v171, v93, v93, v171
	v_cvt_pk_bf16_f32 v90, v90, v91
	v_cvt_pk_bf16_f32 v91, v92, v93
	global_store_dwordx2 v164, v[90:91], s[20:21] offset:1024
	v_lshlrev_b32_e32 v167, 16, v234
	v_and_b32_e32 v168, 0xffff0000, v234
	v_lshlrev_b32_e32 v169, 16, v235
	v_and_b32_e32 v170, 0xffff0000, v235
	v_add_f32_e32 v94, v94, v167
	v_add_f32_e32 v95, v95, v168
	v_add_f32_e32 v96, v96, v169
	v_add_f32_e32 v97, v97, v170
	v_fma_f32 v171, v94, v94, v171
	v_fma_f32 v171, v95, v95, v171
	v_fma_f32 v171, v96, v96, v171
	v_fma_f32 v171, v97, v97, v171
	v_cvt_pk_bf16_f32 v94, v94, v95
	v_cvt_pk_bf16_f32 v95, v96, v97
	global_store_dwordx2 v164, v[94:95], s[20:21] offset:1056
	v_lshlrev_b32_e32 v167, 16, v236
	v_and_b32_e32 v168, 0xffff0000, v236
	v_lshlrev_b32_e32 v169, 16, v237
	v_and_b32_e32 v170, 0xffff0000, v237
	v_add_f32_e32 v98, v98, v167
	v_add_f32_e32 v99, v99, v168
	v_add_f32_e32 v100, v100, v169
	v_add_f32_e32 v101, v101, v170
	v_fma_f32 v171, v98, v98, v171
	v_fma_f32 v171, v99, v99, v171
	v_fma_f32 v171, v100, v100, v171
	v_fma_f32 v171, v101, v101, v171
	v_cvt_pk_bf16_f32 v98, v98, v99
	v_cvt_pk_bf16_f32 v99, v100, v101
	global_store_dwordx2 v122, v[98:99], s[20:21] offset:1024
	v_lshlrev_b32_e32 v167, 16, v238
	v_and_b32_e32 v168, 0xffff0000, v238
	v_lshlrev_b32_e32 v169, 16, v239
	v_and_b32_e32 v170, 0xffff0000, v239
	v_add_f32_e32 v102, v102, v167
	v_add_f32_e32 v103, v103, v168
	v_add_f32_e32 v104, v104, v169
	v_add_f32_e32 v105, v105, v170
	v_fma_f32 v171, v102, v102, v171
	v_fma_f32 v171, v103, v103, v171
	v_fma_f32 v171, v104, v104, v171
	v_fma_f32 v171, v105, v105, v171
	v_cvt_pk_bf16_f32 v102, v102, v103
	v_cvt_pk_bf16_f32 v103, v104, v105
	global_store_dwordx2 v122, v[102:103], s[20:21] offset:1056
	v_mov_b32_e32 v167, v171
	s_nop 1
	v_permlane32_swap_b32_e32 v171, v167
	v_add_f32_e32 v171, v171, v167
	ds_swizzle_b32 v167, v171 offset:0x401f
	s_waitcnt lgkmcnt(0)
; DI u32x4 pack8(const float (&v)[8]) { u32x4 r = {pk2(v[0], v[1]), pk2(v[2], v[3]), pk2(v[4], v[5]), pk2(v[6], v[7])}; return r; }
; DI void tile_outproj(const Params& p, int l, const Chunk& ck, int tile, int next, PF& pf, char* smem) {
;     ...
;   const int row = tid >> 1, half = tid & 1; float ssq = 0.f;
;   u16* xb = (u16*)(p.ws + OFF_XB) + (size_t)(m0 + row) * 1024 + n0 + half * 64;
; #pragma unroll
;   for (int c8 = 0; c8 < 8; ++c8) {
;     float v[8], x[8]; cs_ld8(Cs, row, half * 64 + c8 * 8, v); unpack8(*(const u32x4*)(xb + c8 * 8), x);
; #pragma unroll
;     for (int j = 0; j < 8; ++j) { v[j] += x[j]; ssq += v[j] * v[j]; }
;     *(u32x4*)(xb + c8 * 8) = pack8(v);
;   }
;   ((float*)(p.ws + OFF_PSMID))[(size_t)(m0 + row) * 16 + ni * 2 + half] = ssq;
	v_add_f32_e32 v171, v171, v167
	v_cmp_gt_u32_e32 vcc, 16, v160
	s_and_saveexec_b64 s[98:99], vcc
	global_store_dword v166, v171, s[14:15] offset:1032
	s_or_b64 exec, exec, s[98:99]
	v_mov_b32_e32 v171, 0
	v_lshlrev_b32_e32 v167, 16, v240
	v_and_b32_e32 v168, 0xffff0000, v240
	v_lshlrev_b32_e32 v169, 16, v241
	v_and_b32_e32 v170, 0xffff0000, v241
	v_add_f32_e32 v106, v106, v167
	v_add_f32_e32 v107, v107, v168
	v_add_f32_e32 v108, v108, v169
	v_add_f32_e32 v109, v109, v170
	v_fma_f32 v171, v106, v106, v171
	v_fma_f32 v171, v107, v107, v171
	v_fma_f32 v171, v108, v108, v171
	v_fma_f32 v171, v109, v109, v171
	v_cvt_pk_bf16_f32 v106, v106, v107
	v_cvt_pk_bf16_f32 v107, v108, v109
	global_store_dwordx2 v164, v[106:107], s[20:21] offset:2048
	v_lshlrev_b32_e32 v167, 16, v242
	v_and_b32_e32 v168, 0xffff0000, v242
	v_lshlrev_b32_e32 v169, 16, v243
	v_and_b32_e32 v170, 0xffff0000, v243
	v_add_f32_e32 v110, v110, v167
	v_add_f32_e32 v111, v111, v168
	v_add_f32_e32 v112, v112, v169
	v_add_f32_e32 v113, v113, v170
	v_fma_f32 v171, v110, v110, v171
	v_fma_f32 v171, v111, v111, v171
	v_fma_f32 v171, v112, v112, v171
	v_fma_f32 v171, v113, v113, v171
	v_cvt_pk_bf16_f32 v110, v110, v111
	v_cvt_pk_bf16_f32 v111, v112, v113
	global_store_dwordx2 v164, v[110:111], s[20:21] offset:2080
	v_lshlrev_b32_e32 v167, 16, v244
	v_and_b32_e32 v168, 0xffff0000, v244
	v_lshlrev_b32_e32 v169, 16, v245
	v_and_b32_e32 v170, 0xffff0000, v245
	v_add_f32_e32 v114, v114, v167
	v_add_f32_e32 v115, v115, v168
	v_add_f32_e32 v116, v116, v169
	v_add_f32_e32 v117, v117, v170
	v_fma_f32 v171, v114, v114, v171
	v_fma_f32 v171, v115, v115, v171
	v_fma_f32 v171, v116, v116, v171
	v_fma_f32 v171, v117, v117, v171
	v_cvt_pk_bf16_f32 v114, v114, v115
	v_cvt_pk_bf16_f32 v115, v116, v117
	global_store_dwordx2 v122, v[114:115], s[20:21] offset:2048
	v_lshlrev_b32_e32 v167, 16, v246
	v_and_b32_e32 v168, 0xffff0000, v246
	v_lshlrev_b32_e32 v169, 16, v247
	v_and_b32_e32 v170, 0xffff0000, v247
	v_add_f32_e32 v118, v118, v167
	v_add_f32_e32 v119, v119, v168
	v_add_f32_e32 v120, v120, v169
	v_add_f32_e32 v121, v121, v170
	v_fma_f32 v171, v118, v118, v171
	v_fma_f32 v171, v119, v119, v171
	v_fma_f32 v171, v120, v120, v171
	v_fma_f32 v171, v121, v121, v171
	v_cvt_pk_bf16_f32 v118, v118, v119
	v_cvt_pk_bf16_f32 v119, v120, v121
	global_store_dwordx2 v122, v[118:119], s[20:21] offset:2080
	v_mov_b32_e32 v167, v171
	s_nop 1
	v_permlane32_swap_b32_e32 v171, v167
	v_add_f32_e32 v171, v171, v167
	ds_swizzle_b32 v167, v171 offset:0x401f
	s_waitcnt lgkmcnt(0)
	v_add_f32_e32 v171, v171, v167
	v_cmp_gt_u32_e32 vcc, 16, v160
	s_and_saveexec_b64 s[98:99], vcc
	global_store_dword v166, v171, s[14:15] offset:2056
	s_or_b64 exec, exec, s[98:99]
	v_mov_b32_e32 v171, 0
	v_lshlrev_b32_e32 v167, 16, v248
	v_and_b32_e32 v168, 0xffff0000, v248
	v_lshlrev_b32_e32 v169, 16, v249
	v_and_b32_e32 v170, 0xffff0000, v249
	v_add_f32_e32 v208, v208, v167
	v_add_f32_e32 v209, v209, v168
	v_add_f32_e32 v210, v210, v169
	v_add_f32_e32 v211, v211, v170
	v_fma_f32 v171, v208, v208, v171
	v_fma_f32 v171, v209, v209, v171
	v_fma_f32 v171, v210, v210, v171
	v_fma_f32 v171, v211, v211, v171
	v_cvt_pk_bf16_f32 v208, v208, v209
	v_cvt_pk_bf16_f32 v209, v210, v211
	global_store_dwordx2 v164, v[208:209], s[20:21] offset:3072
	v_lshlrev_b32_e32 v167, 16, v250
	v_and_b32_e32 v168, 0xffff0000, v250
	v_lshlrev_b32_e32 v169, 16, v251
	v_and_b32_e32 v170, 0xffff0000, v251
	v_add_f32_e32 v212, v212, v167
	v_add_f32_e32 v213, v213, v168
	v_add_f32_e32 v214, v214, v169
	v_add_f32_e32 v215, v215, v170
	v_fma_f32 v171, v212, v212, v171
	v_fma_f32 v171, v213, v213, v171
	v_fma_f32 v171, v214, v214, v171
	v_fma_f32 v171, v215, v215, v171
	v_cvt_pk_bf16_f32 v212, v212, v213
	v_cvt_pk_bf16_f32 v213, v214, v215
	global_store_dwordx2 v164, v[212:213], s[20:21] offset:3104
	v_lshlrev_b32_e32 v167, 16, v156
	v_and_b32_e32 v168, 0xffff0000, v156
	v_lshlrev_b32_e32 v169, 16, v157
	v_and_b32_e32 v170, 0xffff0000, v157
	v_add_f32_e32 v216, v216, v167
	v_add_f32_e32 v217, v217, v168
	v_add_f32_e32 v218, v218, v169
	v_add_f32_e32 v219, v219, v170
	v_fma_f32 v171, v216, v216, v171
	v_fma_f32 v171, v217, v217, v171
	v_fma_f32 v171, v218, v218, v171
	v_fma_f32 v171, v219, v219, v171
	v_cvt_pk_bf16_f32 v216, v216, v217
	v_cvt_pk_bf16_f32 v217, v218, v219
	global_store_dwordx2 v122, v[216:217], s[20:21] offset:3072
	v_lshlrev_b32_e32 v167, 16, v158
	v_and_b32_e32 v168, 0xffff0000, v158
	v_lshlrev_b32_e32 v169, 16, v159
	v_and_b32_e32 v170, 0xffff0000, v159
	v_add_f32_e32 v220, v220, v167
	v_add_f32_e32 v221, v221, v168
	v_add_f32_e32 v222, v222, v169
	v_add_f32_e32 v223, v223, v170
	v_fma_f32 v171, v220, v220, v171
	v_fma_f32 v171, v221, v221, v171
	v_fma_f32 v171, v222, v222, v171
	v_fma_f32 v171, v223, v223, v171
	v_cvt_pk_bf16_f32 v220, v220, v221
	v_cvt_pk_bf16_f32 v221, v222, v223
	global_store_dwordx2 v122, v[220:221], s[20:21] offset:3104
	v_mov_b32_e32 v167, v171
	s_nop 1
	v_permlane32_swap_b32_e32 v171, v167
	v_add_f32_e32 v171, v171, v167
	ds_swizzle_b32 v167, v171 offset:0x401f
	s_waitcnt lgkmcnt(0)
	v_add_f32_e32 v171, v171, v167
	v_cmp_gt_u32_e32 vcc, 16, v160
	s_and_saveexec_b64 s[98:99], vcc
	global_store_dword v166, v171, s[14:15] offset:3080
	s_or_b64 exec, exec, s[98:99]
	s_branch .LBB1_254

; #define BLOAD(A_, B_, kt) do { _Pragma("unroll") for (int i = 0; i < 4; ++i) { \
;     A_[i] = *(const u32x4*)((const char*)Ap + (aoff + (unsigned)(32 * i * lda + (kt) * 64) * 2u)); B_[i] = *(const u32x4*)((const char*)Wt + (woff + (unsigned)(32 * i * K + (kt) * 64) * 2u)); } } while (0)
; #define BLOAD(A_, B_, kt) do { _Pragma("unroll") for (int i = 0; i < 4; ++i) { \
;     A_[i] = *(const u32x4*)((const char*)Ap + (aoff + (unsigned)(32 * i * lda + (kt) * 64) * 2u)); B_[i] = *(const u32x4*)((const char*)Wt + (woff + (unsigned)(32 * i * K + (kt) * 64) * 2u)); } } while (0)
; #define BSTORE(A_, B_, buf) do { _Pragma("unroll") for (int i = 0; i < 4; ++i) { \
;     *(u32x4*)&As[(buf) * GBUF + (srow + 32 * i) * LDT + sc8] = A_[i]; \
;     *(u32x4*)&Bs[(buf) * GBUF + (srow + 32 * i) * LDT + sc8] = B_[i]; } } while (0)
; template <bool ROWNORM, int NK>
; DI void gemm_main_bf(const u16* __restrict__ Ap, int lda, const u16* __restrict__ Wt, f32x16 (&acc)[2][2], char* smem, float* rinv_s) {
;     ...
;   __builtin_amdgcn_s_setprio(0);
;   BLOAD(a0, b0, 0); BLOAD(a1, b1, 1);
;   __syncthreads();
;   BSTORE(a0, b0, 0);
;   BLOAD(a0, b0, 2);
;   __syncthreads();
; #pragma unroll
;   for (int kt = 0; kt < nk; kt += 2) {
;     BCOMP(0);
;     BSTORE(a1, b1, 1);
;     if (kt + 3 < nk) BLOAD(a1, b1, kt + 3);
;     __syncthreads();
;     BCOMP(1);
;     if (kt + 2 < nk) { BSTORE(a0, b0, 0); if (kt + 4 < nk) BLOAD(a0, b0, kt + 4); }
;     __syncthreads();
; DI void tile_branch(const Params& p, int l, int tile, char* smem) {
;     ...
;       gemm_main_bf<false, 16>((const u16*)(p.ws + OFF_XB) + (size_t)m0 * 1024, 1024,
;                               (const u16*)(p.ws + OFF_WIN + l * SZ_WIN) + (size_t)(5760 + br * 1024 + n0) * 1024, accg, smem, nullptr);
.Lbr_gate_k:
	s_waitcnt vmcnt(8)
	s_barrier
	ds_read_b128 v[208:211], v240 offset:0
	ds_read_b128 v[224:227], v241 offset:0
	ds_read_b128 v[228:231], v241 offset:1024
	ds_read_b128 v[232:235], v241 offset:2048
	ds_read_b128 v[236:239], v241 offset:3072
	ds_read_b128 v[212:215], v240 offset:1024
	ds_read_b128 v[216:219], v240 offset:2048
	ds_read_b128 v[220:223], v240 offset:3072
	s_add_u32 m0, s52, 0xc000
	s_add_u32 s28, s28, 0x100000
	s_addc_u32 s29, s29, 0
	global_load_lds_dwordx4 v251, s[28:29]
	global_load_lds_dwordx4 v251, s[28:29] offset:1024
	s_add_u32 m0, s53, 0xc000
	s_add_u32 s30, s30, 0x30000
	s_addc_u32 s31, s31, 0
	global_load_lds_dwordx4 v251, s[30:31]
	global_load_lds_dwordx4 v251, s[30:31] offset:1024
	s_waitcnt lgkmcnt(6)
	v_mfma_f32_16x16x32_bf16 v[2:5], v[224:227], v[208:211], v[2:5]
	s_waitcnt lgkmcnt(5)
	v_mfma_f32_16x16x32_bf16 v[6:9], v[228:231], v[208:211], v[6:9]
	s_waitcnt lgkmcnt(4)
	v_mfma_f32_16x16x32_bf16 v[10:13], v[232:235], v[208:211], v[10:13]
	s_waitcnt lgkmcnt(3)
	v_mfma_f32_16x16x32_bf16 v[14:17], v[236:239], v[208:211], v[14:17]
	s_waitcnt lgkmcnt(2)
	v_mfma_f32_16x16x32_bf16 v[18:21], v[224:227], v[212:215], v[18:21]
	v_mfma_f32_16x16x32_bf16 v[22:25], v[228:231], v[212:215], v[22:25]
	v_mfma_f32_16x16x32_bf16 v[26:29], v[232:235], v[212:215], v[26:29]
	v_mfma_f32_16x16x32_bf16 v[30:33], v[236:239], v[212:215], v[30:33]
	s_waitcnt lgkmcnt(1)
	v_mfma_f32_16x16x32_bf16 v[34:37], v[224:227], v[216:219], v[34:37]
	v_mfma_f32_16x16x32_bf16 v[38:41], v[228:231], v[216:219], v[38:41]
	v_mfma_f32_16x16x32_bf16 v[42:45], v[232:235], v[216:219], v[42:45]
	v_mfma_f32_16x16x32_bf16 v[46:49], v[236:239], v[216:219], v[46:49]
	s_waitcnt lgkmcnt(0)
	v_mfma_f32_16x16x32_bf16 v[50:53], v[224:227], v[220:223], v[50:53]
	v_mfma_f32_16x16x32_bf16 v[54:57], v[228:231], v[220:223], v[54:57]
	v_mfma_f32_16x16x32_bf16 v[58:61], v[232:235], v[220:223], v[58:61]
	v_mfma_f32_16x16x32_bf16 v[62:65], v[236:239], v[220:223], v[62:65]
	s_waitcnt vmcnt(8)
	s_barrier
	ds_read_b128 v[208:211], v240 offset:16384
	ds_read_b128 v[224:227], v241 offset:16384
	ds_read_b128 v[228:231], v241 offset:17408
	ds_read_b128 v[232:235], v241 offset:18432
	ds_read_b128 v[236:239], v241 offset:19456
	ds_read_b128 v[212:215], v240 offset:17408
	ds_read_b128 v[216:219], v240 offset:18432
	ds_read_b128 v[220:223], v240 offset:19456
	s_add_u32 m0, s52, 0x0
	s_add_u32 s28, s28, 0x100000
	s_addc_u32 s29, s29, 0
	global_load_lds_dwordx4 v251, s[28:29]
	global_load_lds_dwordx4 v251, s[28:29] offset:1024
	s_add_u32 m0, s53, 0x0
	s_add_u32 s30, s30, 0x30000
	s_addc_u32 s31, s31, 0
	global_load_lds_dwordx4 v251, s[30:31]
	global_load_lds_dwordx4 v251, s[30:31] offset:1024
	s_waitcnt lgkmcnt(6)
	v_mfma_f32_16x16x32_bf16 v[2:5], v[224:227], v[208:211], v[2:5]
	s_waitcnt lgkmcnt(5)
	v_mfma_f32_16x16x32_bf16 v[6:9], v[228:231], v[208:211], v[6:9]
	s_waitcnt lgkmcnt(4)
	v_mfma_f32_16x16x32_bf16 v[10:13], v[232:235], v[208:211], v[10:13]
	s_waitcnt lgkmcnt(3)
	v_mfma_f32_16x16x32_bf16 v[14:17], v[236:239], v[208:211], v[14:17]
	s_waitcnt lgkmcnt(2)
	v_mfma_f32_16x16x32_bf16 v[18:21], v[224:227], v[212:215], v[18:21]
	v_mfma_f32_16x16x32_bf16 v[22:25], v[228:231], v[212:215], v[22:25]
	v_mfma_f32_16x16x32_bf16 v[26:29], v[232:235], v[212:215], v[26:29]
	v_mfma_f32_16x16x32_bf16 v[30:33], v[236:239], v[212:215], v[30:33]
	s_waitcnt lgkmcnt(1)
	v_mfma_f32_16x16x32_bf16 v[34:37], v[224:227], v[216:219], v[34:37]
	v_mfma_f32_16x16x32_bf16 v[38:41], v[228:231], v[216:219], v[38:41]
	v_mfma_f32_16x16x32_bf16 v[42:45], v[232:235], v[216:219], v[42:45]
	v_mfma_f32_16x16x32_bf16 v[46:49], v[236:239], v[216:219], v[46:49]
	s_waitcnt lgkmcnt(0)
	v_mfma_f32_16x16x32_bf16 v[50:53], v[224:227], v[220:223], v[50:53]
	v_mfma_f32_16x16x32_bf16 v[54:57], v[228:231], v[220:223], v[54:57]
	v_mfma_f32_16x16x32_bf16 v[58:61], v[232:235], v[220:223], v[58:61]
	v_mfma_f32_16x16x32_bf16 v[62:65], v[236:239], v[220:223], v[62:65]
	s_waitcnt vmcnt(8)
	s_barrier
	ds_read_b128 v[208:211], v240 offset:32768
	ds_read_b128 v[224:227], v241 offset:32768
	ds_read_b128 v[228:231], v241 offset:33792
	ds_read_b128 v[232:235], v241 offset:34816
	ds_read_b128 v[236:239], v241 offset:35840
	ds_read_b128 v[212:215], v240 offset:33792
	ds_read_b128 v[216:219], v240 offset:34816
	ds_read_b128 v[220:223], v240 offset:35840
	s_add_u32 m0, s52, 0x4000
	s_add_u32 s28, s28, 0x100000
	s_addc_u32 s29, s29, 0
	global_load_lds_dwordx4 v251, s[28:29]
	global_load_lds_dwordx4 v251, s[28:29] offset:1024
	s_add_u32 m0, s53, 0x4000
	s_add_u32 s30, s30, 0x30000
	s_addc_u32 s31, s31, 0
	global_load_lds_dwordx4 v251, s[30:31]
	global_load_lds_dwordx4 v251, s[30:31] offset:1024
	s_waitcnt lgkmcnt(6)
	v_mfma_f32_16x16x32_bf16 v[2:5], v[224:227], v[208:211], v[2:5]
	s_waitcnt lgkmcnt(5)
	v_mfma_f32_16x16x32_bf16 v[6:9], v[228:231], v[208:211], v[6:9]
	s_waitcnt lgkmcnt(4)
	v_mfma_f32_16x16x32_bf16 v[10:13], v[232:235], v[208:211], v[10:13]
	s_waitcnt lgkmcnt(3)
	v_mfma_f32_16x16x32_bf16 v[14:17], v[236:239], v[208:211], v[14:17]
	s_waitcnt lgkmcnt(2)
	v_mfma_f32_16x16x32_bf16 v[18:21], v[224:227], v[212:215], v[18:21]
	v_mfma_f32_16x16x32_bf16 v[22:25], v[228:231], v[212:215], v[22:25]
	v_mfma_f32_16x16x32_bf16 v[26:29], v[232:235], v[212:215], v[26:29]
	v_mfma_f32_16x16x32_bf16 v[30:33], v[236:239], v[212:215], v[30:33]
	s_waitcnt lgkmcnt(1)
	v_mfma_f32_16x16x32_bf16 v[34:37], v[224:227], v[216:219], v[34:37]
	v_mfma_f32_16x16x32_bf16 v[38:41], v[228:231], v[216:219], v[38:41]
	v_mfma_f32_16x16x32_bf16 v[42:45], v[232:235], v[216:219], v[42:45]
	v_mfma_f32_16x16x32_bf16 v[46:49], v[236:239], v[216:219], v[46:49]
	s_waitcnt lgkmcnt(0)
	v_mfma_f32_16x16x32_bf16 v[50:53], v[224:227], v[220:223], v[50:53]
	v_mfma_f32_16x16x32_bf16 v[54:57], v[228:231], v[220:223], v[54:57]
	v_mfma_f32_16x16x32_bf16 v[58:61], v[232:235], v[220:223], v[58:61]
	v_mfma_f32_16x16x32_bf16 v[62:65], v[236:239], v[220:223], v[62:65]
	s_waitcnt vmcnt(8)
	s_barrier
; #define BLOAD(A_, B_, kt) do { _Pragma("unroll") for (int i = 0; i < 4; ++i) { \
;     A_[i] = *(const u32x4*)((const char*)Ap + (aoff + (unsigned)(32 * i * lda + (kt) * 64) * 2u)); B_[i] = *(const u32x4*)((const char*)Wt + (woff + (unsigned)(32 * i * K + (kt) * 64) * 2u)); } } while (0)
; #define BLOAD(A_, B_, kt) do { _Pragma("unroll") for (int i = 0; i < 4; ++i) { \
;     A_[i] = *(const u32x4*)((const char*)Ap + (aoff + (unsigned)(32 * i * lda + (kt) * 64) * 2u)); B_[i] = *(const u32x4*)((const char*)Wt + (woff + (unsigned)(32 * i * K + (kt) * 64) * 2u)); } } while (0)
; #define BSTORE(A_, B_, buf) do { _Pragma("unroll") for (int i = 0; i < 4; ++i) { \
;     *(u32x4*)&As[(buf) * GBUF + (srow + 32 * i) * LDT + sc8] = A_[i]; \
;     *(u32x4*)&Bs[(buf) * GBUF + (srow + 32 * i) * LDT + sc8] = B_[i]; } } while (0)
; template <bool ROWNORM, int NK>
; DI void gemm_main_bf(const u16* __restrict__ Ap, int lda, const u16* __restrict__ Wt, f32x16 (&acc)[2][2], char* smem, float* rinv_s) {
;     ...
;   __builtin_amdgcn_s_setprio(0);
;   BLOAD(a0, b0, 0); BLOAD(a1, b1, 1);
;   __syncthreads();
;   BSTORE(a0, b0, 0);
;   BLOAD(a0, b0, 2);
;   __syncthreads();
; #pragma unroll
;   for (int kt = 0; kt < nk; kt += 2) {
;     BCOMP(0);
;     BSTORE(a1, b1, 1);
;     if (kt + 3 < nk) BLOAD(a1, b1, kt + 3);
;     __syncthreads();
;     BCOMP(1);
;     if (kt + 2 < nk) { BSTORE(a0, b0, 0); if (kt + 4 < nk) BLOAD(a0, b0, kt + 4); }
;     __syncthreads();
	ds_read_b128 v[208:211], v240 offset:49152
	ds_read_b128 v[224:227], v241 offset:49152
	ds_read_b128 v[228:231], v241 offset:50176
	ds_read_b128 v[232:235], v241 offset:51200
	ds_read_b128 v[236:239], v241 offset:52224
	ds_read_b128 v[212:215], v240 offset:50176
	ds_read_b128 v[216:219], v240 offset:51200
	ds_read_b128 v[220:223], v240 offset:52224
	s_add_u32 m0, s52, 0x8000
	s_add_u32 s28, s28, 0x100000
	s_addc_u32 s29, s29, 0
	global_load_lds_dwordx4 v251, s[28:29]
	global_load_lds_dwordx4 v251, s[28:29] offset:1024
	s_add_u32 m0, s53, 0x8000
	s_add_u32 s30, s30, 0x30000
	s_addc_u32 s31, s31, 0
	global_load_lds_dwordx4 v251, s[30:31]
	global_load_lds_dwordx4 v251, s[30:31] offset:1024
	s_waitcnt lgkmcnt(6)
	v_mfma_f32_16x16x32_bf16 v[2:5], v[224:227], v[208:211], v[2:5]
	s_waitcnt lgkmcnt(5)
	v_mfma_f32_16x16x32_bf16 v[6:9], v[228:231], v[208:211], v[6:9]
	s_waitcnt lgkmcnt(4)
	v_mfma_f32_16x16x32_bf16 v[10:13], v[232:235], v[208:211], v[10:13]
	s_waitcnt lgkmcnt(3)
	v_mfma_f32_16x16x32_bf16 v[14:17], v[236:239], v[208:211], v[14:17]
	s_waitcnt lgkmcnt(2)
	v_mfma_f32_16x16x32_bf16 v[18:21], v[224:227], v[212:215], v[18:21]
	v_mfma_f32_16x16x32_bf16 v[22:25], v[228:231], v[212:215], v[22:25]
	v_mfma_f32_16x16x32_bf16 v[26:29], v[232:235], v[212:215], v[26:29]
	v_mfma_f32_16x16x32_bf16 v[30:33], v[236:239], v[212:215], v[30:33]
	s_waitcnt lgkmcnt(1)
	v_mfma_f32_16x16x32_bf16 v[34:37], v[224:227], v[216:219], v[34:37]
	v_mfma_f32_16x16x32_bf16 v[38:41], v[228:231], v[216:219], v[38:41]
	v_mfma_f32_16x16x32_bf16 v[42:45], v[232:235], v[216:219], v[42:45]
	v_mfma_f32_16x16x32_bf16 v[46:49], v[236:239], v[216:219], v[46:49]
	s_waitcnt lgkmcnt(0)
	v_mfma_f32_16x16x32_bf16 v[50:53], v[224:227], v[220:223], v[50:53]
	v_mfma_f32_16x16x32_bf16 v[54:57], v[228:231], v[220:223], v[54:57]
	v_mfma_f32_16x16x32_bf16 v[58:61], v[232:235], v[220:223], v[58:61]
	v_mfma_f32_16x16x32_bf16 v[62:65], v[236:239], v[220:223], v[62:65]
	s_sub_u32 s74, s74, 1
	s_cmp_lg_u32 s74, 0
	s_cbranch_scc1 .Lbr_gate_k
	s_waitcnt vmcnt(8)
	s_barrier
	ds_read_b128 v[208:211], v240 offset:0
	ds_read_b128 v[224:227], v241 offset:0
	ds_read_b128 v[228:231], v241 offset:1024
	ds_read_b128 v[232:235], v241 offset:2048
	ds_read_b128 v[236:239], v241 offset:3072
	ds_read_b128 v[212:215], v240 offset:1024
	ds_read_b128 v[216:219], v240 offset:2048
	ds_read_b128 v[220:223], v240 offset:3072
	s_add_u32 m0, s52, 0xc000
	s_add_u32 s28, s28, 0x100000
	s_addc_u32 s29, s29, 0
	global_load_lds_dwordx4 v251, s[28:29]
	global_load_lds_dwordx4 v251, s[28:29] offset:1024
	s_add_u32 m0, s53, 0xc000
	s_add_u32 s30, s30, 0x30000
	s_addc_u32 s31, s31, 0
	global_load_lds_dwordx4 v251, s[30:31]
	global_load_lds_dwordx4 v251, s[30:31] offset:1024
	s_waitcnt lgkmcnt(6)
	v_mfma_f32_16x16x32_bf16 v[2:5], v[224:227], v[208:211], v[2:5]
	s_waitcnt lgkmcnt(5)
	v_mfma_f32_16x16x32_bf16 v[6:9], v[228:231], v[208:211], v[6:9]
	s_waitcnt lgkmcnt(4)
	v_mfma_f32_16x16x32_bf16 v[10:13], v[232:235], v[208:211], v[10:13]
	s_waitcnt lgkmcnt(3)
	v_mfma_f32_16x16x32_bf16 v[14:17], v[236:239], v[208:211], v[14:17]
	s_waitcnt lgkmcnt(2)
	v_mfma_f32_16x16x32_bf16 v[18:21], v[224:227], v[212:215], v[18:21]
	v_mfma_f32_16x16x32_bf16 v[22:25], v[228:231], v[212:215], v[22:25]
	v_mfma_f32_16x16x32_bf16 v[26:29], v[232:235], v[212:215], v[26:29]
	v_mfma_f32_16x16x32_bf16 v[30:33], v[236:239], v[212:215], v[30:33]
	s_waitcnt lgkmcnt(1)
	v_mfma_f32_16x16x32_bf16 v[34:37], v[224:227], v[216:219], v[34:37]
	v_mfma_f32_16x16x32_bf16 v[38:41], v[228:231], v[216:219], v[38:41]
	v_mfma_f32_16x16x32_bf16 v[42:45], v[232:235], v[216:219], v[42:45]
	v_mfma_f32_16x16x32_bf16 v[46:49], v[236:239], v[216:219], v[46:49]
	s_waitcnt lgkmcnt(0)
	v_mfma_f32_16x16x32_bf16 v[50:53], v[224:227], v[220:223], v[50:53]
	v_mfma_f32_16x16x32_bf16 v[54:57], v[228:231], v[220:223], v[54:57]
	v_mfma_f32_16x16x32_bf16 v[58:61], v[232:235], v[220:223], v[58:61]
	v_mfma_f32_16x16x32_bf16 v[62:65], v[236:239], v[220:223], v[62:65]
	s_waitcnt vmcnt(8)
	s_barrier
	ds_read_b128 v[208:211], v240 offset:16384
	ds_read_b128 v[224:227], v241 offset:16384
	ds_read_b128 v[228:231], v241 offset:17408
	ds_read_b128 v[232:235], v241 offset:18432
	ds_read_b128 v[236:239], v241 offset:19456
	ds_read_b128 v[212:215], v240 offset:17408
	ds_read_b128 v[216:219], v240 offset:18432
	ds_read_b128 v[220:223], v240 offset:19456
	s_waitcnt lgkmcnt(6)
	v_mfma_f32_16x16x32_bf16 v[2:5], v[224:227], v[208:211], v[2:5]
	s_waitcnt lgkmcnt(5)
	v_mfma_f32_16x16x32_bf16 v[6:9], v[228:231], v[208:211], v[6:9]
	s_waitcnt lgkmcnt(4)
	v_mfma_f32_16x16x32_bf16 v[10:13], v[232:235], v[208:211], v[10:13]
	s_waitcnt lgkmcnt(3)
	v_mfma_f32_16x16x32_bf16 v[14:17], v[236:239], v[208:211], v[14:17]
	s_waitcnt lgkmcnt(2)
	v_mfma_f32_16x16x32_bf16 v[18:21], v[224:227], v[212:215], v[18:21]
	v_mfma_f32_16x16x32_bf16 v[22:25], v[228:231], v[212:215], v[22:25]
	v_mfma_f32_16x16x32_bf16 v[26:29], v[232:235], v[212:215], v[26:29]
	v_mfma_f32_16x16x32_bf16 v[30:33], v[236:239], v[212:215], v[30:33]
	s_waitcnt lgkmcnt(1)
	v_mfma_f32_16x16x32_bf16 v[34:37], v[224:227], v[216:219], v[34:37]
	v_mfma_f32_16x16x32_bf16 v[38:41], v[228:231], v[216:219], v[38:41]
	v_mfma_f32_16x16x32_bf16 v[42:45], v[232:235], v[216:219], v[42:45]
	v_mfma_f32_16x16x32_bf16 v[46:49], v[236:239], v[216:219], v[46:49]
	s_waitcnt lgkmcnt(0)
	v_mfma_f32_16x16x32_bf16 v[50:53], v[224:227], v[220:223], v[50:53]
	v_mfma_f32_16x16x32_bf16 v[54:57], v[228:231], v[220:223], v[54:57]
	v_mfma_f32_16x16x32_bf16 v[58:61], v[232:235], v[220:223], v[58:61]
	v_mfma_f32_16x16x32_bf16 v[62:65], v[236:239], v[220:223], v[62:65]
	s_waitcnt vmcnt(4)
	s_barrier
; DI unsigned pk2(float a, float b) { f2_t v = {a, b}; bf2_t r = __builtin_convertvector(v, bf2_t); return __builtin_bit_cast(unsigned, r); }
; #define BLOAD(A_, B_, kt) do { _Pragma("unroll") for (int i = 0; i < 4; ++i) { \
;     A_[i] = *(const u32x4*)((const char*)Ap + (aoff + (unsigned)(32 * i * lda + (kt) * 64) * 2u)); B_[i] = *(const u32x4*)((const char*)Wt + (woff + (unsigned)(32 * i * K + (kt) * 64) * 2u)); } } while (0)
; #define BLOAD(A_, B_, kt) do { _Pragma("unroll") for (int i = 0; i < 4; ++i) { \
;     A_[i] = *(const u32x4*)((const char*)Ap + (aoff + (unsigned)(32 * i * lda + (kt) * 64) * 2u)); B_[i] = *(const u32x4*)((const char*)Wt + (woff + (unsigned)(32 * i * K + (kt) * 64) * 2u)); } } while (0)
; #define BSTORE(A_, B_, buf) do { _Pragma("unroll") for (int i = 0; i < 4; ++i) { \
;     *(u32x4*)&As[(buf) * GBUF + (srow + 32 * i) * LDT + sc8] = A_[i]; \
;     *(u32x4*)&Bs[(buf) * GBUF + (srow + 32 * i) * LDT + sc8] = B_[i]; } } while (0)
; template <bool ROWNORM, int NK>
; DI void gemm_main_bf(const u16* __restrict__ Ap, int lda, const u16* __restrict__ Wt, f32x16 (&acc)[2][2], char* smem, float* rinv_s) {
;     ...
; #pragma unroll
;   for (int kt = 0; kt < nk; kt += 2) {
;     BCOMP(0);
;     BSTORE(a1, b1, 1);
;     if (kt + 3 < nk) BLOAD(a1, b1, kt + 3);
;     __syncthreads();
;     BCOMP(1);
;     if (kt + 2 < nk) { BSTORE(a0, b0, 0); if (kt + 4 < nk) BLOAD(a0, b0, kt + 4); }
;     __syncthreads();
; DI void tile_branch(const Params& p, int l, int tile, char* smem) {
;     ...
; #pragma unroll
;       for (int mt = 0; mt < 2; ++mt)
; #pragma unroll
;         for (int g4 = 0; g4 < 4; ++g4) {
;           const f32x4 r4 = *(const f32x4*)&rinv_s[wm * 64 + mt * 32 + 8 * g4 + 4 * hi];
; #pragma unroll
;           for (int nt = 0; nt < 2; ++nt) {
;             const float s0 = 1.f / (1.f + __expf(-accg[mt][nt][4 * g4 + 0] * r4[0])), s1 = 1.f / (1.f + __expf(-accg[mt][nt][4 * g4 + 1] * r4[1]));
;             const float s2 = 1.f / (1.f + __expf(-accg[mt][nt][4 * g4 + 2] * r4[2])), s3 = 1.f / (1.f + __expf(-accg[mt][nt][4 * g4 + 3] * r4[3]));
;             gpk[mt][nt][2 * g4] = pk2(s0, s1); gpk[mt][nt][2 * g4 + 1] = pk2(s2, s3);
;           }
;         }
	ds_read_b128 v[208:211], v240 offset:32768
	ds_read_b128 v[224:227], v241 offset:32768
	ds_read_b128 v[228:231], v241 offset:33792
	ds_read_b128 v[232:235], v241 offset:34816
	ds_read_b128 v[236:239], v241 offset:35840
	ds_read_b128 v[212:215], v240 offset:33792
	ds_read_b128 v[216:219], v240 offset:34816
	ds_read_b128 v[220:223], v240 offset:35840
	s_waitcnt lgkmcnt(6)
	v_mfma_f32_16x16x32_bf16 v[2:5], v[224:227], v[208:211], v[2:5]
	s_waitcnt lgkmcnt(5)
	v_mfma_f32_16x16x32_bf16 v[6:9], v[228:231], v[208:211], v[6:9]
	s_waitcnt lgkmcnt(4)
	v_mfma_f32_16x16x32_bf16 v[10:13], v[232:235], v[208:211], v[10:13]
	s_waitcnt lgkmcnt(3)
	v_mfma_f32_16x16x32_bf16 v[14:17], v[236:239], v[208:211], v[14:17]
	s_waitcnt lgkmcnt(2)
	v_mfma_f32_16x16x32_bf16 v[18:21], v[224:227], v[212:215], v[18:21]
	v_mfma_f32_16x16x32_bf16 v[22:25], v[228:231], v[212:215], v[22:25]
	v_mfma_f32_16x16x32_bf16 v[26:29], v[232:235], v[212:215], v[26:29]
	v_mfma_f32_16x16x32_bf16 v[30:33], v[236:239], v[212:215], v[30:33]
	s_waitcnt lgkmcnt(1)
	v_mfma_f32_16x16x32_bf16 v[34:37], v[224:227], v[216:219], v[34:37]
	v_mfma_f32_16x16x32_bf16 v[38:41], v[228:231], v[216:219], v[38:41]
	v_mfma_f32_16x16x32_bf16 v[42:45], v[232:235], v[216:219], v[42:45]
	v_mfma_f32_16x16x32_bf16 v[46:49], v[236:239], v[216:219], v[46:49]
	s_waitcnt lgkmcnt(0)
	v_mfma_f32_16x16x32_bf16 v[50:53], v[224:227], v[220:223], v[50:53]
	v_mfma_f32_16x16x32_bf16 v[54:57], v[228:231], v[220:223], v[54:57]
	v_mfma_f32_16x16x32_bf16 v[58:61], v[232:235], v[220:223], v[58:61]
	v_mfma_f32_16x16x32_bf16 v[62:65], v[236:239], v[220:223], v[62:65]
	s_waitcnt vmcnt(0)
	s_barrier
	ds_read_b128 v[208:211], v240 offset:49152
	ds_read_b128 v[224:227], v241 offset:49152
	ds_read_b128 v[228:231], v241 offset:50176
	ds_read_b128 v[232:235], v241 offset:51200
	ds_read_b128 v[236:239], v241 offset:52224
	ds_read_b128 v[212:215], v240 offset:50176
	ds_read_b128 v[216:219], v240 offset:51200
	ds_read_b128 v[220:223], v240 offset:52224
	s_waitcnt lgkmcnt(6)
	v_mfma_f32_16x16x32_bf16 v[2:5], v[224:227], v[208:211], v[2:5]
	s_waitcnt lgkmcnt(5)
	v_mfma_f32_16x16x32_bf16 v[6:9], v[228:231], v[208:211], v[6:9]
	s_waitcnt lgkmcnt(4)
	v_mfma_f32_16x16x32_bf16 v[10:13], v[232:235], v[208:211], v[10:13]
	s_waitcnt lgkmcnt(3)
	v_mfma_f32_16x16x32_bf16 v[14:17], v[236:239], v[208:211], v[14:17]
	s_waitcnt lgkmcnt(2)
	v_mfma_f32_16x16x32_bf16 v[18:21], v[224:227], v[212:215], v[18:21]
	v_mfma_f32_16x16x32_bf16 v[22:25], v[228:231], v[212:215], v[22:25]
	v_mfma_f32_16x16x32_bf16 v[26:29], v[232:235], v[212:215], v[26:29]
	v_mfma_f32_16x16x32_bf16 v[30:33], v[236:239], v[212:215], v[30:33]
	s_waitcnt lgkmcnt(1)
	v_mfma_f32_16x16x32_bf16 v[34:37], v[224:227], v[216:219], v[34:37]
	v_mfma_f32_16x16x32_bf16 v[38:41], v[228:231], v[216:219], v[38:41]
	v_mfma_f32_16x16x32_bf16 v[42:45], v[232:235], v[216:219], v[42:45]
	v_mfma_f32_16x16x32_bf16 v[46:49], v[236:239], v[216:219], v[46:49]
	s_waitcnt lgkmcnt(0)
	v_mfma_f32_16x16x32_bf16 v[50:53], v[224:227], v[220:223], v[50:53]
	v_mfma_f32_16x16x32_bf16 v[54:57], v[228:231], v[220:223], v[54:57]
	v_mfma_f32_16x16x32_bf16 v[58:61], v[232:235], v[220:223], v[58:61]
	v_mfma_f32_16x16x32_bf16 v[62:65], v[236:239], v[220:223], v[62:65]
	s_mov_b64 s[28:29], s[48:49]
	s_mov_b64 s[30:31], s[50:51]
	ds_read_b32 v162, v250 offset:0
	ds_read_b32 v163, v250 offset:64
	ds_read_b32 v164, v250 offset:128
	ds_read_b32 v165, v250 offset:192
	s_waitcnt lgkmcnt(0)
	v_mul_f32_e32 v162, 0xbfb8aa3b, v162
	v_mul_f32_e32 v163, 0xbfb8aa3b, v163
	v_mul_f32_e32 v164, 0xbfb8aa3b, v164
	v_mul_f32_e32 v165, 0xbfb8aa3b, v165
	v_mul_f32_e32 v166, v162, v2
	v_mul_f32_e32 v167, v162, v3
	v_mul_f32_e32 v168, v162, v4
	v_mul_f32_e32 v169, v162, v5
	v_exp_f32_e32 v166, v166
	v_exp_f32_e32 v167, v167
	v_exp_f32_e32 v168, v168
	v_exp_f32_e32 v169, v169
	v_add_f32_e32 v166, 1.0, v166
	v_add_f32_e32 v167, 1.0, v167
	v_add_f32_e32 v168, 1.0, v168
	v_add_f32_e32 v169, 1.0, v169
	v_rcp_f32_e32 v166, v166
	v_rcp_f32_e32 v167, v167
	v_rcp_f32_e32 v168, v168
	v_rcp_f32_e32 v169, v169
	v_cvt_pk_bf16_f32 v130, v166, v167
	v_cvt_pk_bf16_f32 v131, v168, v169
	v_mul_f32_e32 v166, v162, v6
	v_mul_f32_e32 v167, v162, v7
	v_mul_f32_e32 v168, v162, v8
	v_mul_f32_e32 v169, v162, v9
	v_exp_f32_e32 v166, v166
	v_exp_f32_e32 v167, v167
	v_exp_f32_e32 v168, v168
	v_exp_f32_e32 v169, v169
	v_add_f32_e32 v166, 1.0, v166
	v_add_f32_e32 v167, 1.0, v167
	v_add_f32_e32 v168, 1.0, v168
	v_add_f32_e32 v169, 1.0, v169
	v_rcp_f32_e32 v166, v166
	v_rcp_f32_e32 v167, v167
	v_rcp_f32_e32 v168, v168
	v_rcp_f32_e32 v169, v169
	v_cvt_pk_bf16_f32 v132, v166, v167
	v_cvt_pk_bf16_f32 v133, v168, v169
	v_mul_f32_e32 v166, v162, v10
	v_mul_f32_e32 v167, v162, v11
	v_mul_f32_e32 v168, v162, v12
	v_mul_f32_e32 v169, v162, v13
	v_exp_f32_e32 v166, v166
	v_exp_f32_e32 v167, v167
	v_exp_f32_e32 v168, v168
	v_exp_f32_e32 v169, v169
	v_add_f32_e32 v166, 1.0, v166
	v_add_f32_e32 v167, 1.0, v167
	v_add_f32_e32 v168, 1.0, v168
	v_add_f32_e32 v169, 1.0, v169
	v_rcp_f32_e32 v166, v166
	v_rcp_f32_e32 v167, v167
	v_rcp_f32_e32 v168, v168
	v_rcp_f32_e32 v169, v169
	v_cvt_pk_bf16_f32 v134, v166, v167
	v_cvt_pk_bf16_f32 v135, v168, v169
	v_mul_f32_e32 v166, v162, v14
	v_mul_f32_e32 v167, v162, v15
	v_mul_f32_e32 v168, v162, v16
	v_mul_f32_e32 v169, v162, v17
	v_exp_f32_e32 v166, v166
	v_exp_f32_e32 v167, v167
	v_exp_f32_e32 v168, v168
	v_exp_f32_e32 v169, v169
	v_add_f32_e32 v166, 1.0, v166
	v_add_f32_e32 v167, 1.0, v167
	v_add_f32_e32 v168, 1.0, v168
	v_add_f32_e32 v169, 1.0, v169
	v_rcp_f32_e32 v166, v166
	v_rcp_f32_e32 v167, v167
	v_rcp_f32_e32 v168, v168
	v_rcp_f32_e32 v169, v169
; DI unsigned pk2(float a, float b) { f2_t v = {a, b}; bf2_t r = __builtin_convertvector(v, bf2_t); return __builtin_bit_cast(unsigned, r); }
; DI void tile_branch(const Params& p, int l, int tile, char* smem) {
;     ...
;         for (int g4 = 0; g4 < 4; ++g4) {
;           const f32x4 r4 = *(const f32x4*)&rinv_s[wm * 64 + mt * 32 + 8 * g4 + 4 * hi];
; #pragma unroll
;           for (int nt = 0; nt < 2; ++nt) {
;             const float s0 = 1.f / (1.f + __expf(-accg[mt][nt][4 * g4 + 0] * r4[0])), s1 = 1.f / (1.f + __expf(-accg[mt][nt][4 * g4 + 1] * r4[1]));
;             const float s2 = 1.f / (1.f + __expf(-accg[mt][nt][4 * g4 + 2] * r4[2])), s3 = 1.f / (1.f + __expf(-accg[mt][nt][4 * g4 + 3] * r4[3]));
;             gpk[mt][nt][2 * g4] = pk2(s0, s1); gpk[mt][nt][2 * g4 + 1] = pk2(s2, s3);
;           }
;         }
	v_cvt_pk_bf16_f32 v136, v166, v167
	v_cvt_pk_bf16_f32 v137, v168, v169
	v_mul_f32_e32 v166, v163, v18
	v_mul_f32_e32 v167, v163, v19
	v_mul_f32_e32 v168, v163, v20
	v_mul_f32_e32 v169, v163, v21
	v_exp_f32_e32 v166, v166
	v_exp_f32_e32 v167, v167
	v_exp_f32_e32 v168, v168
	v_exp_f32_e32 v169, v169
	v_add_f32_e32 v166, 1.0, v166
	v_add_f32_e32 v167, 1.0, v167
	v_add_f32_e32 v168, 1.0, v168
	v_add_f32_e32 v169, 1.0, v169
	v_rcp_f32_e32 v166, v166
	v_rcp_f32_e32 v167, v167
	v_rcp_f32_e32 v168, v168
	v_rcp_f32_e32 v169, v169
	v_cvt_pk_bf16_f32 v138, v166, v167
	v_cvt_pk_bf16_f32 v139, v168, v169
	v_mul_f32_e32 v166, v163, v22
	v_mul_f32_e32 v167, v163, v23
	v_mul_f32_e32 v168, v163, v24
	v_mul_f32_e32 v169, v163, v25
	v_exp_f32_e32 v166, v166
	v_exp_f32_e32 v167, v167
	v_exp_f32_e32 v168, v168
	v_exp_f32_e32 v169, v169
	v_add_f32_e32 v166, 1.0, v166
	v_add_f32_e32 v167, 1.0, v167
	v_add_f32_e32 v168, 1.0, v168
	v_add_f32_e32 v169, 1.0, v169
	v_rcp_f32_e32 v166, v166
	v_rcp_f32_e32 v167, v167
	v_rcp_f32_e32 v168, v168
	v_rcp_f32_e32 v169, v169
	v_cvt_pk_bf16_f32 v140, v166, v167
	v_cvt_pk_bf16_f32 v141, v168, v169
	v_mul_f32_e32 v166, v163, v26
	v_mul_f32_e32 v167, v163, v27
	v_mul_f32_e32 v168, v163, v28
	v_mul_f32_e32 v169, v163, v29
	v_exp_f32_e32 v166, v166
	v_exp_f32_e32 v167, v167
	v_exp_f32_e32 v168, v168
	v_exp_f32_e32 v169, v169
	v_add_f32_e32 v166, 1.0, v166
	v_add_f32_e32 v167, 1.0, v167
	v_add_f32_e32 v168, 1.0, v168
	v_add_f32_e32 v169, 1.0, v169
	v_rcp_f32_e32 v166, v166
	v_rcp_f32_e32 v167, v167
	v_rcp_f32_e32 v168, v168
	v_rcp_f32_e32 v169, v169
	v_cvt_pk_bf16_f32 v142, v166, v167
	v_cvt_pk_bf16_f32 v143, v168, v169
	v_mul_f32_e32 v166, v163, v30
	v_mul_f32_e32 v167, v163, v31
	v_mul_f32_e32 v168, v163, v32
	v_mul_f32_e32 v169, v163, v33
	v_exp_f32_e32 v166, v166
	v_exp_f32_e32 v167, v167
	v_exp_f32_e32 v168, v168
	v_exp_f32_e32 v169, v169
	v_add_f32_e32 v166, 1.0, v166
	v_add_f32_e32 v167, 1.0, v167
	v_add_f32_e32 v168, 1.0, v168
	v_add_f32_e32 v169, 1.0, v169
	v_rcp_f32_e32 v166, v166
	v_rcp_f32_e32 v167, v167
	v_rcp_f32_e32 v168, v168
	v_rcp_f32_e32 v169, v169
	v_cvt_pk_bf16_f32 v144, v166, v167
	v_cvt_pk_bf16_f32 v145, v168, v169
	v_mul_f32_e32 v166, v164, v34
	v_mul_f32_e32 v167, v164, v35
	v_mul_f32_e32 v168, v164, v36
	v_mul_f32_e32 v169, v164, v37
	v_exp_f32_e32 v166, v166
	v_exp_f32_e32 v167, v167
	v_exp_f32_e32 v168, v168
	v_exp_f32_e32 v169, v169
	v_add_f32_e32 v166, 1.0, v166
	v_add_f32_e32 v167, 1.0, v167
	v_add_f32_e32 v168, 1.0, v168
	v_add_f32_e32 v169, 1.0, v169
	v_rcp_f32_e32 v166, v166
	v_rcp_f32_e32 v167, v167
	v_rcp_f32_e32 v168, v168
	v_rcp_f32_e32 v169, v169
	v_cvt_pk_bf16_f32 v146, v166, v167
	v_cvt_pk_bf16_f32 v147, v168, v169
	v_mul_f32_e32 v166, v164, v38
	v_mul_f32_e32 v167, v164, v39
	v_mul_f32_e32 v168, v164, v40
	v_mul_f32_e32 v169, v164, v41
	v_exp_f32_e32 v166, v166
	v_exp_f32_e32 v167, v167
	v_exp_f32_e32 v168, v168
	v_exp_f32_e32 v169, v169
	v_add_f32_e32 v166, 1.0, v166
	v_add_f32_e32 v167, 1.0, v167
	v_add_f32_e32 v168, 1.0, v168
	v_add_f32_e32 v169, 1.0, v169
	v_rcp_f32_e32 v166, v166
	v_rcp_f32_e32 v167, v167
	v_rcp_f32_e32 v168, v168
	v_rcp_f32_e32 v169, v169
	v_cvt_pk_bf16_f32 v148, v166, v167
	v_cvt_pk_bf16_f32 v149, v168, v169
	v_mul_f32_e32 v166, v164, v42
	v_mul_f32_e32 v167, v164, v43
	v_mul_f32_e32 v168, v164, v44
	v_mul_f32_e32 v169, v164, v45
	v_exp_f32_e32 v166, v166
	v_exp_f32_e32 v167, v167
	v_exp_f32_e32 v168, v168
	v_exp_f32_e32 v169, v169
	v_add_f32_e32 v166, 1.0, v166
	v_add_f32_e32 v167, 1.0, v167
	v_add_f32_e32 v168, 1.0, v168
	v_add_f32_e32 v169, 1.0, v169
	v_rcp_f32_e32 v166, v166
	v_rcp_f32_e32 v167, v167
	v_rcp_f32_e32 v168, v168
	v_rcp_f32_e32 v169, v169
	v_cvt_pk_bf16_f32 v150, v166, v167
	v_cvt_pk_bf16_f32 v151, v168, v169
	v_mul_f32_e32 v166, v164, v46
	v_mul_f32_e32 v167, v164, v47
	v_mul_f32_e32 v168, v164, v48
	v_mul_f32_e32 v169, v164, v49
	v_exp_f32_e32 v166, v166
	v_exp_f32_e32 v167, v167
	v_exp_f32_e32 v168, v168
	v_exp_f32_e32 v169, v169
	v_add_f32_e32 v166, 1.0, v166
	v_add_f32_e32 v167, 1.0, v167
	v_add_f32_e32 v168, 1.0, v168
	v_add_f32_e32 v169, 1.0, v169
	v_rcp_f32_e32 v166, v166
	v_rcp_f32_e32 v167, v167
	v_rcp_f32_e32 v168, v168
	v_rcp_f32_e32 v169, v169
	v_cvt_pk_bf16_f32 v152, v166, v167
	v_cvt_pk_bf16_f32 v153, v168, v169
	v_mul_f32_e32 v166, v165, v50
	v_mul_f32_e32 v167, v165, v51
	v_mul_f32_e32 v168, v165, v52
	v_mul_f32_e32 v169, v165, v53
	v_exp_f32_e32 v166, v166
	v_exp_f32_e32 v167, v167
	v_exp_f32_e32 v168, v168
	v_exp_f32_e32 v169, v169
	v_add_f32_e32 v166, 1.0, v166
	v_add_f32_e32 v167, 1.0, v167
	v_add_f32_e32 v168, 1.0, v168
	v_add_f32_e32 v169, 1.0, v169
	v_rcp_f32_e32 v166, v166
	v_rcp_f32_e32 v167, v167
	v_rcp_f32_e32 v168, v168
	v_rcp_f32_e32 v169, v169
	v_cvt_pk_bf16_f32 v154, v166, v167
	v_cvt_pk_bf16_f32 v155, v168, v169
	v_mul_f32_e32 v166, v165, v54
	v_mul_f32_e32 v167, v165, v55
	v_mul_f32_e32 v168, v165, v56
	v_mul_f32_e32 v169, v165, v57
	v_exp_f32_e32 v166, v166
	v_exp_f32_e32 v167, v167
	v_exp_f32_e32 v168, v168
	v_exp_f32_e32 v169, v169
	v_add_f32_e32 v166, 1.0, v166
	v_add_f32_e32 v167, 1.0, v167
	v_add_f32_e32 v168, 1.0, v168
	v_add_f32_e32 v169, 1.0, v169
	v_rcp_f32_e32 v166, v166
	v_rcp_f32_e32 v167, v167
	v_rcp_f32_e32 v168, v168
	v_rcp_f32_e32 v169, v169
	v_cvt_pk_bf16_f32 v156, v166, v167
	v_cvt_pk_bf16_f32 v157, v168, v169
	v_mul_f32_e32 v166, v165, v58
	v_mul_f32_e32 v167, v165, v59
	v_mul_f32_e32 v168, v165, v60
	v_mul_f32_e32 v169, v165, v61
	v_exp_f32_e32 v166, v166
	v_exp_f32_e32 v167, v167
	v_exp_f32_e32 v168, v168
	v_exp_f32_e32 v169, v169
	v_add_f32_e32 v166, 1.0, v166
	v_add_f32_e32 v167, 1.0, v167
; DI unsigned pk2(float a, float b) { f2_t v = {a, b}; bf2_t r = __builtin_convertvector(v, bf2_t); return __builtin_bit_cast(unsigned, r); }
; #define BLOAD(A_, B_, kt) do { _Pragma("unroll") for (int i = 0; i < 4; ++i) { \
;     A_[i] = *(const u32x4*)((const char*)Ap + (aoff + (unsigned)(32 * i * lda + (kt) * 64) * 2u)); B_[i] = *(const u32x4*)((const char*)Wt + (woff + (unsigned)(32 * i * K + (kt) * 64) * 2u)); } } while (0)
; #define BLOAD(A_, B_, kt) do { _Pragma("unroll") for (int i = 0; i < 4; ++i) { \
;     A_[i] = *(const u32x4*)((const char*)Ap + (aoff + (unsigned)(32 * i * lda + (kt) * 64) * 2u)); B_[i] = *(const u32x4*)((const char*)Wt + (woff + (unsigned)(32 * i * K + (kt) * 64) * 2u)); } } while (0)
; #define BSTORE(A_, B_, buf) do { _Pragma("unroll") for (int i = 0; i < 4; ++i) { \
;     *(u32x4*)&As[(buf) * GBUF + (srow + 32 * i) * LDT + sc8] = A_[i]; \
;     *(u32x4*)&Bs[(buf) * GBUF + (srow + 32 * i) * LDT + sc8] = B_[i]; } } while (0)
; template <bool ROWNORM, int NK>
; DI void gemm_main_bf(const u16* __restrict__ Ap, int lda, const u16* __restrict__ Wt, f32x16 (&acc)[2][2], char* smem, float* rinv_s) {
;     ...
;   BLOAD(a0, b0, 0); BLOAD(a1, b1, 1);
;   __syncthreads();
;   BSTORE(a0, b0, 0);
;   BLOAD(a0, b0, 2);
;   __syncthreads();
; #pragma unroll
;   for (int kt = 0; kt < nk; kt += 2) {
;     BCOMP(0);
;     BSTORE(a1, b1, 1);
;     if (kt + 3 < nk) BLOAD(a1, b1, kt + 3);
;     __syncthreads();
;     BCOMP(1);
;     if (kt + 2 < nk) { BSTORE(a0, b0, 0); if (kt + 4 < nk) BLOAD(a0, b0, kt + 4); }
;     __syncthreads();
; DI void tile_branch(const Params& p, int l, int tile, char* smem) {
;     ...
;             const float s0 = 1.f / (1.f + __expf(-accg[mt][nt][4 * g4 + 0] * r4[0])), s1 = 1.f / (1.f + __expf(-accg[mt][nt][4 * g4 + 1] * r4[1]));
;             const float s2 = 1.f / (1.f + __expf(-accg[mt][nt][4 * g4 + 2] * r4[2])), s3 = 1.f / (1.f + __expf(-accg[mt][nt][4 * g4 + 3] * r4[3]));
;             gpk[mt][nt][2 * g4] = pk2(s0, s1); gpk[mt][nt][2 * g4 + 1] = pk2(s2, s3);
;           }
;         }
;     }
;     f32x16 acc[2][2]; zero_acc(acc);
;     gemm_main_bf<false, 8>((const u16*)(p.ws + OFF_BR) + (size_t)(br * CT + m0) * 512, 512,
	v_add_f32_e32 v168, 1.0, v168
	v_add_f32_e32 v169, 1.0, v169
	v_rcp_f32_e32 v166, v166
	v_rcp_f32_e32 v167, v167
	v_rcp_f32_e32 v168, v168
	v_rcp_f32_e32 v169, v169
	v_cvt_pk_bf16_f32 v158, v166, v167
	v_cvt_pk_bf16_f32 v159, v168, v169
	v_mul_f32_e32 v166, v165, v62
	v_mul_f32_e32 v167, v165, v63
	v_mul_f32_e32 v168, v165, v64
	v_mul_f32_e32 v169, v165, v65
	v_exp_f32_e32 v166, v166
	v_exp_f32_e32 v167, v167
	v_exp_f32_e32 v168, v168
	v_exp_f32_e32 v169, v169
	v_add_f32_e32 v166, 1.0, v166
	v_add_f32_e32 v167, 1.0, v167
	v_add_f32_e32 v168, 1.0, v168
	v_add_f32_e32 v169, 1.0, v169
	v_rcp_f32_e32 v166, v166
	v_rcp_f32_e32 v167, v167
	v_rcp_f32_e32 v168, v168
	v_rcp_f32_e32 v169, v169
	v_cvt_pk_bf16_f32 v160, v166, v167
	v_cvt_pk_bf16_f32 v161, v168, v169
	s_add_u32 m0, s52, 0x0
	s_nop 0
	global_load_lds_dwordx4 v244, s[28:29]
	global_load_lds_dwordx4 v245, s[28:29] offset:1024
	s_add_u32 m0, s53, 0x0
	s_nop 0
	global_load_lds_dwordx4 v251, s[30:31]
	global_load_lds_dwordx4 v251, s[30:31] offset:1024
	s_add_u32 m0, s52, 0x4000
	s_add_u32 s28, s28, 0x40
	s_addc_u32 s29, s29, 0
	global_load_lds_dwordx4 v244, s[28:29]
	global_load_lds_dwordx4 v245, s[28:29] offset:1024
	s_add_u32 m0, s53, 0x4000
	s_add_u32 s30, s30, 0x10000
	s_addc_u32 s31, s31, 0
	global_load_lds_dwordx4 v251, s[30:31]
	global_load_lds_dwordx4 v251, s[30:31] offset:1024
	s_add_u32 m0, s52, 0x8000
	s_add_u32 s28, s28, 0x40
	s_addc_u32 s29, s29, 0
	global_load_lds_dwordx4 v244, s[28:29]
	global_load_lds_dwordx4 v245, s[28:29] offset:1024
	s_add_u32 m0, s53, 0x8000
	s_add_u32 s30, s30, 0x10000
	s_addc_u32 s31, s31, 0
	global_load_lds_dwordx4 v251, s[30:31]
	global_load_lds_dwordx4 v251, s[30:31] offset:1024
	v_mov_b32_e32 v2, 0
	v_mov_b32_e32 v3, 0
	v_mov_b32_e32 v4, 0
	v_mov_b32_e32 v5, 0
	v_mov_b32_e32 v6, 0
	v_mov_b32_e32 v7, 0
	v_mov_b32_e32 v8, 0
	v_mov_b32_e32 v9, 0
	v_mov_b32_e32 v10, 0
	v_mov_b32_e32 v11, 0
	v_mov_b32_e32 v12, 0
	v_mov_b32_e32 v13, 0
	v_mov_b32_e32 v14, 0
	v_mov_b32_e32 v15, 0
	v_mov_b32_e32 v16, 0
	v_mov_b32_e32 v17, 0
	v_mov_b32_e32 v18, 0
	v_mov_b32_e32 v19, 0
	v_mov_b32_e32 v20, 0
	v_mov_b32_e32 v21, 0
	v_mov_b32_e32 v22, 0
	v_mov_b32_e32 v23, 0
	v_mov_b32_e32 v24, 0
	v_mov_b32_e32 v25, 0
	v_mov_b32_e32 v26, 0
	v_mov_b32_e32 v27, 0
	v_mov_b32_e32 v28, 0
	v_mov_b32_e32 v29, 0
	v_mov_b32_e32 v30, 0
	v_mov_b32_e32 v31, 0
	v_mov_b32_e32 v32, 0
	v_mov_b32_e32 v33, 0
	v_mov_b32_e32 v34, 0
	v_mov_b32_e32 v35, 0
	v_mov_b32_e32 v36, 0
	v_mov_b32_e32 v37, 0
	v_mov_b32_e32 v38, 0
	v_mov_b32_e32 v39, 0
	v_mov_b32_e32 v40, 0
	v_mov_b32_e32 v41, 0
	v_mov_b32_e32 v42, 0
	v_mov_b32_e32 v43, 0
	v_mov_b32_e32 v44, 0
	v_mov_b32_e32 v45, 0
	v_mov_b32_e32 v46, 0
	v_mov_b32_e32 v47, 0
	v_mov_b32_e32 v48, 0
	v_mov_b32_e32 v49, 0
	v_mov_b32_e32 v50, 0
	v_mov_b32_e32 v51, 0
	v_mov_b32_e32 v52, 0
	v_mov_b32_e32 v53, 0
	v_mov_b32_e32 v54, 0
	v_mov_b32_e32 v55, 0
	v_mov_b32_e32 v56, 0
	v_mov_b32_e32 v57, 0
	v_mov_b32_e32 v58, 0
	v_mov_b32_e32 v59, 0
	v_mov_b32_e32 v60, 0
	v_mov_b32_e32 v61, 0
	v_mov_b32_e32 v62, 0
	v_mov_b32_e32 v63, 0
	v_mov_b32_e32 v64, 0
	v_mov_b32_e32 v65, 0
	s_mov_b32 s74, 3
.Lbr_proj_k:
	s_waitcnt vmcnt(8)
	s_barrier
	ds_read_b128 v[208:211], v240 offset:0
	ds_read_b128 v[224:227], v241 offset:0
	ds_read_b128 v[228:231], v241 offset:1024
	ds_read_b128 v[232:235], v241 offset:2048
	ds_read_b128 v[236:239], v241 offset:3072
	ds_read_b128 v[212:215], v240 offset:1024
	ds_read_b128 v[216:219], v240 offset:2048
	ds_read_b128 v[220:223], v240 offset:3072
	s_add_u32 m0, s52, 0xc000
	s_add_u32 s28, s28, 0x40
	s_addc_u32 s29, s29, 0
	global_load_lds_dwordx4 v244, s[28:29]
	global_load_lds_dwordx4 v245, s[28:29] offset:1024
	s_add_u32 m0, s53, 0xc000
	s_add_u32 s30, s30, 0x10000
	s_addc_u32 s31, s31, 0
	global_load_lds_dwordx4 v251, s[30:31]
	global_load_lds_dwordx4 v251, s[30:31] offset:1024
	s_waitcnt lgkmcnt(6)
	v_mfma_f32_16x16x32_bf16 v[2:5], v[224:227], v[208:211], v[2:5]
	s_waitcnt lgkmcnt(5)
	v_mfma_f32_16x16x32_bf16 v[6:9], v[228:231], v[208:211], v[6:9]
	s_waitcnt lgkmcnt(4)
	v_mfma_f32_16x16x32_bf16 v[10:13], v[232:235], v[208:211], v[10:13]
	s_waitcnt lgkmcnt(3)
	v_mfma_f32_16x16x32_bf16 v[14:17], v[236:239], v[208:211], v[14:17]
	s_waitcnt lgkmcnt(2)
	v_mfma_f32_16x16x32_bf16 v[18:21], v[224:227], v[212:215], v[18:21]
	v_mfma_f32_16x16x32_bf16 v[22:25], v[228:231], v[212:215], v[22:25]
	v_mfma_f32_16x16x32_bf16 v[26:29], v[232:235], v[212:215], v[26:29]
	v_mfma_f32_16x16x32_bf16 v[30:33], v[236:239], v[212:215], v[30:33]
	s_waitcnt lgkmcnt(1)
	v_mfma_f32_16x16x32_bf16 v[34:37], v[224:227], v[216:219], v[34:37]
	v_mfma_f32_16x16x32_bf16 v[38:41], v[228:231], v[216:219], v[38:41]
	v_mfma_f32_16x16x32_bf16 v[42:45], v[232:235], v[216:219], v[42:45]
	v_mfma_f32_16x16x32_bf16 v[46:49], v[236:239], v[216:219], v[46:49]
	s_waitcnt lgkmcnt(0)
	v_mfma_f32_16x16x32_bf16 v[50:53], v[224:227], v[220:223], v[50:53]
	v_mfma_f32_16x16x32_bf16 v[54:57], v[228:231], v[220:223], v[54:57]
	v_mfma_f32_16x16x32_bf16 v[58:61], v[232:235], v[220:223], v[58:61]
	v_mfma_f32_16x16x32_bf16 v[62:65], v[236:239], v[220:223], v[62:65]
	s_waitcnt vmcnt(8)
	s_barrier
; #define BLOAD(A_, B_, kt) do { _Pragma("unroll") for (int i = 0; i < 4; ++i) { \
;     A_[i] = *(const u32x4*)((const char*)Ap + (aoff + (unsigned)(32 * i * lda + (kt) * 64) * 2u)); B_[i] = *(const u32x4*)((const char*)Wt + (woff + (unsigned)(32 * i * K + (kt) * 64) * 2u)); } } while (0)
; #define BLOAD(A_, B_, kt) do { _Pragma("unroll") for (int i = 0; i < 4; ++i) { \
;     A_[i] = *(const u32x4*)((const char*)Ap + (aoff + (unsigned)(32 * i * lda + (kt) * 64) * 2u)); B_[i] = *(const u32x4*)((const char*)Wt + (woff + (unsigned)(32 * i * K + (kt) * 64) * 2u)); } } while (0)
; #define BSTORE(A_, B_, buf) do { _Pragma("unroll") for (int i = 0; i < 4; ++i) { \
;     *(u32x4*)&As[(buf) * GBUF + (srow + 32 * i) * LDT + sc8] = A_[i]; \
;     *(u32x4*)&Bs[(buf) * GBUF + (srow + 32 * i) * LDT + sc8] = B_[i]; } } while (0)
; template <bool ROWNORM, int NK>
; DI void gemm_main_bf(const u16* __restrict__ Ap, int lda, const u16* __restrict__ Wt, f32x16 (&acc)[2][2], char* smem, float* rinv_s) {
;     ...
; #pragma unroll
;   for (int kt = 0; kt < nk; kt += 2) {
;     BCOMP(0);
;     BSTORE(a1, b1, 1);
;     if (kt + 3 < nk) BLOAD(a1, b1, kt + 3);
;     __syncthreads();
;     BCOMP(1);
;     if (kt + 2 < nk) { BSTORE(a0, b0, 0); if (kt + 4 < nk) BLOAD(a0, b0, kt + 4); }
;     __syncthreads();
	ds_read_b128 v[208:211], v240 offset:16384
	ds_read_b128 v[224:227], v241 offset:16384
	ds_read_b128 v[228:231], v241 offset:17408
	ds_read_b128 v[232:235], v241 offset:18432
	ds_read_b128 v[236:239], v241 offset:19456
	ds_read_b128 v[212:215], v240 offset:17408
	ds_read_b128 v[216:219], v240 offset:18432
	ds_read_b128 v[220:223], v240 offset:19456
	s_add_u32 m0, s52, 0x0
	s_add_u32 s28, s28, 0x40
	s_addc_u32 s29, s29, 0
	global_load_lds_dwordx4 v244, s[28:29]
	global_load_lds_dwordx4 v245, s[28:29] offset:1024
	s_add_u32 m0, s53, 0x0
	s_add_u32 s30, s30, 0x10000
	s_addc_u32 s31, s31, 0
	global_load_lds_dwordx4 v251, s[30:31]
	global_load_lds_dwordx4 v251, s[30:31] offset:1024
	s_waitcnt lgkmcnt(6)
	v_mfma_f32_16x16x32_bf16 v[2:5], v[224:227], v[208:211], v[2:5]
	s_waitcnt lgkmcnt(5)
	v_mfma_f32_16x16x32_bf16 v[6:9], v[228:231], v[208:211], v[6:9]
	s_waitcnt lgkmcnt(4)
	v_mfma_f32_16x16x32_bf16 v[10:13], v[232:235], v[208:211], v[10:13]
	s_waitcnt lgkmcnt(3)
	v_mfma_f32_16x16x32_bf16 v[14:17], v[236:239], v[208:211], v[14:17]
	s_waitcnt lgkmcnt(2)
	v_mfma_f32_16x16x32_bf16 v[18:21], v[224:227], v[212:215], v[18:21]
	v_mfma_f32_16x16x32_bf16 v[22:25], v[228:231], v[212:215], v[22:25]
	v_mfma_f32_16x16x32_bf16 v[26:29], v[232:235], v[212:215], v[26:29]
	v_mfma_f32_16x16x32_bf16 v[30:33], v[236:239], v[212:215], v[30:33]
	s_waitcnt lgkmcnt(1)
	v_mfma_f32_16x16x32_bf16 v[34:37], v[224:227], v[216:219], v[34:37]
	v_mfma_f32_16x16x32_bf16 v[38:41], v[228:231], v[216:219], v[38:41]
	v_mfma_f32_16x16x32_bf16 v[42:45], v[232:235], v[216:219], v[42:45]
	v_mfma_f32_16x16x32_bf16 v[46:49], v[236:239], v[216:219], v[46:49]
	s_waitcnt lgkmcnt(0)
	v_mfma_f32_16x16x32_bf16 v[50:53], v[224:227], v[220:223], v[50:53]
	v_mfma_f32_16x16x32_bf16 v[54:57], v[228:231], v[220:223], v[54:57]
	v_mfma_f32_16x16x32_bf16 v[58:61], v[232:235], v[220:223], v[58:61]
	v_mfma_f32_16x16x32_bf16 v[62:65], v[236:239], v[220:223], v[62:65]
	s_waitcnt vmcnt(8)
	s_barrier
	ds_read_b128 v[208:211], v240 offset:32768
	ds_read_b128 v[224:227], v241 offset:32768
	ds_read_b128 v[228:231], v241 offset:33792
	ds_read_b128 v[232:235], v241 offset:34816
	ds_read_b128 v[236:239], v241 offset:35840
	ds_read_b128 v[212:215], v240 offset:33792
	ds_read_b128 v[216:219], v240 offset:34816
	ds_read_b128 v[220:223], v240 offset:35840
	s_add_u32 m0, s52, 0x4000
	s_add_u32 s28, s28, 0x40
	s_addc_u32 s29, s29, 0
	global_load_lds_dwordx4 v244, s[28:29]
	global_load_lds_dwordx4 v245, s[28:29] offset:1024
	s_add_u32 m0, s53, 0x4000
	s_add_u32 s30, s30, 0x10000
	s_addc_u32 s31, s31, 0
	global_load_lds_dwordx4 v251, s[30:31]
	global_load_lds_dwordx4 v251, s[30:31] offset:1024
	s_waitcnt lgkmcnt(6)
	v_mfma_f32_16x16x32_bf16 v[2:5], v[224:227], v[208:211], v[2:5]
	s_waitcnt lgkmcnt(5)
	v_mfma_f32_16x16x32_bf16 v[6:9], v[228:231], v[208:211], v[6:9]
	s_waitcnt lgkmcnt(4)
	v_mfma_f32_16x16x32_bf16 v[10:13], v[232:235], v[208:211], v[10:13]
	s_waitcnt lgkmcnt(3)
	v_mfma_f32_16x16x32_bf16 v[14:17], v[236:239], v[208:211], v[14:17]
	s_waitcnt lgkmcnt(2)
	v_mfma_f32_16x16x32_bf16 v[18:21], v[224:227], v[212:215], v[18:21]
	v_mfma_f32_16x16x32_bf16 v[22:25], v[228:231], v[212:215], v[22:25]
	v_mfma_f32_16x16x32_bf16 v[26:29], v[232:235], v[212:215], v[26:29]
	v_mfma_f32_16x16x32_bf16 v[30:33], v[236:239], v[212:215], v[30:33]
	s_waitcnt lgkmcnt(1)
	v_mfma_f32_16x16x32_bf16 v[34:37], v[224:227], v[216:219], v[34:37]
	v_mfma_f32_16x16x32_bf16 v[38:41], v[228:231], v[216:219], v[38:41]
	v_mfma_f32_16x16x32_bf16 v[42:45], v[232:235], v[216:219], v[42:45]
	v_mfma_f32_16x16x32_bf16 v[46:49], v[236:239], v[216:219], v[46:49]
	s_waitcnt lgkmcnt(0)
	v_mfma_f32_16x16x32_bf16 v[50:53], v[224:227], v[220:223], v[50:53]
	v_mfma_f32_16x16x32_bf16 v[54:57], v[228:231], v[220:223], v[54:57]
	v_mfma_f32_16x16x32_bf16 v[58:61], v[232:235], v[220:223], v[58:61]
	v_mfma_f32_16x16x32_bf16 v[62:65], v[236:239], v[220:223], v[62:65]
	s_waitcnt vmcnt(8)
	s_barrier
	ds_read_b128 v[208:211], v240 offset:49152
	ds_read_b128 v[224:227], v241 offset:49152
	ds_read_b128 v[228:231], v241 offset:50176
	ds_read_b128 v[232:235], v241 offset:51200
	ds_read_b128 v[236:239], v241 offset:52224
	ds_read_b128 v[212:215], v240 offset:50176
	ds_read_b128 v[216:219], v240 offset:51200
	ds_read_b128 v[220:223], v240 offset:52224
	s_add_u32 m0, s52, 0x8000
	s_add_u32 s28, s28, 0x40
	s_addc_u32 s29, s29, 0
	global_load_lds_dwordx4 v244, s[28:29]
	global_load_lds_dwordx4 v245, s[28:29] offset:1024
	s_add_u32 m0, s53, 0x8000
	s_add_u32 s30, s30, 0x10000
	s_addc_u32 s31, s31, 0
	global_load_lds_dwordx4 v251, s[30:31]
	global_load_lds_dwordx4 v251, s[30:31] offset:1024
	s_waitcnt lgkmcnt(6)
	v_mfma_f32_16x16x32_bf16 v[2:5], v[224:227], v[208:211], v[2:5]
	s_waitcnt lgkmcnt(5)
	v_mfma_f32_16x16x32_bf16 v[6:9], v[228:231], v[208:211], v[6:9]
	s_waitcnt lgkmcnt(4)
	v_mfma_f32_16x16x32_bf16 v[10:13], v[232:235], v[208:211], v[10:13]
	s_waitcnt lgkmcnt(3)
	v_mfma_f32_16x16x32_bf16 v[14:17], v[236:239], v[208:211], v[14:17]
	s_waitcnt lgkmcnt(2)
	v_mfma_f32_16x16x32_bf16 v[18:21], v[224:227], v[212:215], v[18:21]
	v_mfma_f32_16x16x32_bf16 v[22:25], v[228:231], v[212:215], v[22:25]
	v_mfma_f32_16x16x32_bf16 v[26:29], v[232:235], v[212:215], v[26:29]
	v_mfma_f32_16x16x32_bf16 v[30:33], v[236:239], v[212:215], v[30:33]
	s_waitcnt lgkmcnt(1)
	v_mfma_f32_16x16x32_bf16 v[34:37], v[224:227], v[216:219], v[34:37]
	v_mfma_f32_16x16x32_bf16 v[38:41], v[228:231], v[216:219], v[38:41]
	v_mfma_f32_16x16x32_bf16 v[42:45], v[232:235], v[216:219], v[42:45]
	v_mfma_f32_16x16x32_bf16 v[46:49], v[236:239], v[216:219], v[46:49]
	s_waitcnt lgkmcnt(0)
	v_mfma_f32_16x16x32_bf16 v[50:53], v[224:227], v[220:223], v[50:53]
	v_mfma_f32_16x16x32_bf16 v[54:57], v[228:231], v[220:223], v[54:57]
	v_mfma_f32_16x16x32_bf16 v[58:61], v[232:235], v[220:223], v[58:61]
	v_mfma_f32_16x16x32_bf16 v[62:65], v[236:239], v[220:223], v[62:65]
	s_sub_u32 s74, s74, 1
	s_cmp_lg_u32 s74, 0
	s_cbranch_scc1 .Lbr_proj_k
; #define BLOAD(A_, B_, kt) do { _Pragma("unroll") for (int i = 0; i < 4; ++i) { \
;     A_[i] = *(const u32x4*)((const char*)Ap + (aoff + (unsigned)(32 * i * lda + (kt) * 64) * 2u)); B_[i] = *(const u32x4*)((const char*)Wt + (woff + (unsigned)(32 * i * K + (kt) * 64) * 2u)); } } while (0)
; #define BLOAD(A_, B_, kt) do { _Pragma("unroll") for (int i = 0; i < 4; ++i) { \
;     A_[i] = *(const u32x4*)((const char*)Ap + (aoff + (unsigned)(32 * i * lda + (kt) * 64) * 2u)); B_[i] = *(const u32x4*)((const char*)Wt + (woff + (unsigned)(32 * i * K + (kt) * 64) * 2u)); } } while (0)
; #define BSTORE(A_, B_, buf) do { _Pragma("unroll") for (int i = 0; i < 4; ++i) { \
;     *(u32x4*)&As[(buf) * GBUF + (srow + 32 * i) * LDT + sc8] = A_[i]; \
;     *(u32x4*)&Bs[(buf) * GBUF + (srow + 32 * i) * LDT + sc8] = B_[i]; } } while (0)
; template <bool ROWNORM, int NK>
; DI void gemm_main_bf(const u16* __restrict__ Ap, int lda, const u16* __restrict__ Wt, f32x16 (&acc)[2][2], char* smem, float* rinv_s) {
;     ...
; #pragma unroll
;   for (int kt = 0; kt < nk; kt += 2) {
;     BCOMP(0);
;     BSTORE(a1, b1, 1);
;     if (kt + 3 < nk) BLOAD(a1, b1, kt + 3);
;     __syncthreads();
;     BCOMP(1);
;     if (kt + 2 < nk) { BSTORE(a0, b0, 0); if (kt + 4 < nk) BLOAD(a0, b0, kt + 4); }
;     __syncthreads();
	s_waitcnt vmcnt(8)
	s_barrier
	ds_read_b128 v[208:211], v240 offset:0
	ds_read_b128 v[224:227], v241 offset:0
	ds_read_b128 v[228:231], v241 offset:1024
	ds_read_b128 v[232:235], v241 offset:2048
	ds_read_b128 v[236:239], v241 offset:3072
	ds_read_b128 v[212:215], v240 offset:1024
	ds_read_b128 v[216:219], v240 offset:2048
	ds_read_b128 v[220:223], v240 offset:3072
	s_add_u32 m0, s52, 0xc000
	s_add_u32 s28, s28, 0x40
	s_addc_u32 s29, s29, 0
	global_load_lds_dwordx4 v244, s[28:29]
	global_load_lds_dwordx4 v245, s[28:29] offset:1024
	s_add_u32 m0, s53, 0xc000
	s_add_u32 s30, s30, 0x10000
	s_addc_u32 s31, s31, 0
	global_load_lds_dwordx4 v251, s[30:31]
	global_load_lds_dwordx4 v251, s[30:31] offset:1024
	s_waitcnt lgkmcnt(6)
	v_mfma_f32_16x16x32_bf16 v[2:5], v[224:227], v[208:211], v[2:5]
	s_waitcnt lgkmcnt(5)
	v_mfma_f32_16x16x32_bf16 v[6:9], v[228:231], v[208:211], v[6:9]
	s_waitcnt lgkmcnt(4)
	v_mfma_f32_16x16x32_bf16 v[10:13], v[232:235], v[208:211], v[10:13]
	s_waitcnt lgkmcnt(3)
	v_mfma_f32_16x16x32_bf16 v[14:17], v[236:239], v[208:211], v[14:17]
	s_waitcnt lgkmcnt(2)
	v_mfma_f32_16x16x32_bf16 v[18:21], v[224:227], v[212:215], v[18:21]
	v_mfma_f32_16x16x32_bf16 v[22:25], v[228:231], v[212:215], v[22:25]
	v_mfma_f32_16x16x32_bf16 v[26:29], v[232:235], v[212:215], v[26:29]
	v_mfma_f32_16x16x32_bf16 v[30:33], v[236:239], v[212:215], v[30:33]
	s_waitcnt lgkmcnt(1)
	v_mfma_f32_16x16x32_bf16 v[34:37], v[224:227], v[216:219], v[34:37]
	v_mfma_f32_16x16x32_bf16 v[38:41], v[228:231], v[216:219], v[38:41]
	v_mfma_f32_16x16x32_bf16 v[42:45], v[232:235], v[216:219], v[42:45]
	v_mfma_f32_16x16x32_bf16 v[46:49], v[236:239], v[216:219], v[46:49]
	s_waitcnt lgkmcnt(0)
	v_mfma_f32_16x16x32_bf16 v[50:53], v[224:227], v[220:223], v[50:53]
	v_mfma_f32_16x16x32_bf16 v[54:57], v[228:231], v[220:223], v[54:57]
	v_mfma_f32_16x16x32_bf16 v[58:61], v[232:235], v[220:223], v[58:61]
	v_mfma_f32_16x16x32_bf16 v[62:65], v[236:239], v[220:223], v[62:65]
	s_waitcnt vmcnt(8)
	s_barrier
	ds_read_b128 v[208:211], v240 offset:16384
	ds_read_b128 v[224:227], v241 offset:16384
	ds_read_b128 v[228:231], v241 offset:17408
	ds_read_b128 v[232:235], v241 offset:18432
	ds_read_b128 v[236:239], v241 offset:19456
	ds_read_b128 v[212:215], v240 offset:17408
	ds_read_b128 v[216:219], v240 offset:18432
	ds_read_b128 v[220:223], v240 offset:19456
	s_waitcnt lgkmcnt(6)
	v_mfma_f32_16x16x32_bf16 v[2:5], v[224:227], v[208:211], v[2:5]
	s_waitcnt lgkmcnt(5)
	v_mfma_f32_16x16x32_bf16 v[6:9], v[228:231], v[208:211], v[6:9]
	s_waitcnt lgkmcnt(4)
	v_mfma_f32_16x16x32_bf16 v[10:13], v[232:235], v[208:211], v[10:13]
	s_waitcnt lgkmcnt(3)
	v_mfma_f32_16x16x32_bf16 v[14:17], v[236:239], v[208:211], v[14:17]
	s_waitcnt lgkmcnt(2)
	v_mfma_f32_16x16x32_bf16 v[18:21], v[224:227], v[212:215], v[18:21]
	v_mfma_f32_16x16x32_bf16 v[22:25], v[228:231], v[212:215], v[22:25]
	v_mfma_f32_16x16x32_bf16 v[26:29], v[232:235], v[212:215], v[26:29]
	v_mfma_f32_16x16x32_bf16 v[30:33], v[236:239], v[212:215], v[30:33]
	s_waitcnt lgkmcnt(1)
	v_mfma_f32_16x16x32_bf16 v[34:37], v[224:227], v[216:219], v[34:37]
	v_mfma_f32_16x16x32_bf16 v[38:41], v[228:231], v[216:219], v[38:41]
	v_mfma_f32_16x16x32_bf16 v[42:45], v[232:235], v[216:219], v[42:45]
	v_mfma_f32_16x16x32_bf16 v[46:49], v[236:239], v[216:219], v[46:49]
	s_waitcnt lgkmcnt(0)
	v_mfma_f32_16x16x32_bf16 v[50:53], v[224:227], v[220:223], v[50:53]
	v_mfma_f32_16x16x32_bf16 v[54:57], v[228:231], v[220:223], v[54:57]
	v_mfma_f32_16x16x32_bf16 v[58:61], v[232:235], v[220:223], v[58:61]
	v_mfma_f32_16x16x32_bf16 v[62:65], v[236:239], v[220:223], v[62:65]
	s_waitcnt vmcnt(4)
	s_barrier
	ds_read_b128 v[208:211], v240 offset:32768
	ds_read_b128 v[224:227], v241 offset:32768
	ds_read_b128 v[228:231], v241 offset:33792
	ds_read_b128 v[232:235], v241 offset:34816
	ds_read_b128 v[236:239], v241 offset:35840
	ds_read_b128 v[212:215], v240 offset:33792
	ds_read_b128 v[216:219], v240 offset:34816
	ds_read_b128 v[220:223], v240 offset:35840
	s_waitcnt lgkmcnt(6)
	v_mfma_f32_16x16x32_bf16 v[2:5], v[224:227], v[208:211], v[2:5]
	s_waitcnt lgkmcnt(5)
	v_mfma_f32_16x16x32_bf16 v[6:9], v[228:231], v[208:211], v[6:9]
	s_waitcnt lgkmcnt(4)
	v_mfma_f32_16x16x32_bf16 v[10:13], v[232:235], v[208:211], v[10:13]
	s_waitcnt lgkmcnt(3)
	v_mfma_f32_16x16x32_bf16 v[14:17], v[236:239], v[208:211], v[14:17]
	s_waitcnt lgkmcnt(2)
	v_mfma_f32_16x16x32_bf16 v[18:21], v[224:227], v[212:215], v[18:21]
	v_mfma_f32_16x16x32_bf16 v[22:25], v[228:231], v[212:215], v[22:25]
	v_mfma_f32_16x16x32_bf16 v[26:29], v[232:235], v[212:215], v[26:29]
	v_mfma_f32_16x16x32_bf16 v[30:33], v[236:239], v[212:215], v[30:33]
	s_waitcnt lgkmcnt(1)
	v_mfma_f32_16x16x32_bf16 v[34:37], v[224:227], v[216:219], v[34:37]
	v_mfma_f32_16x16x32_bf16 v[38:41], v[228:231], v[216:219], v[38:41]
	v_mfma_f32_16x16x32_bf16 v[42:45], v[232:235], v[216:219], v[42:45]
	v_mfma_f32_16x16x32_bf16 v[46:49], v[236:239], v[216:219], v[46:49]
	s_waitcnt lgkmcnt(0)
	v_mfma_f32_16x16x32_bf16 v[50:53], v[224:227], v[220:223], v[50:53]
	v_mfma_f32_16x16x32_bf16 v[54:57], v[228:231], v[220:223], v[54:57]
	v_mfma_f32_16x16x32_bf16 v[58:61], v[232:235], v[220:223], v[58:61]
	v_mfma_f32_16x16x32_bf16 v[62:65], v[236:239], v[220:223], v[62:65]
	s_waitcnt vmcnt(0)
	s_barrier
; DI unsigned pk2(float a, float b) { f2_t v = {a, b}; bf2_t r = __builtin_convertvector(v, bf2_t); return __builtin_bit_cast(unsigned, r); }
; #define BLOAD(A_, B_, kt) do { _Pragma("unroll") for (int i = 0; i < 4; ++i) { \
;     A_[i] = *(const u32x4*)((const char*)Ap + (aoff + (unsigned)(32 * i * lda + (kt) * 64) * 2u)); B_[i] = *(const u32x4*)((const char*)Wt + (woff + (unsigned)(32 * i * K + (kt) * 64) * 2u)); } } while (0)
; #define BLOAD(A_, B_, kt) do { _Pragma("unroll") for (int i = 0; i < 4; ++i) { \
;     A_[i] = *(const u32x4*)((const char*)Ap + (aoff + (unsigned)(32 * i * lda + (kt) * 64) * 2u)); B_[i] = *(const u32x4*)((const char*)Wt + (woff + (unsigned)(32 * i * K + (kt) * 64) * 2u)); } } while (0)
; #define BSTORE(A_, B_, buf) do { _Pragma("unroll") for (int i = 0; i < 4; ++i) { \
;     *(u32x4*)&As[(buf) * GBUF + (srow + 32 * i) * LDT + sc8] = A_[i]; \
;     *(u32x4*)&Bs[(buf) * GBUF + (srow + 32 * i) * LDT + sc8] = B_[i]; } } while (0)
; template <bool ROWNORM, int NK>
; DI void gemm_main_bf(const u16* __restrict__ Ap, int lda, const u16* __restrict__ Wt, f32x16 (&acc)[2][2], char* smem, float* rinv_s) {
;     ...
; #pragma unroll
;   for (int kt = 0; kt < nk; kt += 2) {
;     BCOMP(0);
;     BSTORE(a1, b1, 1);
;     if (kt + 3 < nk) BLOAD(a1, b1, kt + 3);
;     __syncthreads();
;     BCOMP(1);
;     if (kt + 2 < nk) { BSTORE(a0, b0, 0); if (kt + 4 < nk) BLOAD(a0, b0, kt + 4); }
;     __syncthreads();
; DI void tile_branch(const Params& p, int l, int tile, char* smem) {
;     ...
; #pragma unroll
;     for (int mt = 0; mt < 2; ++mt)
; #pragma unroll
;       for (int nt = 0; nt < 2; ++nt)
; #pragma unroll
;         for (int i = 0; i < 8; ++i) {
;           const float g0 = __uint_as_float(gpk[mt][nt][i] << 16), g1 = __uint_as_float(gpk[mt][nt][i] & 0xffff0000u);
;           const float a = __uint_as_float(upk[mt][nt][i] << 16) + g0 * acc[mt][nt][2 * i];
;           const float b = __uint_as_float(upk[mt][nt][i] & 0xffff0000u) + g1 * acc[mt][nt][2 * i + 1];
;           upk[mt][nt][i] = pk2(a, b);
;         }
	ds_read_b128 v[208:211], v240 offset:49152
	ds_read_b128 v[224:227], v241 offset:49152
	ds_read_b128 v[228:231], v241 offset:50176
	ds_read_b128 v[232:235], v241 offset:51200
	ds_read_b128 v[236:239], v241 offset:52224
	ds_read_b128 v[212:215], v240 offset:50176
	ds_read_b128 v[216:219], v240 offset:51200
	ds_read_b128 v[220:223], v240 offset:52224
	s_waitcnt lgkmcnt(6)
	v_mfma_f32_16x16x32_bf16 v[2:5], v[224:227], v[208:211], v[2:5]
	s_waitcnt lgkmcnt(5)
	v_mfma_f32_16x16x32_bf16 v[6:9], v[228:231], v[208:211], v[6:9]
	s_waitcnt lgkmcnt(4)
	v_mfma_f32_16x16x32_bf16 v[10:13], v[232:235], v[208:211], v[10:13]
	s_waitcnt lgkmcnt(3)
	v_mfma_f32_16x16x32_bf16 v[14:17], v[236:239], v[208:211], v[14:17]
	s_waitcnt lgkmcnt(2)
	v_mfma_f32_16x16x32_bf16 v[18:21], v[224:227], v[212:215], v[18:21]
	v_mfma_f32_16x16x32_bf16 v[22:25], v[228:231], v[212:215], v[22:25]
	v_mfma_f32_16x16x32_bf16 v[26:29], v[232:235], v[212:215], v[26:29]
	v_mfma_f32_16x16x32_bf16 v[30:33], v[236:239], v[212:215], v[30:33]
	s_waitcnt lgkmcnt(1)
	v_mfma_f32_16x16x32_bf16 v[34:37], v[224:227], v[216:219], v[34:37]
	v_mfma_f32_16x16x32_bf16 v[38:41], v[228:231], v[216:219], v[38:41]
	v_mfma_f32_16x16x32_bf16 v[42:45], v[232:235], v[216:219], v[42:45]
	v_mfma_f32_16x16x32_bf16 v[46:49], v[236:239], v[216:219], v[46:49]
	s_waitcnt lgkmcnt(0)
	v_mfma_f32_16x16x32_bf16 v[50:53], v[224:227], v[220:223], v[50:53]
	v_mfma_f32_16x16x32_bf16 v[54:57], v[228:231], v[220:223], v[54:57]
	v_mfma_f32_16x16x32_bf16 v[58:61], v[232:235], v[220:223], v[58:61]
	v_mfma_f32_16x16x32_bf16 v[62:65], v[236:239], v[220:223], v[62:65]
	s_add_u32 s46, s46, 0x10000
	s_addc_u32 s47, s47, 0
	s_add_u32 s48, s48, 0x1000000
	s_addc_u32 s49, s49, 0
	s_add_u32 s50, s50, 0x100000
	s_addc_u32 s51, s51, 0
	v_lshlrev_b32_e32 v166, 16, v130
	v_and_b32_e32 v167, 0xffff0000, v130
	v_lshlrev_b32_e32 v168, 16, v131
	v_and_b32_e32 v169, 0xffff0000, v131
	v_fmac_f32_e32 v66, v166, v2
	v_fmac_f32_e32 v67, v167, v3
	v_fmac_f32_e32 v68, v168, v4
	v_fmac_f32_e32 v69, v169, v5
	v_lshlrev_b32_e32 v166, 16, v132
	v_and_b32_e32 v167, 0xffff0000, v132
	v_lshlrev_b32_e32 v168, 16, v133
	v_and_b32_e32 v169, 0xffff0000, v133
	v_fmac_f32_e32 v70, v166, v6
	v_fmac_f32_e32 v71, v167, v7
	v_fmac_f32_e32 v72, v168, v8
	v_fmac_f32_e32 v73, v169, v9
	v_lshlrev_b32_e32 v166, 16, v134
	v_and_b32_e32 v167, 0xffff0000, v134
	v_lshlrev_b32_e32 v168, 16, v135
	v_and_b32_e32 v169, 0xffff0000, v135
	v_fmac_f32_e32 v74, v166, v10
	v_fmac_f32_e32 v75, v167, v11
	v_fmac_f32_e32 v76, v168, v12
	v_fmac_f32_e32 v77, v169, v13
	v_lshlrev_b32_e32 v166, 16, v136
	v_and_b32_e32 v167, 0xffff0000, v136
	v_lshlrev_b32_e32 v168, 16, v137
	v_and_b32_e32 v169, 0xffff0000, v137
	v_fmac_f32_e32 v78, v166, v14
	v_fmac_f32_e32 v79, v167, v15
	v_fmac_f32_e32 v80, v168, v16
	v_fmac_f32_e32 v81, v169, v17
	v_lshlrev_b32_e32 v166, 16, v138
	v_and_b32_e32 v167, 0xffff0000, v138
	v_lshlrev_b32_e32 v168, 16, v139
	v_and_b32_e32 v169, 0xffff0000, v139
	v_fmac_f32_e32 v82, v166, v18
	v_fmac_f32_e32 v83, v167, v19
	v_fmac_f32_e32 v84, v168, v20
	v_fmac_f32_e32 v85, v169, v21
	v_lshlrev_b32_e32 v166, 16, v140
	v_and_b32_e32 v167, 0xffff0000, v140
	v_lshlrev_b32_e32 v168, 16, v141
	v_and_b32_e32 v169, 0xffff0000, v141
	v_fmac_f32_e32 v86, v166, v22
	v_fmac_f32_e32 v87, v167, v23
	v_fmac_f32_e32 v88, v168, v24
	v_fmac_f32_e32 v89, v169, v25
	v_lshlrev_b32_e32 v166, 16, v142
	v_and_b32_e32 v167, 0xffff0000, v142
	v_lshlrev_b32_e32 v168, 16, v143
	v_and_b32_e32 v169, 0xffff0000, v143
	v_fmac_f32_e32 v90, v166, v26
	v_fmac_f32_e32 v91, v167, v27
	v_fmac_f32_e32 v92, v168, v28
	v_fmac_f32_e32 v93, v169, v29
	v_lshlrev_b32_e32 v166, 16, v144
	v_and_b32_e32 v167, 0xffff0000, v144
	v_lshlrev_b32_e32 v168, 16, v145
	v_and_b32_e32 v169, 0xffff0000, v145
	v_fmac_f32_e32 v94, v166, v30
	v_fmac_f32_e32 v95, v167, v31
	v_fmac_f32_e32 v96, v168, v32
	v_fmac_f32_e32 v97, v169, v33
	v_lshlrev_b32_e32 v166, 16, v146
	v_and_b32_e32 v167, 0xffff0000, v146
	v_lshlrev_b32_e32 v168, 16, v147
	v_and_b32_e32 v169, 0xffff0000, v147
	v_fmac_f32_e32 v98, v166, v34
	v_fmac_f32_e32 v99, v167, v35
	v_fmac_f32_e32 v100, v168, v36
	v_fmac_f32_e32 v101, v169, v37
	v_lshlrev_b32_e32 v166, 16, v148
	v_and_b32_e32 v167, 0xffff0000, v148
	v_lshlrev_b32_e32 v168, 16, v149
	v_and_b32_e32 v169, 0xffff0000, v149
	v_fmac_f32_e32 v102, v166, v38
	v_fmac_f32_e32 v103, v167, v39
	v_fmac_f32_e32 v104, v168, v40
	v_fmac_f32_e32 v105, v169, v41
	v_lshlrev_b32_e32 v166, 16, v150
	v_and_b32_e32 v167, 0xffff0000, v150
	v_lshlrev_b32_e32 v168, 16, v151
	v_and_b32_e32 v169, 0xffff0000, v151
	v_fmac_f32_e32 v106, v166, v42
	v_fmac_f32_e32 v107, v167, v43
	v_fmac_f32_e32 v108, v168, v44
	v_fmac_f32_e32 v109, v169, v45
	v_lshlrev_b32_e32 v166, 16, v152
	v_and_b32_e32 v167, 0xffff0000, v152
	v_lshlrev_b32_e32 v168, 16, v153
	v_and_b32_e32 v169, 0xffff0000, v153
	v_fmac_f32_e32 v110, v166, v46
	v_fmac_f32_e32 v111, v167, v47
	v_fmac_f32_e32 v112, v168, v48
	v_fmac_f32_e32 v113, v169, v49
	v_lshlrev_b32_e32 v166, 16, v154
	v_and_b32_e32 v167, 0xffff0000, v154
	v_lshlrev_b32_e32 v168, 16, v155
	v_and_b32_e32 v169, 0xffff0000, v155
	v_fmac_f32_e32 v114, v166, v50
	v_fmac_f32_e32 v115, v167, v51
	v_fmac_f32_e32 v116, v168, v52
	v_fmac_f32_e32 v117, v169, v53
	v_lshlrev_b32_e32 v166, 16, v156
	v_and_b32_e32 v167, 0xffff0000, v156
	v_lshlrev_b32_e32 v168, 16, v157
	v_and_b32_e32 v169, 0xffff0000, v157
	v_fmac_f32_e32 v118, v166, v54
	v_fmac_f32_e32 v119, v167, v55
	v_fmac_f32_e32 v120, v168, v56
	v_fmac_f32_e32 v121, v169, v57
	v_lshlrev_b32_e32 v166, 16, v158
	v_and_b32_e32 v167, 0xffff0000, v158
	v_lshlrev_b32_e32 v168, 16, v159
	v_and_b32_e32 v169, 0xffff0000, v159
	v_fmac_f32_e32 v122, v166, v58
	v_fmac_f32_e32 v123, v167, v59
	v_fmac_f32_e32 v124, v168, v60
	v_fmac_f32_e32 v125, v169, v61
	v_lshlrev_b32_e32 v166, 16, v160
	v_and_b32_e32 v167, 0xffff0000, v160
	v_lshlrev_b32_e32 v168, 16, v161
	v_and_b32_e32 v169, 0xffff0000, v161
	v_fmac_f32_e32 v126, v166, v62
	v_fmac_f32_e32 v127, v167, v63
	v_fmac_f32_e32 v128, v168, v64
	v_fmac_f32_e32 v129, v169, v65
	s_cmp_eq_u32 s75, 2
	s_cbranch_scc1 .Lbr_noprol
; #define BLOAD(A_, B_, kt) do { _Pragma("unroll") for (int i = 0; i < 4; ++i) { \
;     A_[i] = *(const u32x4*)((const char*)Ap + (aoff + (unsigned)(32 * i * lda + (kt) * 64) * 2u)); B_[i] = *(const u32x4*)((const char*)Wt + (woff + (unsigned)(32 * i * K + (kt) * 64) * 2u)); } } while (0)
; #define BLOAD(A_, B_, kt) do { _Pragma("unroll") for (int i = 0; i < 4; ++i) { \
;     A_[i] = *(const u32x4*)((const char*)Ap + (aoff + (unsigned)(32 * i * lda + (kt) * 64) * 2u)); B_[i] = *(const u32x4*)((const char*)Wt + (woff + (unsigned)(32 * i * K + (kt) * 64) * 2u)); } } while (0)
; #define BSTORE(A_, B_, buf) do { _Pragma("unroll") for (int i = 0; i < 4; ++i) { \
;     *(u32x4*)&As[(buf) * GBUF + (srow + 32 * i) * LDT + sc8] = A_[i]; \
;     *(u32x4*)&Bs[(buf) * GBUF + (srow + 32 * i) * LDT + sc8] = B_[i]; } } while (0)
; template <bool ROWNORM, int NK>
; DI void gemm_main_bf(const u16* __restrict__ Ap, int lda, const u16* __restrict__ Wt, f32x16 (&acc)[2][2], char* smem, float* rinv_s) {
;     ...
;   BLOAD(a0, b0, 0); BLOAD(a1, b1, 1);
;   __syncthreads();
;   BSTORE(a0, b0, 0);
;   BLOAD(a0, b0, 2);
;   __syncthreads();
; DI void tile_branch(const Params& p, int l, int tile, char* smem) {
;     ...
;   for (int br = 0; br < 3; ++br) {
;     unsigned gpk[2][2][8];
;     {
;       f32x16 accg[2][2]; zero_acc(accg);
;       gemm_main_bf<false, 16>((const u16*)(p.ws + OFF_XB) + (size_t)m0 * 1024, 1024,
;                               (const u16*)(p.ws + OFF_WIN + l * SZ_WIN) + (size_t)(5760 + br * 1024 + n0) * 1024, accg, smem, nullptr);
	s_mov_b64 s[28:29], s[44:45]
	s_mov_b64 s[30:31], s[46:47]
	s_add_u32 m0, s52, 0x0
	s_nop 0
	global_load_lds_dwordx4 v251, s[28:29]
	global_load_lds_dwordx4 v251, s[28:29] offset:1024
	s_add_u32 m0, s53, 0x0
	s_nop 0
	global_load_lds_dwordx4 v251, s[30:31]
	global_load_lds_dwordx4 v251, s[30:31] offset:1024
	s_add_u32 m0, s52, 0x4000
	s_add_u32 s28, s28, 0x100000
	s_addc_u32 s29, s29, 0
	global_load_lds_dwordx4 v251, s[28:29]
	global_load_lds_dwordx4 v251, s[28:29] offset:1024
	s_add_u32 m0, s53, 0x4000
	s_add_u32 s30, s30, 0x30000
	s_addc_u32 s31, s31, 0
	global_load_lds_dwordx4 v251, s[30:31]
	global_load_lds_dwordx4 v251, s[30:31] offset:1024
	s_add_u32 m0, s52, 0x8000
	s_add_u32 s28, s28, 0x100000
	s_addc_u32 s29, s29, 0
	global_load_lds_dwordx4 v251, s[28:29]
	global_load_lds_dwordx4 v251, s[28:29] offset:1024
	s_add_u32 m0, s53, 0x8000
	s_add_u32 s30, s30, 0x30000
	s_addc_u32 s31, s31, 0
	global_load_lds_dwordx4 v251, s[30:31]
	global_load_lds_dwordx4 v251, s[30:31] offset:1024

; #define BLOAD(A_, B_, kt) do { _Pragma("unroll") for (int i = 0; i < 4; ++i) { \
;     A_[i] = *(const u32x4*)((const char*)Ap + (aoff + (unsigned)(32 * i * lda + (kt) * 64) * 2u)); B_[i] = *(const u32x4*)((const char*)Wt + (woff + (unsigned)(32 * i * K + (kt) * 64) * 2u)); } } while (0)
; #define BLOAD(A_, B_, kt) do { _Pragma("unroll") for (int i = 0; i < 4; ++i) { \
;     A_[i] = *(const u32x4*)((const char*)Ap + (aoff + (unsigned)(32 * i * lda + (kt) * 64) * 2u)); B_[i] = *(const u32x4*)((const char*)Wt + (woff + (unsigned)(32 * i * K + (kt) * 64) * 2u)); } } while (0)
; #define BSTORE(A_, B_, buf) do { _Pragma("unroll") for (int i = 0; i < 4; ++i) { \
;     *(u32x4*)&As[(buf) * GBUF + (srow + 32 * i) * LDT + sc8] = A_[i]; \
;     *(u32x4*)&Bs[(buf) * GBUF + (srow + 32 * i) * LDT + sc8] = B_[i]; } } while (0)
; template <int NK>
; DI void gemm_run(PF& pf, const u16* __restrict__ Ap, int lda, const u16* __restrict__ Wt, f32x16 (&acc)[2][2], char* smem) {
;     ...
;   __builtin_amdgcn_s_setprio(0);
;   __syncthreads();
;   BSTORE(pf.a0, pf.b0, 0);
;   BLOAD(pf.a0, pf.b0, 2);
;   __syncthreads();
; #pragma unroll
;   for (int kt = 0; kt < nk; kt += 2) {
;     BCOMP(0);
;     BSTORE(pf.a1, pf.b1, 1);
;     if (kt + 3 < nk) BLOAD(pf.a1, pf.b1, kt + 3);
;     __syncthreads();
;     BCOMP(1);
;     if (kt + 2 < nk) { BSTORE(pf.a0, pf.b0, 0); if (kt + 4 < nk) BLOAD(pf.a0, pf.b0, kt + 4); }
;     __syncthreads();
.Linp_kloop:
	s_waitcnt vmcnt(6)
	s_barrier
	ds_read_b128 v[224:227], v126 offset:0
	ds_read_b128 v[240:243], v128 offset:0
	ds_read_b128 v[244:247], v128 offset:1024
	ds_read_b128 v[248:251], v128 offset:2048
	ds_read_b128 v[156:159], v128 offset:3072
	ds_read_b128 v[228:231], v126 offset:1024
	ds_read_b128 v[232:235], v126 offset:2048
	ds_read_b128 v[236:239], v126 offset:3072
	ds_read_b128 v[160:163], v128 offset:8192
	ds_read_b128 v[164:167], v128 offset:9216
	ds_read_b128 v[168:171], v128 offset:10240
	ds_read_b128 v[122:125], v128 offset:11264
	s_add_u32 m0, s46, 0xc000
	s_add_u32 s48, s48, 0x100000
	s_addc_u32 s49, s49, 0
	global_load_lds_dwordx4 v138, s[48:49]
	global_load_lds_dwordx4 v139, s[48:49] offset:1024
	s_add_u32 m0, s47, 0xc000
	s_add_u32 s50, s50, s13
	s_addc_u32 s51, s51, 0
	global_load_lds_dwordx4 v140, s[50:51]
	global_load_lds_dwordx4 v141, s[50:51] offset:1024
	global_load_lds_dwordx4 v142, s[50:51] offset:2048
	global_load_lds_dwordx4 v143, s[50:51] offset:3072
	s_waitcnt lgkmcnt(10)
	v_mfma_f32_16x16x32_bf16 v[2:5], v[224:227], v[240:243], v[2:5]
	s_waitcnt lgkmcnt(9)
	v_mfma_f32_16x16x32_bf16 v[6:9], v[224:227], v[244:247], v[6:9]
	s_waitcnt lgkmcnt(8)
	v_mfma_f32_16x16x32_bf16 v[10:13], v[224:227], v[248:251], v[10:13]
	s_waitcnt lgkmcnt(7)
	v_mfma_f32_16x16x32_bf16 v[14:17], v[224:227], v[156:159], v[14:17]
	s_waitcnt lgkmcnt(6)
	v_mfma_f32_16x16x32_bf16 v[18:21], v[228:231], v[240:243], v[18:21]
	v_mfma_f32_16x16x32_bf16 v[22:25], v[228:231], v[244:247], v[22:25]
	v_mfma_f32_16x16x32_bf16 v[26:29], v[228:231], v[248:251], v[26:29]
	v_mfma_f32_16x16x32_bf16 v[30:33], v[228:231], v[156:159], v[30:33]
	s_waitcnt lgkmcnt(5)
	v_mfma_f32_16x16x32_bf16 v[34:37], v[232:235], v[240:243], v[34:37]
	v_mfma_f32_16x16x32_bf16 v[38:41], v[232:235], v[244:247], v[38:41]
	v_mfma_f32_16x16x32_bf16 v[42:45], v[232:235], v[248:251], v[42:45]
	v_mfma_f32_16x16x32_bf16 v[46:49], v[232:235], v[156:159], v[46:49]
	s_waitcnt lgkmcnt(4)
	v_mfma_f32_16x16x32_bf16 v[50:53], v[236:239], v[240:243], v[50:53]
	v_mfma_f32_16x16x32_bf16 v[54:57], v[236:239], v[244:247], v[54:57]
	v_mfma_f32_16x16x32_bf16 v[58:61], v[236:239], v[248:251], v[58:61]
	v_mfma_f32_16x16x32_bf16 v[62:65], v[236:239], v[156:159], v[62:65]
	s_waitcnt lgkmcnt(3)
	v_mfma_f32_16x16x32_bf16 v[74:77], v[224:227], v[160:163], v[74:77]
	s_waitcnt lgkmcnt(2)
	v_mfma_f32_16x16x32_bf16 v[78:81], v[224:227], v[164:167], v[78:81]
	s_waitcnt lgkmcnt(1)
	v_mfma_f32_16x16x32_bf16 v[82:85], v[224:227], v[168:171], v[82:85]
	s_waitcnt lgkmcnt(0)
	v_mfma_f32_16x16x32_bf16 v[86:89], v[224:227], v[122:125], v[86:89]
	v_mfma_f32_16x16x32_bf16 v[90:93], v[228:231], v[160:163], v[90:93]
	v_mfma_f32_16x16x32_bf16 v[94:97], v[228:231], v[164:167], v[94:97]
	v_mfma_f32_16x16x32_bf16 v[98:101], v[228:231], v[168:171], v[98:101]
	v_mfma_f32_16x16x32_bf16 v[102:105], v[228:231], v[122:125], v[102:105]
	v_mfma_f32_16x16x32_bf16 v[106:109], v[232:235], v[160:163], v[106:109]
	v_mfma_f32_16x16x32_bf16 v[110:113], v[232:235], v[164:167], v[110:113]
	v_mfma_f32_16x16x32_bf16 v[114:117], v[232:235], v[168:171], v[114:117]
	v_mfma_f32_16x16x32_bf16 v[118:121], v[232:235], v[122:125], v[118:121]
	v_mfma_f32_16x16x32_bf16 v[208:211], v[236:239], v[160:163], v[208:211]
	v_mfma_f32_16x16x32_bf16 v[212:215], v[236:239], v[164:167], v[212:215]
	v_mfma_f32_16x16x32_bf16 v[216:219], v[236:239], v[168:171], v[216:219]
	v_mfma_f32_16x16x32_bf16 v[220:223], v[236:239], v[122:125], v[220:223]
	s_waitcnt vmcnt(6)
	s_barrier
	ds_read_b128 v[224:227], v126 offset:24576
	ds_read_b128 v[240:243], v128 offset:24576
	ds_read_b128 v[244:247], v128 offset:25600
	ds_read_b128 v[248:251], v128 offset:26624
	ds_read_b128 v[156:159], v128 offset:27648
	ds_read_b128 v[228:231], v126 offset:25600
	ds_read_b128 v[232:235], v126 offset:26624
	ds_read_b128 v[236:239], v126 offset:27648
	ds_read_b128 v[160:163], v128 offset:32768
	ds_read_b128 v[164:167], v128 offset:33792
	ds_read_b128 v[168:171], v128 offset:34816
	ds_read_b128 v[122:125], v128 offset:35840
	s_add_u32 m0, s46, 0x0
	s_add_u32 s48, s48, 0x100000
	s_addc_u32 s49, s49, 0
	global_load_lds_dwordx4 v138, s[48:49]
	global_load_lds_dwordx4 v139, s[48:49] offset:1024
	s_add_u32 m0, s47, 0x0
	s_add_u32 s50, s50, s13
	s_addc_u32 s51, s51, 0
	global_load_lds_dwordx4 v140, s[50:51]
	global_load_lds_dwordx4 v141, s[50:51] offset:1024
	global_load_lds_dwordx4 v142, s[50:51] offset:2048
	global_load_lds_dwordx4 v143, s[50:51] offset:3072
	s_waitcnt lgkmcnt(10)
	v_mfma_f32_16x16x32_bf16 v[2:5], v[224:227], v[240:243], v[2:5]
	s_waitcnt lgkmcnt(9)
	v_mfma_f32_16x16x32_bf16 v[6:9], v[224:227], v[244:247], v[6:9]
	s_waitcnt lgkmcnt(8)
	v_mfma_f32_16x16x32_bf16 v[10:13], v[224:227], v[248:251], v[10:13]
	s_waitcnt lgkmcnt(7)
	v_mfma_f32_16x16x32_bf16 v[14:17], v[224:227], v[156:159], v[14:17]
	s_waitcnt lgkmcnt(6)
	v_mfma_f32_16x16x32_bf16 v[18:21], v[228:231], v[240:243], v[18:21]
	v_mfma_f32_16x16x32_bf16 v[22:25], v[228:231], v[244:247], v[22:25]
	v_mfma_f32_16x16x32_bf16 v[26:29], v[228:231], v[248:251], v[26:29]
	v_mfma_f32_16x16x32_bf16 v[30:33], v[228:231], v[156:159], v[30:33]
	s_waitcnt lgkmcnt(5)
	v_mfma_f32_16x16x32_bf16 v[34:37], v[232:235], v[240:243], v[34:37]
	v_mfma_f32_16x16x32_bf16 v[38:41], v[232:235], v[244:247], v[38:41]
	v_mfma_f32_16x16x32_bf16 v[42:45], v[232:235], v[248:251], v[42:45]
	v_mfma_f32_16x16x32_bf16 v[46:49], v[232:235], v[156:159], v[46:49]
	s_waitcnt lgkmcnt(4)
	v_mfma_f32_16x16x32_bf16 v[50:53], v[236:239], v[240:243], v[50:53]
	v_mfma_f32_16x16x32_bf16 v[54:57], v[236:239], v[244:247], v[54:57]
	v_mfma_f32_16x16x32_bf16 v[58:61], v[236:239], v[248:251], v[58:61]
	v_mfma_f32_16x16x32_bf16 v[62:65], v[236:239], v[156:159], v[62:65]
	s_waitcnt lgkmcnt(3)
	v_mfma_f32_16x16x32_bf16 v[74:77], v[224:227], v[160:163], v[74:77]
	s_waitcnt lgkmcnt(2)
	v_mfma_f32_16x16x32_bf16 v[78:81], v[224:227], v[164:167], v[78:81]
	s_waitcnt lgkmcnt(1)
	v_mfma_f32_16x16x32_bf16 v[82:85], v[224:227], v[168:171], v[82:85]
	s_waitcnt lgkmcnt(0)
	v_mfma_f32_16x16x32_bf16 v[86:89], v[224:227], v[122:125], v[86:89]
	v_mfma_f32_16x16x32_bf16 v[90:93], v[228:231], v[160:163], v[90:93]
	v_mfma_f32_16x16x32_bf16 v[94:97], v[228:231], v[164:167], v[94:97]
	v_mfma_f32_16x16x32_bf16 v[98:101], v[228:231], v[168:171], v[98:101]
	v_mfma_f32_16x16x32_bf16 v[102:105], v[228:231], v[122:125], v[102:105]
	v_mfma_f32_16x16x32_bf16 v[106:109], v[232:235], v[160:163], v[106:109]
	v_mfma_f32_16x16x32_bf16 v[110:113], v[232:235], v[164:167], v[110:113]
	v_mfma_f32_16x16x32_bf16 v[114:117], v[232:235], v[168:171], v[114:117]
	v_mfma_f32_16x16x32_bf16 v[118:121], v[232:235], v[122:125], v[118:121]
	v_mfma_f32_16x16x32_bf16 v[208:211], v[236:239], v[160:163], v[208:211]
	v_mfma_f32_16x16x32_bf16 v[212:215], v[236:239], v[164:167], v[212:215]
	v_mfma_f32_16x16x32_bf16 v[216:219], v[236:239], v[168:171], v[216:219]
	v_mfma_f32_16x16x32_bf16 v[220:223], v[236:239], v[122:125], v[220:223]
	s_waitcnt vmcnt(6)
	s_barrier
; #define BLOAD(A_, B_, kt) do { _Pragma("unroll") for (int i = 0; i < 4; ++i) { \
;     A_[i] = *(const u32x4*)((const char*)Ap + (aoff + (unsigned)(32 * i * lda + (kt) * 64) * 2u)); B_[i] = *(const u32x4*)((const char*)Wt + (woff + (unsigned)(32 * i * K + (kt) * 64) * 2u)); } } while (0)
; #define BLOAD(A_, B_, kt) do { _Pragma("unroll") for (int i = 0; i < 4; ++i) { \
;     A_[i] = *(const u32x4*)((const char*)Ap + (aoff + (unsigned)(32 * i * lda + (kt) * 64) * 2u)); B_[i] = *(const u32x4*)((const char*)Wt + (woff + (unsigned)(32 * i * K + (kt) * 64) * 2u)); } } while (0)
; #define BSTORE(A_, B_, buf) do { _Pragma("unroll") for (int i = 0; i < 4; ++i) { \
;     *(u32x4*)&As[(buf) * GBUF + (srow + 32 * i) * LDT + sc8] = A_[i]; \
;     *(u32x4*)&Bs[(buf) * GBUF + (srow + 32 * i) * LDT + sc8] = B_[i]; } } while (0)
; template <int NK>
; DI void gemm_run(PF& pf, const u16* __restrict__ Ap, int lda, const u16* __restrict__ Wt, f32x16 (&acc)[2][2], char* smem) {
;     ...
;   __builtin_amdgcn_s_setprio(0);
;   __syncthreads();
;   BSTORE(pf.a0, pf.b0, 0);
;   BLOAD(pf.a0, pf.b0, 2);
;   __syncthreads();
; #pragma unroll
;   for (int kt = 0; kt < nk; kt += 2) {
;     BCOMP(0);
;     BSTORE(pf.a1, pf.b1, 1);
;     if (kt + 3 < nk) BLOAD(pf.a1, pf.b1, kt + 3);
;     __syncthreads();
;     BCOMP(1);
;     if (kt + 2 < nk) { BSTORE(pf.a0, pf.b0, 0); if (kt + 4 < nk) BLOAD(pf.a0, pf.b0, kt + 4); }
;     __syncthreads();
	ds_read_b128 v[224:227], v126 offset:49152
	ds_read_b128 v[240:243], v128 offset:49152
	ds_read_b128 v[244:247], v128 offset:50176
	ds_read_b128 v[248:251], v128 offset:51200
	ds_read_b128 v[156:159], v128 offset:52224
	ds_read_b128 v[228:231], v126 offset:50176
	ds_read_b128 v[232:235], v126 offset:51200
	ds_read_b128 v[236:239], v126 offset:52224
	ds_read_b128 v[160:163], v128 offset:57344
	ds_read_b128 v[164:167], v128 offset:58368
	ds_read_b128 v[168:171], v128 offset:59392
	ds_read_b128 v[122:125], v128 offset:60416
	s_add_u32 m0, s46, 0x6000
	s_add_u32 s48, s48, 0x100000
	s_addc_u32 s49, s49, 0
	global_load_lds_dwordx4 v138, s[48:49]
	global_load_lds_dwordx4 v139, s[48:49] offset:1024
	s_add_u32 m0, s47, 0x6000
	s_add_u32 s50, s50, s13
	s_addc_u32 s51, s51, 0
	global_load_lds_dwordx4 v140, s[50:51]
	global_load_lds_dwordx4 v141, s[50:51] offset:1024
	global_load_lds_dwordx4 v142, s[50:51] offset:2048
	global_load_lds_dwordx4 v143, s[50:51] offset:3072
	s_waitcnt lgkmcnt(10)
	v_mfma_f32_16x16x32_bf16 v[2:5], v[224:227], v[240:243], v[2:5]
	s_waitcnt lgkmcnt(9)
	v_mfma_f32_16x16x32_bf16 v[6:9], v[224:227], v[244:247], v[6:9]
	s_waitcnt lgkmcnt(8)
	v_mfma_f32_16x16x32_bf16 v[10:13], v[224:227], v[248:251], v[10:13]
	s_waitcnt lgkmcnt(7)
	v_mfma_f32_16x16x32_bf16 v[14:17], v[224:227], v[156:159], v[14:17]
	s_waitcnt lgkmcnt(6)
	v_mfma_f32_16x16x32_bf16 v[18:21], v[228:231], v[240:243], v[18:21]
	v_mfma_f32_16x16x32_bf16 v[22:25], v[228:231], v[244:247], v[22:25]
	v_mfma_f32_16x16x32_bf16 v[26:29], v[228:231], v[248:251], v[26:29]
	v_mfma_f32_16x16x32_bf16 v[30:33], v[228:231], v[156:159], v[30:33]
	s_waitcnt lgkmcnt(5)
	v_mfma_f32_16x16x32_bf16 v[34:37], v[232:235], v[240:243], v[34:37]
	v_mfma_f32_16x16x32_bf16 v[38:41], v[232:235], v[244:247], v[38:41]
	v_mfma_f32_16x16x32_bf16 v[42:45], v[232:235], v[248:251], v[42:45]
	v_mfma_f32_16x16x32_bf16 v[46:49], v[232:235], v[156:159], v[46:49]
	s_waitcnt lgkmcnt(4)
	v_mfma_f32_16x16x32_bf16 v[50:53], v[236:239], v[240:243], v[50:53]
	v_mfma_f32_16x16x32_bf16 v[54:57], v[236:239], v[244:247], v[54:57]
	v_mfma_f32_16x16x32_bf16 v[58:61], v[236:239], v[248:251], v[58:61]
	v_mfma_f32_16x16x32_bf16 v[62:65], v[236:239], v[156:159], v[62:65]
	s_waitcnt lgkmcnt(3)
	v_mfma_f32_16x16x32_bf16 v[74:77], v[224:227], v[160:163], v[74:77]
	s_waitcnt lgkmcnt(2)
	v_mfma_f32_16x16x32_bf16 v[78:81], v[224:227], v[164:167], v[78:81]
	s_waitcnt lgkmcnt(1)
	v_mfma_f32_16x16x32_bf16 v[82:85], v[224:227], v[168:171], v[82:85]
	s_waitcnt lgkmcnt(0)
	v_mfma_f32_16x16x32_bf16 v[86:89], v[224:227], v[122:125], v[86:89]
	v_mfma_f32_16x16x32_bf16 v[90:93], v[228:231], v[160:163], v[90:93]
	v_mfma_f32_16x16x32_bf16 v[94:97], v[228:231], v[164:167], v[94:97]
	v_mfma_f32_16x16x32_bf16 v[98:101], v[228:231], v[168:171], v[98:101]
	v_mfma_f32_16x16x32_bf16 v[102:105], v[228:231], v[122:125], v[102:105]
	v_mfma_f32_16x16x32_bf16 v[106:109], v[232:235], v[160:163], v[106:109]
	v_mfma_f32_16x16x32_bf16 v[110:113], v[232:235], v[164:167], v[110:113]
	v_mfma_f32_16x16x32_bf16 v[114:117], v[232:235], v[168:171], v[114:117]
	v_mfma_f32_16x16x32_bf16 v[118:121], v[232:235], v[122:125], v[118:121]
	v_mfma_f32_16x16x32_bf16 v[208:211], v[236:239], v[160:163], v[208:211]
	v_mfma_f32_16x16x32_bf16 v[212:215], v[236:239], v[164:167], v[212:215]
	v_mfma_f32_16x16x32_bf16 v[216:219], v[236:239], v[168:171], v[216:219]
	v_mfma_f32_16x16x32_bf16 v[220:223], v[236:239], v[122:125], v[220:223]
	s_sub_u32 s12, s12, 1
	s_cmp_lg_u32 s12, 0
	s_cbranch_scc1 .Linp_kloop
	s_waitcnt vmcnt(6)
	s_barrier
; #define BLOAD(A_, B_, kt) do { _Pragma("unroll") for (int i = 0; i < 4; ++i) { \
;     A_[i] = *(const u32x4*)((const char*)Ap + (aoff + (unsigned)(32 * i * lda + (kt) * 64) * 2u)); B_[i] = *(const u32x4*)((const char*)Wt + (woff + (unsigned)(32 * i * K + (kt) * 64) * 2u)); } } while (0)
; #define BLOAD(A_, B_, kt) do { _Pragma("unroll") for (int i = 0; i < 4; ++i) { \
;     A_[i] = *(const u32x4*)((const char*)Ap + (aoff + (unsigned)(32 * i * lda + (kt) * 64) * 2u)); B_[i] = *(const u32x4*)((const char*)Wt + (woff + (unsigned)(32 * i * K + (kt) * 64) * 2u)); } } while (0)
; #define BSTORE(A_, B_, buf) do { _Pragma("unroll") for (int i = 0; i < 4; ++i) { \
;     *(u32x4*)&As[(buf) * GBUF + (srow + 32 * i) * LDT + sc8] = A_[i]; \
;     *(u32x4*)&Bs[(buf) * GBUF + (srow + 32 * i) * LDT + sc8] = B_[i]; } } while (0)
; template <int NK>
; DI void gemm_run(PF& pf, const u16* __restrict__ Ap, int lda, const u16* __restrict__ Wt, f32x16 (&acc)[2][2], char* smem) {
;     ...
;   __builtin_amdgcn_s_setprio(0);
;   __syncthreads();
;   BSTORE(pf.a0, pf.b0, 0);
;   BLOAD(pf.a0, pf.b0, 2);
;   __syncthreads();
; #pragma unroll
;   for (int kt = 0; kt < nk; kt += 2) {
;     BCOMP(0);
;     BSTORE(pf.a1, pf.b1, 1);
;     if (kt + 3 < nk) BLOAD(pf.a1, pf.b1, kt + 3);
;     __syncthreads();
;     BCOMP(1);
;     if (kt + 2 < nk) { BSTORE(pf.a0, pf.b0, 0); if (kt + 4 < nk) BLOAD(pf.a0, pf.b0, kt + 4); }
;     __syncthreads();
	ds_read_b128 v[224:227], v126 offset:0
	ds_read_b128 v[240:243], v128 offset:0
	ds_read_b128 v[244:247], v128 offset:1024
	ds_read_b128 v[248:251], v128 offset:2048
	ds_read_b128 v[156:159], v128 offset:3072
	ds_read_b128 v[228:231], v126 offset:1024
	ds_read_b128 v[232:235], v126 offset:2048
	ds_read_b128 v[236:239], v126 offset:3072
	ds_read_b128 v[160:163], v128 offset:8192
	ds_read_b128 v[164:167], v128 offset:9216
	ds_read_b128 v[168:171], v128 offset:10240
	ds_read_b128 v[122:125], v128 offset:11264
	s_waitcnt lgkmcnt(10)
	v_mfma_f32_16x16x32_bf16 v[2:5], v[224:227], v[240:243], v[2:5]
	s_waitcnt lgkmcnt(9)
	v_mfma_f32_16x16x32_bf16 v[6:9], v[224:227], v[244:247], v[6:9]
	s_waitcnt lgkmcnt(8)
	v_mfma_f32_16x16x32_bf16 v[10:13], v[224:227], v[248:251], v[10:13]
	s_waitcnt lgkmcnt(7)
	v_mfma_f32_16x16x32_bf16 v[14:17], v[224:227], v[156:159], v[14:17]
	s_waitcnt lgkmcnt(6)
	v_mfma_f32_16x16x32_bf16 v[18:21], v[228:231], v[240:243], v[18:21]
	v_mfma_f32_16x16x32_bf16 v[22:25], v[228:231], v[244:247], v[22:25]
	v_mfma_f32_16x16x32_bf16 v[26:29], v[228:231], v[248:251], v[26:29]
	v_mfma_f32_16x16x32_bf16 v[30:33], v[228:231], v[156:159], v[30:33]
	s_waitcnt lgkmcnt(5)
	v_mfma_f32_16x16x32_bf16 v[34:37], v[232:235], v[240:243], v[34:37]
	v_mfma_f32_16x16x32_bf16 v[38:41], v[232:235], v[244:247], v[38:41]
	v_mfma_f32_16x16x32_bf16 v[42:45], v[232:235], v[248:251], v[42:45]
	v_mfma_f32_16x16x32_bf16 v[46:49], v[232:235], v[156:159], v[46:49]
	s_waitcnt lgkmcnt(4)
	v_mfma_f32_16x16x32_bf16 v[50:53], v[236:239], v[240:243], v[50:53]
	v_mfma_f32_16x16x32_bf16 v[54:57], v[236:239], v[244:247], v[54:57]
	v_mfma_f32_16x16x32_bf16 v[58:61], v[236:239], v[248:251], v[58:61]
	v_mfma_f32_16x16x32_bf16 v[62:65], v[236:239], v[156:159], v[62:65]
	s_waitcnt lgkmcnt(3)
	v_mfma_f32_16x16x32_bf16 v[74:77], v[224:227], v[160:163], v[74:77]
	s_waitcnt lgkmcnt(2)
	v_mfma_f32_16x16x32_bf16 v[78:81], v[224:227], v[164:167], v[78:81]
	s_waitcnt lgkmcnt(1)
	v_mfma_f32_16x16x32_bf16 v[82:85], v[224:227], v[168:171], v[82:85]
	s_waitcnt lgkmcnt(0)
	v_mfma_f32_16x16x32_bf16 v[86:89], v[224:227], v[122:125], v[86:89]
	v_mfma_f32_16x16x32_bf16 v[90:93], v[228:231], v[160:163], v[90:93]
	v_mfma_f32_16x16x32_bf16 v[94:97], v[228:231], v[164:167], v[94:97]
	v_mfma_f32_16x16x32_bf16 v[98:101], v[228:231], v[168:171], v[98:101]
	v_mfma_f32_16x16x32_bf16 v[102:105], v[228:231], v[122:125], v[102:105]
	v_mfma_f32_16x16x32_bf16 v[106:109], v[232:235], v[160:163], v[106:109]
	v_mfma_f32_16x16x32_bf16 v[110:113], v[232:235], v[164:167], v[110:113]
	v_mfma_f32_16x16x32_bf16 v[114:117], v[232:235], v[168:171], v[114:117]
	v_mfma_f32_16x16x32_bf16 v[118:121], v[232:235], v[122:125], v[118:121]
	v_mfma_f32_16x16x32_bf16 v[208:211], v[236:239], v[160:163], v[208:211]
	v_mfma_f32_16x16x32_bf16 v[212:215], v[236:239], v[164:167], v[212:215]
	v_mfma_f32_16x16x32_bf16 v[216:219], v[236:239], v[168:171], v[216:219]
	v_mfma_f32_16x16x32_bf16 v[220:223], v[236:239], v[122:125], v[220:223]
	s_waitcnt vmcnt(0)
	s_barrier
	ds_read_b128 v[224:227], v126 offset:24576
	ds_read_b128 v[240:243], v128 offset:24576
	ds_read_b128 v[244:247], v128 offset:25600
	ds_read_b128 v[248:251], v128 offset:26624
	ds_read_b128 v[156:159], v128 offset:27648
	ds_read_b128 v[228:231], v126 offset:25600
	ds_read_b128 v[232:235], v126 offset:26624
	ds_read_b128 v[236:239], v126 offset:27648
	ds_read_b128 v[160:163], v128 offset:32768
	ds_read_b128 v[164:167], v128 offset:33792
	ds_read_b128 v[168:171], v128 offset:34816
	ds_read_b128 v[122:125], v128 offset:35840
	s_waitcnt lgkmcnt(10)
	v_mfma_f32_16x16x32_bf16 v[2:5], v[224:227], v[240:243], v[2:5]
	s_waitcnt lgkmcnt(9)
	v_mfma_f32_16x16x32_bf16 v[6:9], v[224:227], v[244:247], v[6:9]
	s_waitcnt lgkmcnt(8)
	v_mfma_f32_16x16x32_bf16 v[10:13], v[224:227], v[248:251], v[10:13]
	s_waitcnt lgkmcnt(7)
	v_mfma_f32_16x16x32_bf16 v[14:17], v[224:227], v[156:159], v[14:17]
	s_waitcnt lgkmcnt(6)
	v_mfma_f32_16x16x32_bf16 v[18:21], v[228:231], v[240:243], v[18:21]
	v_mfma_f32_16x16x32_bf16 v[22:25], v[228:231], v[244:247], v[22:25]
	v_mfma_f32_16x16x32_bf16 v[26:29], v[228:231], v[248:251], v[26:29]
	v_mfma_f32_16x16x32_bf16 v[30:33], v[228:231], v[156:159], v[30:33]
	s_waitcnt lgkmcnt(5)
	v_mfma_f32_16x16x32_bf16 v[34:37], v[232:235], v[240:243], v[34:37]
	v_mfma_f32_16x16x32_bf16 v[38:41], v[232:235], v[244:247], v[38:41]
	v_mfma_f32_16x16x32_bf16 v[42:45], v[232:235], v[248:251], v[42:45]
	v_mfma_f32_16x16x32_bf16 v[46:49], v[232:235], v[156:159], v[46:49]
	s_waitcnt lgkmcnt(4)
	v_mfma_f32_16x16x32_bf16 v[50:53], v[236:239], v[240:243], v[50:53]
	v_mfma_f32_16x16x32_bf16 v[54:57], v[236:239], v[244:247], v[54:57]
	v_mfma_f32_16x16x32_bf16 v[58:61], v[236:239], v[248:251], v[58:61]
	v_mfma_f32_16x16x32_bf16 v[62:65], v[236:239], v[156:159], v[62:65]
	s_waitcnt lgkmcnt(3)
	v_mfma_f32_16x16x32_bf16 v[74:77], v[224:227], v[160:163], v[74:77]
	s_waitcnt lgkmcnt(2)
	v_mfma_f32_16x16x32_bf16 v[78:81], v[224:227], v[164:167], v[78:81]
	s_waitcnt lgkmcnt(1)
	v_mfma_f32_16x16x32_bf16 v[82:85], v[224:227], v[168:171], v[82:85]
	s_waitcnt lgkmcnt(0)
	v_mfma_f32_16x16x32_bf16 v[86:89], v[224:227], v[122:125], v[86:89]
	v_mfma_f32_16x16x32_bf16 v[90:93], v[228:231], v[160:163], v[90:93]
	v_mfma_f32_16x16x32_bf16 v[94:97], v[228:231], v[164:167], v[94:97]
	v_mfma_f32_16x16x32_bf16 v[98:101], v[228:231], v[168:171], v[98:101]
	v_mfma_f32_16x16x32_bf16 v[102:105], v[228:231], v[122:125], v[102:105]
	v_mfma_f32_16x16x32_bf16 v[106:109], v[232:235], v[160:163], v[106:109]
	v_mfma_f32_16x16x32_bf16 v[110:113], v[232:235], v[164:167], v[110:113]
	v_mfma_f32_16x16x32_bf16 v[114:117], v[232:235], v[168:171], v[114:117]
	v_mfma_f32_16x16x32_bf16 v[118:121], v[232:235], v[122:125], v[118:121]
	v_mfma_f32_16x16x32_bf16 v[208:211], v[236:239], v[160:163], v[208:211]
	v_mfma_f32_16x16x32_bf16 v[212:215], v[236:239], v[164:167], v[212:215]
	v_mfma_f32_16x16x32_bf16 v[216:219], v[236:239], v[168:171], v[216:219]
	v_mfma_f32_16x16x32_bf16 v[220:223], v[236:239], v[122:125], v[220:223]
	s_barrier
	s_branch .Linp_post

; #define BLOAD(A_, B_, kt) do { _Pragma("unroll") for (int i = 0; i < 4; ++i) { \
;     A_[i] = *(const u32x4*)((const char*)Ap + (aoff + (unsigned)(32 * i * lda + (kt) * 64) * 2u)); B_[i] = *(const u32x4*)((const char*)Wt + (woff + (unsigned)(32 * i * K + (kt) * 64) * 2u)); } } while (0)
; #define BLOAD(A_, B_, kt) do { _Pragma("unroll") for (int i = 0; i < 4; ++i) { \
;     A_[i] = *(const u32x4*)((const char*)Ap + (aoff + (unsigned)(32 * i * lda + (kt) * 64) * 2u)); B_[i] = *(const u32x4*)((const char*)Wt + (woff + (unsigned)(32 * i * K + (kt) * 64) * 2u)); } } while (0)
; #define BSTORE(A_, B_, buf) do { _Pragma("unroll") for (int i = 0; i < 4; ++i) { \
;     *(u32x4*)&As[(buf) * GBUF + (srow + 32 * i) * LDT + sc8] = A_[i]; \
;     *(u32x4*)&Bs[(buf) * GBUF + (srow + 32 * i) * LDT + sc8] = B_[i]; } } while (0)
; template <int NK>
; DI void gemm_run(PF& pf, const u16* __restrict__ Ap, int lda, const u16* __restrict__ Wt, f32x16 (&acc)[2][2], char* smem) {
;     ...
;   __builtin_amdgcn_s_setprio(0);
;   __syncthreads();
;   BSTORE(pf.a0, pf.b0, 0);
;   BLOAD(pf.a0, pf.b0, 2);
;   __syncthreads();
; #pragma unroll
;   for (int kt = 0; kt < nk; kt += 2) {
;     BCOMP(0);
;     BSTORE(pf.a1, pf.b1, 1);
;     if (kt + 3 < nk) BLOAD(pf.a1, pf.b1, kt + 3);
;     __syncthreads();
;     BCOMP(1);
;     if (kt + 2 < nk) { BSTORE(pf.a0, pf.b0, 0); if (kt + 4 < nk) BLOAD(pf.a0, pf.b0, kt + 4); }
;     __syncthreads();
.Linpd_kloop:
	s_waitcnt vmcnt(6)
	s_barrier
	ds_read_b128 v[224:227], v126 offset:0
	ds_read_b128 v[240:243], v128 offset:0
	ds_read_b128 v[244:247], v128 offset:1024
	ds_read_b128 v[248:251], v128 offset:2048
	ds_read_b128 v[156:159], v128 offset:3072
	ds_read_b128 v[228:231], v126 offset:1024
	ds_read_b128 v[232:235], v126 offset:2048
	ds_read_b128 v[236:239], v126 offset:3072
	ds_read_b128 v[160:163], v128 offset:8192
	ds_read_b128 v[164:167], v128 offset:9216
	ds_read_b128 v[168:171], v128 offset:10240
	ds_read_b128 v[122:125], v128 offset:11264
	s_add_u32 m0, s46, 0xc000
	s_add_u32 s48, s48, 0x100000
	s_addc_u32 s49, s49, 0
	global_load_lds_dwordx4 v138, s[48:49]
	global_load_lds_dwordx4 v139, s[48:49] offset:1024
	s_add_u32 m0, s47, 0xc000
	s_add_u32 s50, s50, s13
	s_addc_u32 s51, s51, 0
	global_load_lds_dwordx4 v140, s[50:51]
	global_load_lds_dwordx4 v141, s[50:51] offset:1024
	global_load_lds_dwordx4 v142, s[50:51] offset:2048
	global_load_lds_dwordx4 v143, s[50:51] offset:3072
	s_waitcnt lgkmcnt(10)
	v_mfma_f32_16x16x32_bf16 v[2:5], v[240:243], v[224:227], v[2:5]
	s_waitcnt lgkmcnt(9)
	v_mfma_f32_16x16x32_bf16 v[6:9], v[244:247], v[224:227], v[6:9]
	s_waitcnt lgkmcnt(8)
	v_mfma_f32_16x16x32_bf16 v[10:13], v[248:251], v[224:227], v[10:13]
	s_waitcnt lgkmcnt(7)
	v_mfma_f32_16x16x32_bf16 v[14:17], v[156:159], v[224:227], v[14:17]
	s_waitcnt lgkmcnt(6)
	v_mfma_f32_16x16x32_bf16 v[18:21], v[240:243], v[228:231], v[18:21]
	v_mfma_f32_16x16x32_bf16 v[22:25], v[244:247], v[228:231], v[22:25]
	v_mfma_f32_16x16x32_bf16 v[26:29], v[248:251], v[228:231], v[26:29]
	v_mfma_f32_16x16x32_bf16 v[30:33], v[156:159], v[228:231], v[30:33]
	s_waitcnt lgkmcnt(5)
	v_mfma_f32_16x16x32_bf16 v[34:37], v[240:243], v[232:235], v[34:37]
	v_mfma_f32_16x16x32_bf16 v[38:41], v[244:247], v[232:235], v[38:41]
	v_mfma_f32_16x16x32_bf16 v[42:45], v[248:251], v[232:235], v[42:45]
	v_mfma_f32_16x16x32_bf16 v[46:49], v[156:159], v[232:235], v[46:49]
	s_waitcnt lgkmcnt(4)
	v_mfma_f32_16x16x32_bf16 v[50:53], v[240:243], v[236:239], v[50:53]
	v_mfma_f32_16x16x32_bf16 v[54:57], v[244:247], v[236:239], v[54:57]
	v_mfma_f32_16x16x32_bf16 v[58:61], v[248:251], v[236:239], v[58:61]
	v_mfma_f32_16x16x32_bf16 v[62:65], v[156:159], v[236:239], v[62:65]
	s_waitcnt lgkmcnt(3)
	v_mfma_f32_16x16x32_bf16 v[74:77], v[160:163], v[224:227], v[74:77]
	s_waitcnt lgkmcnt(2)
	v_mfma_f32_16x16x32_bf16 v[78:81], v[164:167], v[224:227], v[78:81]
	s_waitcnt lgkmcnt(1)
	v_mfma_f32_16x16x32_bf16 v[82:85], v[168:171], v[224:227], v[82:85]
	s_waitcnt lgkmcnt(0)
	v_mfma_f32_16x16x32_bf16 v[86:89], v[122:125], v[224:227], v[86:89]
	v_mfma_f32_16x16x32_bf16 v[90:93], v[160:163], v[228:231], v[90:93]
	v_mfma_f32_16x16x32_bf16 v[94:97], v[164:167], v[228:231], v[94:97]
	v_mfma_f32_16x16x32_bf16 v[98:101], v[168:171], v[228:231], v[98:101]
	v_mfma_f32_16x16x32_bf16 v[102:105], v[122:125], v[228:231], v[102:105]
	v_mfma_f32_16x16x32_bf16 v[106:109], v[160:163], v[232:235], v[106:109]
	v_mfma_f32_16x16x32_bf16 v[110:113], v[164:167], v[232:235], v[110:113]
	v_mfma_f32_16x16x32_bf16 v[114:117], v[168:171], v[232:235], v[114:117]
	v_mfma_f32_16x16x32_bf16 v[118:121], v[122:125], v[232:235], v[118:121]
	v_mfma_f32_16x16x32_bf16 v[208:211], v[160:163], v[236:239], v[208:211]
	v_mfma_f32_16x16x32_bf16 v[212:215], v[164:167], v[236:239], v[212:215]
	v_mfma_f32_16x16x32_bf16 v[216:219], v[168:171], v[236:239], v[216:219]
	v_mfma_f32_16x16x32_bf16 v[220:223], v[122:125], v[236:239], v[220:223]
	s_waitcnt vmcnt(6)
	s_barrier
	ds_read_b128 v[224:227], v126 offset:24576
	ds_read_b128 v[240:243], v128 offset:24576
	ds_read_b128 v[244:247], v128 offset:25600
	ds_read_b128 v[248:251], v128 offset:26624
	ds_read_b128 v[156:159], v128 offset:27648
	ds_read_b128 v[228:231], v126 offset:25600
	ds_read_b128 v[232:235], v126 offset:26624
	ds_read_b128 v[236:239], v126 offset:27648
	ds_read_b128 v[160:163], v128 offset:32768
	ds_read_b128 v[164:167], v128 offset:33792
	ds_read_b128 v[168:171], v128 offset:34816
	ds_read_b128 v[122:125], v128 offset:35840
	s_add_u32 m0, s46, 0x0
	s_add_u32 s48, s48, 0x100000
	s_addc_u32 s49, s49, 0
	global_load_lds_dwordx4 v138, s[48:49]
	global_load_lds_dwordx4 v139, s[48:49] offset:1024
	s_add_u32 m0, s47, 0x0
	s_add_u32 s50, s50, s13
	s_addc_u32 s51, s51, 0
	global_load_lds_dwordx4 v140, s[50:51]
	global_load_lds_dwordx4 v141, s[50:51] offset:1024
	global_load_lds_dwordx4 v142, s[50:51] offset:2048
	global_load_lds_dwordx4 v143, s[50:51] offset:3072
	s_waitcnt lgkmcnt(10)
	v_mfma_f32_16x16x32_bf16 v[2:5], v[240:243], v[224:227], v[2:5]
	s_waitcnt lgkmcnt(9)
	v_mfma_f32_16x16x32_bf16 v[6:9], v[244:247], v[224:227], v[6:9]
	s_waitcnt lgkmcnt(8)
	v_mfma_f32_16x16x32_bf16 v[10:13], v[248:251], v[224:227], v[10:13]
	s_waitcnt lgkmcnt(7)
	v_mfma_f32_16x16x32_bf16 v[14:17], v[156:159], v[224:227], v[14:17]
	s_waitcnt lgkmcnt(6)
	v_mfma_f32_16x16x32_bf16 v[18:21], v[240:243], v[228:231], v[18:21]
	v_mfma_f32_16x16x32_bf16 v[22:25], v[244:247], v[228:231], v[22:25]
	v_mfma_f32_16x16x32_bf16 v[26:29], v[248:251], v[228:231], v[26:29]
	v_mfma_f32_16x16x32_bf16 v[30:33], v[156:159], v[228:231], v[30:33]
	s_waitcnt lgkmcnt(5)
	v_mfma_f32_16x16x32_bf16 v[34:37], v[240:243], v[232:235], v[34:37]
	v_mfma_f32_16x16x32_bf16 v[38:41], v[244:247], v[232:235], v[38:41]
	v_mfma_f32_16x16x32_bf16 v[42:45], v[248:251], v[232:235], v[42:45]
	v_mfma_f32_16x16x32_bf16 v[46:49], v[156:159], v[232:235], v[46:49]
	s_waitcnt lgkmcnt(4)
	v_mfma_f32_16x16x32_bf16 v[50:53], v[240:243], v[236:239], v[50:53]
	v_mfma_f32_16x16x32_bf16 v[54:57], v[244:247], v[236:239], v[54:57]
	v_mfma_f32_16x16x32_bf16 v[58:61], v[248:251], v[236:239], v[58:61]
	v_mfma_f32_16x16x32_bf16 v[62:65], v[156:159], v[236:239], v[62:65]
	s_waitcnt lgkmcnt(3)
	v_mfma_f32_16x16x32_bf16 v[74:77], v[160:163], v[224:227], v[74:77]
	s_waitcnt lgkmcnt(2)
	v_mfma_f32_16x16x32_bf16 v[78:81], v[164:167], v[224:227], v[78:81]
	s_waitcnt lgkmcnt(1)
	v_mfma_f32_16x16x32_bf16 v[82:85], v[168:171], v[224:227], v[82:85]
	s_waitcnt lgkmcnt(0)
	v_mfma_f32_16x16x32_bf16 v[86:89], v[122:125], v[224:227], v[86:89]
	v_mfma_f32_16x16x32_bf16 v[90:93], v[160:163], v[228:231], v[90:93]
	v_mfma_f32_16x16x32_bf16 v[94:97], v[164:167], v[228:231], v[94:97]
	v_mfma_f32_16x16x32_bf16 v[98:101], v[168:171], v[228:231], v[98:101]
	v_mfma_f32_16x16x32_bf16 v[102:105], v[122:125], v[228:231], v[102:105]
	v_mfma_f32_16x16x32_bf16 v[106:109], v[160:163], v[232:235], v[106:109]
	v_mfma_f32_16x16x32_bf16 v[110:113], v[164:167], v[232:235], v[110:113]
	v_mfma_f32_16x16x32_bf16 v[114:117], v[168:171], v[232:235], v[114:117]
	v_mfma_f32_16x16x32_bf16 v[118:121], v[122:125], v[232:235], v[118:121]
	v_mfma_f32_16x16x32_bf16 v[208:211], v[160:163], v[236:239], v[208:211]
	v_mfma_f32_16x16x32_bf16 v[212:215], v[164:167], v[236:239], v[212:215]
	v_mfma_f32_16x16x32_bf16 v[216:219], v[168:171], v[236:239], v[216:219]
	v_mfma_f32_16x16x32_bf16 v[220:223], v[122:125], v[236:239], v[220:223]
	s_waitcnt vmcnt(6)
	s_barrier
; #define BLOAD(A_, B_, kt) do { _Pragma("unroll") for (int i = 0; i < 4; ++i) { \
;     A_[i] = *(const u32x4*)((const char*)Ap + (aoff + (unsigned)(32 * i * lda + (kt) * 64) * 2u)); B_[i] = *(const u32x4*)((const char*)Wt + (woff + (unsigned)(32 * i * K + (kt) * 64) * 2u)); } } while (0)
; #define BLOAD(A_, B_, kt) do { _Pragma("unroll") for (int i = 0; i < 4; ++i) { \
;     A_[i] = *(const u32x4*)((const char*)Ap + (aoff + (unsigned)(32 * i * lda + (kt) * 64) * 2u)); B_[i] = *(const u32x4*)((const char*)Wt + (woff + (unsigned)(32 * i * K + (kt) * 64) * 2u)); } } while (0)
; #define BSTORE(A_, B_, buf) do { _Pragma("unroll") for (int i = 0; i < 4; ++i) { \
;     *(u32x4*)&As[(buf) * GBUF + (srow + 32 * i) * LDT + sc8] = A_[i]; \
;     *(u32x4*)&Bs[(buf) * GBUF + (srow + 32 * i) * LDT + sc8] = B_[i]; } } while (0)
; template <int NK>
; DI void gemm_run(PF& pf, const u16* __restrict__ Ap, int lda, const u16* __restrict__ Wt, f32x16 (&acc)[2][2], char* smem) {
;     ...
;   __builtin_amdgcn_s_setprio(0);
;   __syncthreads();
;   BSTORE(pf.a0, pf.b0, 0);
;   BLOAD(pf.a0, pf.b0, 2);
;   __syncthreads();
; #pragma unroll
;   for (int kt = 0; kt < nk; kt += 2) {
;     BCOMP(0);
;     BSTORE(pf.a1, pf.b1, 1);
;     if (kt + 3 < nk) BLOAD(pf.a1, pf.b1, kt + 3);
;     __syncthreads();
;     BCOMP(1);
;     if (kt + 2 < nk) { BSTORE(pf.a0, pf.b0, 0); if (kt + 4 < nk) BLOAD(pf.a0, pf.b0, kt + 4); }
;     __syncthreads();
	ds_read_b128 v[224:227], v126 offset:49152
	ds_read_b128 v[240:243], v128 offset:49152
	ds_read_b128 v[244:247], v128 offset:50176
	ds_read_b128 v[248:251], v128 offset:51200
	ds_read_b128 v[156:159], v128 offset:52224
	ds_read_b128 v[228:231], v126 offset:50176
	ds_read_b128 v[232:235], v126 offset:51200
	ds_read_b128 v[236:239], v126 offset:52224
	ds_read_b128 v[160:163], v128 offset:57344
	ds_read_b128 v[164:167], v128 offset:58368
	ds_read_b128 v[168:171], v128 offset:59392
	ds_read_b128 v[122:125], v128 offset:60416
	s_add_u32 m0, s46, 0x6000
	s_add_u32 s48, s48, 0x100000
	s_addc_u32 s49, s49, 0
	global_load_lds_dwordx4 v138, s[48:49]
	global_load_lds_dwordx4 v139, s[48:49] offset:1024
	s_add_u32 m0, s47, 0x6000
	s_add_u32 s50, s50, s13
	s_addc_u32 s51, s51, 0
	global_load_lds_dwordx4 v140, s[50:51]
	global_load_lds_dwordx4 v141, s[50:51] offset:1024
	global_load_lds_dwordx4 v142, s[50:51] offset:2048
	global_load_lds_dwordx4 v143, s[50:51] offset:3072
	s_waitcnt lgkmcnt(10)
	v_mfma_f32_16x16x32_bf16 v[2:5], v[240:243], v[224:227], v[2:5]
	s_waitcnt lgkmcnt(9)
	v_mfma_f32_16x16x32_bf16 v[6:9], v[244:247], v[224:227], v[6:9]
	s_waitcnt lgkmcnt(8)
	v_mfma_f32_16x16x32_bf16 v[10:13], v[248:251], v[224:227], v[10:13]
	s_waitcnt lgkmcnt(7)
	v_mfma_f32_16x16x32_bf16 v[14:17], v[156:159], v[224:227], v[14:17]
	s_waitcnt lgkmcnt(6)
	v_mfma_f32_16x16x32_bf16 v[18:21], v[240:243], v[228:231], v[18:21]
	v_mfma_f32_16x16x32_bf16 v[22:25], v[244:247], v[228:231], v[22:25]
	v_mfma_f32_16x16x32_bf16 v[26:29], v[248:251], v[228:231], v[26:29]
	v_mfma_f32_16x16x32_bf16 v[30:33], v[156:159], v[228:231], v[30:33]
	s_waitcnt lgkmcnt(5)
	v_mfma_f32_16x16x32_bf16 v[34:37], v[240:243], v[232:235], v[34:37]
	v_mfma_f32_16x16x32_bf16 v[38:41], v[244:247], v[232:235], v[38:41]
	v_mfma_f32_16x16x32_bf16 v[42:45], v[248:251], v[232:235], v[42:45]
	v_mfma_f32_16x16x32_bf16 v[46:49], v[156:159], v[232:235], v[46:49]
	s_waitcnt lgkmcnt(4)
	v_mfma_f32_16x16x32_bf16 v[50:53], v[240:243], v[236:239], v[50:53]
	v_mfma_f32_16x16x32_bf16 v[54:57], v[244:247], v[236:239], v[54:57]
	v_mfma_f32_16x16x32_bf16 v[58:61], v[248:251], v[236:239], v[58:61]
	v_mfma_f32_16x16x32_bf16 v[62:65], v[156:159], v[236:239], v[62:65]
	s_waitcnt lgkmcnt(3)
	v_mfma_f32_16x16x32_bf16 v[74:77], v[160:163], v[224:227], v[74:77]
	s_waitcnt lgkmcnt(2)
	v_mfma_f32_16x16x32_bf16 v[78:81], v[164:167], v[224:227], v[78:81]
	s_waitcnt lgkmcnt(1)
	v_mfma_f32_16x16x32_bf16 v[82:85], v[168:171], v[224:227], v[82:85]
	s_waitcnt lgkmcnt(0)
	v_mfma_f32_16x16x32_bf16 v[86:89], v[122:125], v[224:227], v[86:89]
	v_mfma_f32_16x16x32_bf16 v[90:93], v[160:163], v[228:231], v[90:93]
	v_mfma_f32_16x16x32_bf16 v[94:97], v[164:167], v[228:231], v[94:97]
	v_mfma_f32_16x16x32_bf16 v[98:101], v[168:171], v[228:231], v[98:101]
	v_mfma_f32_16x16x32_bf16 v[102:105], v[122:125], v[228:231], v[102:105]
	v_mfma_f32_16x16x32_bf16 v[106:109], v[160:163], v[232:235], v[106:109]
	v_mfma_f32_16x16x32_bf16 v[110:113], v[164:167], v[232:235], v[110:113]
	v_mfma_f32_16x16x32_bf16 v[114:117], v[168:171], v[232:235], v[114:117]
	v_mfma_f32_16x16x32_bf16 v[118:121], v[122:125], v[232:235], v[118:121]
	v_mfma_f32_16x16x32_bf16 v[208:211], v[160:163], v[236:239], v[208:211]
	v_mfma_f32_16x16x32_bf16 v[212:215], v[164:167], v[236:239], v[212:215]
	v_mfma_f32_16x16x32_bf16 v[216:219], v[168:171], v[236:239], v[216:219]
	v_mfma_f32_16x16x32_bf16 v[220:223], v[122:125], v[236:239], v[220:223]
	s_sub_u32 s12, s12, 1
	s_cmp_lg_u32 s12, 0
	s_cbranch_scc1 .Linpd_kloop
	s_waitcnt vmcnt(6)
	s_barrier
; #define BLOAD(A_, B_, kt) do { _Pragma("unroll") for (int i = 0; i < 4; ++i) { \
;     A_[i] = *(const u32x4*)((const char*)Ap + (aoff + (unsigned)(32 * i * lda + (kt) * 64) * 2u)); B_[i] = *(const u32x4*)((const char*)Wt + (woff + (unsigned)(32 * i * K + (kt) * 64) * 2u)); } } while (0)
; #define BLOAD(A_, B_, kt) do { _Pragma("unroll") for (int i = 0; i < 4; ++i) { \
;     A_[i] = *(const u32x4*)((const char*)Ap + (aoff + (unsigned)(32 * i * lda + (kt) * 64) * 2u)); B_[i] = *(const u32x4*)((const char*)Wt + (woff + (unsigned)(32 * i * K + (kt) * 64) * 2u)); } } while (0)
; #define BSTORE(A_, B_, buf) do { _Pragma("unroll") for (int i = 0; i < 4; ++i) { \
;     *(u32x4*)&As[(buf) * GBUF + (srow + 32 * i) * LDT + sc8] = A_[i]; \
;     *(u32x4*)&Bs[(buf) * GBUF + (srow + 32 * i) * LDT + sc8] = B_[i]; } } while (0)
; template <int NK>
; DI void gemm_run(PF& pf, const u16* __restrict__ Ap, int lda, const u16* __restrict__ Wt, f32x16 (&acc)[2][2], char* smem) {
;     ...
;   __builtin_amdgcn_s_setprio(0);
;   __syncthreads();
;   BSTORE(pf.a0, pf.b0, 0);
;   BLOAD(pf.a0, pf.b0, 2);
;   __syncthreads();
; #pragma unroll
;   for (int kt = 0; kt < nk; kt += 2) {
;     BCOMP(0);
;     BSTORE(pf.a1, pf.b1, 1);
;     if (kt + 3 < nk) BLOAD(pf.a1, pf.b1, kt + 3);
;     __syncthreads();
;     BCOMP(1);
;     if (kt + 2 < nk) { BSTORE(pf.a0, pf.b0, 0); if (kt + 4 < nk) BLOAD(pf.a0, pf.b0, kt + 4); }
;     __syncthreads();
	ds_read_b128 v[224:227], v126 offset:0
	ds_read_b128 v[240:243], v128 offset:0
	ds_read_b128 v[244:247], v128 offset:1024
	ds_read_b128 v[248:251], v128 offset:2048
	ds_read_b128 v[156:159], v128 offset:3072
	ds_read_b128 v[228:231], v126 offset:1024
	ds_read_b128 v[232:235], v126 offset:2048
	ds_read_b128 v[236:239], v126 offset:3072
	ds_read_b128 v[160:163], v128 offset:8192
	ds_read_b128 v[164:167], v128 offset:9216
	ds_read_b128 v[168:171], v128 offset:10240
	ds_read_b128 v[122:125], v128 offset:11264
	s_waitcnt lgkmcnt(10)
	v_mfma_f32_16x16x32_bf16 v[2:5], v[240:243], v[224:227], v[2:5]
	s_waitcnt lgkmcnt(9)
	v_mfma_f32_16x16x32_bf16 v[6:9], v[244:247], v[224:227], v[6:9]
	s_waitcnt lgkmcnt(8)
	v_mfma_f32_16x16x32_bf16 v[10:13], v[248:251], v[224:227], v[10:13]
	s_waitcnt lgkmcnt(7)
	v_mfma_f32_16x16x32_bf16 v[14:17], v[156:159], v[224:227], v[14:17]
	s_waitcnt lgkmcnt(6)
	v_mfma_f32_16x16x32_bf16 v[18:21], v[240:243], v[228:231], v[18:21]
	v_mfma_f32_16x16x32_bf16 v[22:25], v[244:247], v[228:231], v[22:25]
	v_mfma_f32_16x16x32_bf16 v[26:29], v[248:251], v[228:231], v[26:29]
	v_mfma_f32_16x16x32_bf16 v[30:33], v[156:159], v[228:231], v[30:33]
	s_waitcnt lgkmcnt(5)
	v_mfma_f32_16x16x32_bf16 v[34:37], v[240:243], v[232:235], v[34:37]
	v_mfma_f32_16x16x32_bf16 v[38:41], v[244:247], v[232:235], v[38:41]
	v_mfma_f32_16x16x32_bf16 v[42:45], v[248:251], v[232:235], v[42:45]
	v_mfma_f32_16x16x32_bf16 v[46:49], v[156:159], v[232:235], v[46:49]
	s_waitcnt lgkmcnt(4)
	v_mfma_f32_16x16x32_bf16 v[50:53], v[240:243], v[236:239], v[50:53]
	v_mfma_f32_16x16x32_bf16 v[54:57], v[244:247], v[236:239], v[54:57]
	v_mfma_f32_16x16x32_bf16 v[58:61], v[248:251], v[236:239], v[58:61]
	v_mfma_f32_16x16x32_bf16 v[62:65], v[156:159], v[236:239], v[62:65]
	s_waitcnt lgkmcnt(3)
	v_mfma_f32_16x16x32_bf16 v[74:77], v[160:163], v[224:227], v[74:77]
	s_waitcnt lgkmcnt(2)
	v_mfma_f32_16x16x32_bf16 v[78:81], v[164:167], v[224:227], v[78:81]
	s_waitcnt lgkmcnt(1)
	v_mfma_f32_16x16x32_bf16 v[82:85], v[168:171], v[224:227], v[82:85]
	s_waitcnt lgkmcnt(0)
	v_mfma_f32_16x16x32_bf16 v[86:89], v[122:125], v[224:227], v[86:89]
	v_mfma_f32_16x16x32_bf16 v[90:93], v[160:163], v[228:231], v[90:93]
	v_mfma_f32_16x16x32_bf16 v[94:97], v[164:167], v[228:231], v[94:97]
	v_mfma_f32_16x16x32_bf16 v[98:101], v[168:171], v[228:231], v[98:101]
	v_mfma_f32_16x16x32_bf16 v[102:105], v[122:125], v[228:231], v[102:105]
	v_mfma_f32_16x16x32_bf16 v[106:109], v[160:163], v[232:235], v[106:109]
	v_mfma_f32_16x16x32_bf16 v[110:113], v[164:167], v[232:235], v[110:113]
	v_mfma_f32_16x16x32_bf16 v[114:117], v[168:171], v[232:235], v[114:117]
	v_mfma_f32_16x16x32_bf16 v[118:121], v[122:125], v[232:235], v[118:121]
	v_mfma_f32_16x16x32_bf16 v[208:211], v[160:163], v[236:239], v[208:211]
	v_mfma_f32_16x16x32_bf16 v[212:215], v[164:167], v[236:239], v[212:215]
	v_mfma_f32_16x16x32_bf16 v[216:219], v[168:171], v[236:239], v[216:219]
	v_mfma_f32_16x16x32_bf16 v[220:223], v[122:125], v[236:239], v[220:223]
	s_waitcnt vmcnt(0)
	s_barrier
	ds_read_b128 v[224:227], v126 offset:24576
	ds_read_b128 v[240:243], v128 offset:24576
	ds_read_b128 v[244:247], v128 offset:25600
	ds_read_b128 v[248:251], v128 offset:26624
	ds_read_b128 v[156:159], v128 offset:27648
	ds_read_b128 v[228:231], v126 offset:25600
	ds_read_b128 v[232:235], v126 offset:26624
	ds_read_b128 v[236:239], v126 offset:27648
	ds_read_b128 v[160:163], v128 offset:32768
	ds_read_b128 v[164:167], v128 offset:33792
	ds_read_b128 v[168:171], v128 offset:34816
	ds_read_b128 v[122:125], v128 offset:35840
	s_waitcnt lgkmcnt(10)
	v_mfma_f32_16x16x32_bf16 v[2:5], v[240:243], v[224:227], v[2:5]
	s_waitcnt lgkmcnt(9)
	v_mfma_f32_16x16x32_bf16 v[6:9], v[244:247], v[224:227], v[6:9]
	s_waitcnt lgkmcnt(8)
	v_mfma_f32_16x16x32_bf16 v[10:13], v[248:251], v[224:227], v[10:13]
	s_waitcnt lgkmcnt(7)
	v_mfma_f32_16x16x32_bf16 v[14:17], v[156:159], v[224:227], v[14:17]
	s_waitcnt lgkmcnt(6)
	v_mfma_f32_16x16x32_bf16 v[18:21], v[240:243], v[228:231], v[18:21]
	v_mfma_f32_16x16x32_bf16 v[22:25], v[244:247], v[228:231], v[22:25]
	v_mfma_f32_16x16x32_bf16 v[26:29], v[248:251], v[228:231], v[26:29]
	v_mfma_f32_16x16x32_bf16 v[30:33], v[156:159], v[228:231], v[30:33]
	s_waitcnt lgkmcnt(5)
	v_mfma_f32_16x16x32_bf16 v[34:37], v[240:243], v[232:235], v[34:37]
	v_mfma_f32_16x16x32_bf16 v[38:41], v[244:247], v[232:235], v[38:41]
	v_mfma_f32_16x16x32_bf16 v[42:45], v[248:251], v[232:235], v[42:45]
	v_mfma_f32_16x16x32_bf16 v[46:49], v[156:159], v[232:235], v[46:49]
	s_waitcnt lgkmcnt(4)
	v_mfma_f32_16x16x32_bf16 v[50:53], v[240:243], v[236:239], v[50:53]
	v_mfma_f32_16x16x32_bf16 v[54:57], v[244:247], v[236:239], v[54:57]
	v_mfma_f32_16x16x32_bf16 v[58:61], v[248:251], v[236:239], v[58:61]
	v_mfma_f32_16x16x32_bf16 v[62:65], v[156:159], v[236:239], v[62:65]
	s_waitcnt lgkmcnt(3)
	v_mfma_f32_16x16x32_bf16 v[74:77], v[160:163], v[224:227], v[74:77]
	s_waitcnt lgkmcnt(2)
	v_mfma_f32_16x16x32_bf16 v[78:81], v[164:167], v[224:227], v[78:81]
	s_waitcnt lgkmcnt(1)
	v_mfma_f32_16x16x32_bf16 v[82:85], v[168:171], v[224:227], v[82:85]
	s_waitcnt lgkmcnt(0)
	v_mfma_f32_16x16x32_bf16 v[86:89], v[122:125], v[224:227], v[86:89]
	v_mfma_f32_16x16x32_bf16 v[90:93], v[160:163], v[228:231], v[90:93]
	v_mfma_f32_16x16x32_bf16 v[94:97], v[164:167], v[228:231], v[94:97]
	v_mfma_f32_16x16x32_bf16 v[98:101], v[168:171], v[228:231], v[98:101]
	v_mfma_f32_16x16x32_bf16 v[102:105], v[122:125], v[228:231], v[102:105]
	v_mfma_f32_16x16x32_bf16 v[106:109], v[160:163], v[232:235], v[106:109]
	v_mfma_f32_16x16x32_bf16 v[110:113], v[164:167], v[232:235], v[110:113]
	v_mfma_f32_16x16x32_bf16 v[114:117], v[168:171], v[232:235], v[114:117]
	v_mfma_f32_16x16x32_bf16 v[118:121], v[122:125], v[232:235], v[118:121]
	v_mfma_f32_16x16x32_bf16 v[208:211], v[160:163], v[236:239], v[208:211]
	v_mfma_f32_16x16x32_bf16 v[212:215], v[164:167], v[236:239], v[212:215]
	v_mfma_f32_16x16x32_bf16 v[216:219], v[168:171], v[236:239], v[216:219]
	v_mfma_f32_16x16x32_bf16 v[220:223], v[122:125], v[236:239], v[220:223]
	s_barrier
	s_branch .Linp_post
